# LayerNorm row reductions: 6-hop ds_bpermute chains replaced by DPP row sums + v_readlane, on top of attention loop changes
# baseline (speedup 1.0000x reference)
.LBB0_208:
	v_mov_b32_e32 v84, v60
	v_mov_b32_e32 v85, v56
	v_mov_b32_e32 v86, v61
	v_mov_b32_e32 v87, v57
	v_pk_add_f32 v[84:85], v[84:85], v[86:87]
	v_mov_b32_e32 v86, v62
	v_mov_b32_e32 v87, v58
	v_mov_b32_e32 v88, v63
	v_mov_b32_e32 v89, v59
	v_pk_add_f32 v[86:87], v[86:87], v[88:89]
	v_mov_b32_e32 v88, v52
	v_pk_add_f32 v[84:85], v[84:85], v[86:87]
	v_mov_b32_e32 v86, v53
	v_mov_b32_e32 v87, v54
	v_mov_b32_e32 v89, v55
	v_pk_add_f32 v[86:87], v[86:87], v[88:89]
	v_add_f32_e32 v84, 0, v84
	v_pk_add_f32 v[86:87], v[86:87], v[86:87] op_sel:[0,1] op_sel_hi:[1,0]
	v_add_f32_e32 v84, v84, v85
	v_add_f32_e32 v88, v48, v49
	v_add_f32_e32 v90, v50, v51
	v_mov_b32_e32 v85, v44
	v_mov_b32_e32 v87, v45
	v_mov_b32_e32 v89, v46
	v_mov_b32_e32 v91, v47
	v_pk_add_f32 v[84:85], v[84:85], v[86:87]
	v_pk_add_f32 v[86:87], v[88:89], v[90:91]
	v_mov_b32_e32 v88, v40
	v_pk_add_f32 v[84:85], v[84:85], v[86:87]
	v_mov_b32_e32 v86, v41
	v_mov_b32_e32 v87, v42
	v_mov_b32_e32 v89, v43
	v_pk_add_f32 v[86:87], v[86:87], v[88:89]
	v_pk_add_f32 v[84:85], v[84:85], v[84:85] op_sel:[0,1] op_sel_hi:[1,0]
	v_pk_add_f32 v[86:87], v[86:87], v[86:87] op_sel:[0,1] op_sel_hi:[1,0]
	v_add_f32_e32 v88, v36, v37
	v_add_f32_e32 v90, v38, v39
	v_mov_b32_e32 v85, v32
	v_mov_b32_e32 v87, v33
	v_mov_b32_e32 v89, v34
	v_mov_b32_e32 v91, v35
	v_pk_add_f32 v[84:85], v[84:85], v[86:87]
	v_pk_add_f32 v[86:87], v[88:89], v[90:91]
	s_nop 0
	v_pk_add_f32 v[84:85], v[84:85], v[86:87]
	s_nop 0
	v_add_f32_e32 v84, v84, v85
	s_waitcnt lgkmcnt(0)
	s_nop 1
	v_add_f32_dpp v84, v84, v84 quad_perm:[1,0,3,2] row_mask:0xf bank_mask:0xf
	s_nop 1
	v_add_f32_dpp v84, v84, v84 quad_perm:[2,3,0,1] row_mask:0xf bank_mask:0xf
	s_nop 1
	v_add_f32_dpp v84, v84, v84 row_half_mirror row_mask:0xf bank_mask:0xf
	s_nop 1
	v_add_f32_dpp v84, v84, v84 row_ror:8 row_mask:0xf bank_mask:0xf
	s_nop 0
	v_readlane_b32 s100, v84, 0
	v_readlane_b32 s101, v84, 16
	s_nop 0
	v_mov_b32_e32 v85, s100
	v_add_f32_e32 v85, s101, v85
	v_readlane_b32 s100, v84, 32
	v_readlane_b32 s101, v84, 48
	s_nop 0
	v_add_f32_e32 v85, s100, v85
	v_add_f32_e32 v90, s101, v85
	v_fmamk_f32 v61, v90, 0xba000000, v61
	v_fmamk_f32 v57, v90, 0xba000000, v57
	v_fmamk_f32 v63, v90, 0xba000000, v63
	v_fmac_f32_e32 v60, 0xba000000, v90
	v_fmamk_f32 v93, v90, 0xba000000, v59
	v_fmac_f32_e32 v56, 0xba000000, v90
	v_mov_b32_e32 v84, v61
	v_mov_b32_e32 v85, v57
	v_fmamk_f32 v62, v90, 0xba000000, v62
	v_fmamk_f32 v92, v90, 0xba000000, v58
	v_mov_b32_e32 v58, v60
	v_mov_b32_e32 v59, v56
	v_pk_mul_f32 v[84:85], v[84:85], v[84:85]
	v_mov_b32_e32 v86, v63
	v_mov_b32_e32 v87, v93
	v_pk_fma_f32 v[58:59], v[58:59], v[58:59], v[84:85]
	v_mov_b32_e32 v84, v62
	v_mov_b32_e32 v85, v92
	v_pk_mul_f32 v[86:87], v[86:87], v[86:87]
	v_fmamk_f32 v95, v90, 0xba000000, v53
	v_pk_fma_f32 v[84:85], v[84:85], v[84:85], v[86:87]
	v_fmamk_f32 v94, v90, 0xba000000, v52
	v_fmamk_f32 v55, v90, 0xba000000, v55
	v_fmac_f32_e32 v54, 0xba000000, v90
	v_pk_add_f32 v[58:59], v[58:59], v[84:85]
	v_pk_mul_f32 v[52:53], v[54:55], v[54:55]
	v_pk_mul_f32 v[84:85], v[94:95], v[94:95]
	v_fmac_f32_e32 v50, 0xba000000, v90
	v_pk_mov_b32 v[86:87], v[84:85], v[52:53] op_sel:[1,0]
	v_mov_b32_e32 v85, v53
	v_pk_add_f32 v[52:53], v[86:87], v[84:85]
	v_fmamk_f32 v51, v90, 0xba000000, v51
	v_pk_add_f32 v[84:85], v[52:53], v[52:53] op_sel_hi:[0,1]
	v_fmamk_f32 v52, v90, 0xba000000, v48
	v_fmamk_f32 v53, v90, 0xba000000, v49
	v_mul_f32_e32 v48, v52, v52
	v_pk_fma_f32 v[86:87], v[52:53], v[52:53], v[48:49] op_sel_hi:[1,1,0]
	v_mul_f32_e32 v48, v50, v50
	v_pk_add_f32 v[58:59], v[58:59], v[58:59] op_sel_hi:[0,1]
	v_pk_fma_f32 v[88:89], v[50:51], v[50:51], v[48:49] op_sel_hi:[1,1,0]
	v_fmamk_f32 v49, v90, 0xba000000, v47
	v_fmamk_f32 v48, v90, 0xba000000, v46
	v_fmamk_f32 v45, v90, 0xba000000, v45
	v_fmac_f32_e32 v44, 0xba000000, v90
	v_mul_f32_e32 v86, v44, v44
	v_mul_f32_e32 v88, v45, v45
	v_mul_f32_e32 v84, v48, v48
	v_mul_f32_e32 v58, v49, v49
	v_pk_add_f32 v[46:47], v[86:87], v[88:89]
	v_pk_add_f32 v[58:59], v[84:85], v[58:59]
	v_fmamk_f32 v41, v90, 0xba000000, v41
	v_pk_add_f32 v[46:47], v[46:47], v[58:59]
	v_fmamk_f32 v40, v90, 0xba000000, v40
	v_fmamk_f32 v43, v90, 0xba000000, v43
	v_fmac_f32_e32 v42, 0xba000000, v90
	v_pk_add_f32 v[46:47], v[46:47], v[46:47] op_sel_hi:[0,1]
	v_pk_mul_f32 v[58:59], v[42:43], v[42:43]
	v_pk_mul_f32 v[84:85], v[40:41], v[40:41]
	v_fmamk_f32 v36, v90, 0xba000000, v36
	v_pk_mov_b32 v[86:87], v[84:85], v[58:59] op_sel:[1,0]
	v_mov_b32_e32 v85, v59
	v_fmamk_f32 v37, v90, 0xba000000, v37
	v_fmac_f32_e32 v38, 0xba000000, v90
	v_mul_f32_e32 v46, v36, v36
	v_pk_add_f32 v[58:59], v[86:87], v[84:85]
	v_fmamk_f32 v39, v90, 0xba000000, v39
	v_pk_fma_f32 v[84:85], v[36:37], v[36:37], v[46:47] op_sel_hi:[1,1,0]
	v_mul_f32_e32 v46, v38, v38
	v_pk_add_f32 v[58:59], v[58:59], v[58:59] op_sel_hi:[0,1]
	v_pk_fma_f32 v[86:87], v[38:39], v[38:39], v[46:47] op_sel_hi:[1,1,0]
	v_fmamk_f32 v35, v90, 0xba000000, v35
	v_fmamk_f32 v34, v90, 0xba000000, v34
	v_fmamk_f32 v33, v90, 0xba000000, v33
	v_fmac_f32_e32 v32, 0xba000000, v90
	v_mul_f32_e32 v84, v32, v32
	v_mul_f32_e32 v86, v33, v33
	v_mul_f32_e32 v58, v34, v34
	v_mul_f32_e32 v46, v35, v35
	v_pk_add_f32 v[84:85], v[84:85], v[86:87]
	v_pk_add_f32 v[46:47], v[58:59], v[46:47]
	s_nop 0
	v_pk_add_f32 v[46:47], v[84:85], v[46:47]
	s_nop 0
	v_add_f32_e32 v46, v46, v47
	s_waitcnt lgkmcnt(0)
	s_nop 1
	v_add_f32_dpp v46, v46, v46 quad_perm:[1,0,3,2] row_mask:0xf bank_mask:0xf
	s_nop 1
	v_add_f32_dpp v46, v46, v46 quad_perm:[2,3,0,1] row_mask:0xf bank_mask:0xf
	s_nop 1
	v_add_f32_dpp v46, v46, v46 row_half_mirror row_mask:0xf bank_mask:0xf
	s_nop 1
	v_add_f32_dpp v46, v46, v46 row_ror:8 row_mask:0xf bank_mask:0xf
	s_nop 0
	v_readlane_b32 s100, v46, 0
	v_readlane_b32 s101, v46, 16
	s_nop 0
	v_mov_b32_e32 v47, s100
	v_add_f32_e32 v47, s101, v47
	v_readlane_b32 s100, v46, 32
	v_readlane_b32 s101, v46, 48
	s_nop 0
	v_add_f32_e32 v47, s100, v47
	v_add_f32_e32 v46, s101, v47
	v_fmamk_f32 v46, v46, 0x3a000000, v82
	v_mul_f32_e32 v47, 0x4f800000, v46
	v_cmp_gt_f32_e32 vcc, s3, v46
	s_nop 1
	v_cndmask_b32_e32 v46, v46, v47, vcc
	v_sqrt_f32_e32 v47, v46
	s_nop 0
	v_add_u32_e32 v58, -1, v47
	v_fma_f32 v59, -v58, v47, v46
	v_cmp_ge_f32_e64 s[4:5], 0, v59
	v_add_u32_e32 v59, 1, v47
	s_nop 0
	v_cndmask_b32_e64 v58, v47, v58, s[4:5]
	v_fma_f32 v47, -v59, v47, v46
	v_cmp_lt_f32_e64 s[4:5], 0, v47
	s_nop 1
	v_cndmask_b32_e64 v47, v58, v59, s[4:5]
	v_mul_f32_e32 v58, 0x37800000, v47
	v_cndmask_b32_e32 v47, v47, v58, vcc
	v_cmp_class_f32_e32 vcc, v46, v83
	s_nop 1
	v_cndmask_b32_e32 v46, v47, v46, vcc
	v_div_scale_f32 v47, s[4:5], v46, v46, 1.0
	v_rcp_f32_e32 v58, v47
	s_min_i32 s4, s20, 0x4000
	s_and_b32 s4, s4, 0x3ffff000
	v_fma_f32 v59, -v47, v58, 1.0
	v_fmac_f32_e32 v58, v59, v58
	v_div_scale_f32 v59, vcc, 1.0, v46, 1.0
	v_mul_f32_e32 v84, v59, v58
	v_fma_f32 v85, -v47, v84, v59
	v_fmac_f32_e32 v84, v85, v58
	v_fma_f32 v47, -v47, v84, v59
	v_div_fmas_f32 v47, v47, v58, v84
	v_div_fixup_f32 v46, v47, v46, 1.0
	v_lshl_add_u32 v47, s4, 2, v77
	ds_read_b128 v[84:87], v47 offset:8192
	ds_read_b128 v[88:91], v47
	v_pk_mul_f32 v[96:97], v[60:61], v[46:47] op_sel_hi:[1,0]
	ds_read_b128 v[58:61], v47 offset:9216
	v_pk_mul_f32 v[62:63], v[62:63], v[46:47] op_sel_hi:[1,0]
	s_waitcnt lgkmcnt(2)
	v_pk_add_f32 v[100:101], v[84:85], 1.0 op_sel_hi:[1,0]
	v_pk_add_f32 v[98:99], v[86:87], 1.0 op_sel_hi:[1,0]
	ds_read_b128 v[84:87], v47 offset:1024
	s_waitcnt lgkmcnt(2)
	v_pk_fma_f32 v[88:89], v[100:101], v[96:97], v[88:89]
	v_pk_fma_f32 v[62:63], v[98:99], v[62:63], v[90:91]
	v_bfe_u32 v90, v88, 16, 1
	v_add3_u32 v88, v88, v90, s28
	v_bfe_u32 v90, v89, 16, 1
	v_lshrrev_b32_e32 v88, 16, v88
	v_add3_u32 v89, v89, v90, s28
	v_and_or_b32 v88, v89, s29, v88
	v_bfe_u32 v89, v62, 16, 1
	v_pk_mul_f32 v[56:57], v[56:57], v[46:47] op_sel_hi:[1,0]
	s_waitcnt lgkmcnt(1)
	v_pk_add_f32 v[58:59], v[58:59], 1.0 op_sel_hi:[1,0]
	v_add3_u32 v62, v62, v89, s28
	v_bfe_u32 v89, v63, 16, 1
	s_waitcnt lgkmcnt(0)
	v_pk_fma_f32 v[56:57], v[58:59], v[56:57], v[84:85]
	v_lshrrev_b32_e32 v62, 16, v62
	v_add3_u32 v63, v63, v89, s28
	v_bfe_u32 v58, v56, 16, 1
	v_and_or_b32 v89, v63, s29, v62
	v_pk_mul_f32 v[62:63], v[92:93], v[46:47] op_sel_hi:[1,0]
	v_pk_add_f32 v[60:61], v[60:61], 1.0 op_sel_hi:[1,0]
	v_add3_u32 v56, v56, v58, s28
	v_bfe_u32 v58, v57, 16, 1
	v_pk_fma_f32 v[60:61], v[60:61], v[62:63], v[86:87]
	v_lshrrev_b32_e32 v56, 16, v56
	v_add3_u32 v57, v57, v58, s28
	v_and_or_b32 v56, v57, s29, v56
	v_bfe_u32 v57, v60, 16, 1
	v_add3_u32 v57, v60, v57, s28
	v_bfe_u32 v58, v61, 16, 1
	v_lshrrev_b32_e32 v57, 16, v57
	v_add3_u32 v58, v61, v58, s28
	v_and_or_b32 v57, v58, s29, v57
	global_store_dwordx2 v[70:71], v[88:89], off
	global_store_dwordx2 v[70:71], v[56:57], off offset:512
	ds_read_b128 v[56:59], v47 offset:10240
	ds_read_b128 v[60:63], v47 offset:2048
	v_pk_mul_f32 v[88:89], v[94:95], v[46:47] op_sel_hi:[1,0]
	v_pk_mul_f32 v[90:91], v[54:55], v[46:47] op_sel_hi:[1,0]
	ds_read_b128 v[84:87], v47 offset:11264
	s_waitcnt lgkmcnt(2)
	v_pk_add_f32 v[92:93], v[56:57], 1.0 op_sel_hi:[1,0]
	v_pk_add_f32 v[58:59], v[58:59], 1.0 op_sel_hi:[1,0]
	s_waitcnt lgkmcnt(1)
	v_pk_fma_f32 v[60:61], v[92:93], v[88:89], v[60:61]
	v_pk_fma_f32 v[58:59], v[58:59], v[90:91], v[62:63]
	v_bfe_u32 v62, v60, 16, 1
	v_add3_u32 v60, v60, v62, s28
	v_bfe_u32 v62, v61, 16, 1
	v_lshrrev_b32_e32 v60, 16, v60
	v_add3_u32 v61, v61, v62, s28
	ds_read_b128 v[54:57], v47 offset:3072
	v_and_or_b32 v60, v61, s29, v60
	v_bfe_u32 v61, v58, 16, 1
	v_add3_u32 v58, v58, v61, s28
	v_bfe_u32 v61, v59, 16, 1
	v_lshrrev_b32_e32 v58, 16, v58
	v_add3_u32 v59, v59, v61, s28
	v_and_or_b32 v61, v59, s29, v58
	global_store_dwordx2 v[70:71], v[60:61], off offset:1024
	v_pk_mul_f32 v[52:53], v[52:53], v[46:47] op_sel_hi:[1,0]
	s_waitcnt lgkmcnt(1)
	v_pk_add_f32 v[60:61], v[84:85], 1.0 op_sel_hi:[1,0]
	v_pk_mul_f32 v[50:51], v[50:51], v[46:47] op_sel_hi:[1,0]
	s_waitcnt lgkmcnt(0)
	v_pk_fma_f32 v[52:53], v[60:61], v[52:53], v[54:55]
	v_pk_add_f32 v[58:59], v[86:87], 1.0 op_sel_hi:[1,0]
	v_bfe_u32 v54, v52, 16, 1
	v_add3_u32 v52, v52, v54, s28
	v_bfe_u32 v54, v53, 16, 1
	v_pk_fma_f32 v[50:51], v[58:59], v[50:51], v[56:57]
	v_lshrrev_b32_e32 v52, 16, v52
	v_add3_u32 v53, v53, v54, s28
	v_and_or_b32 v52, v53, s29, v52
	v_bfe_u32 v53, v50, 16, 1
	v_add3_u32 v50, v50, v53, s28
	v_bfe_u32 v53, v51, 16, 1
	v_lshrrev_b32_e32 v50, 16, v50
	v_add3_u32 v51, v51, v53, s28
	v_and_or_b32 v53, v51, s29, v50
	global_store_dwordx2 v[70:71], v[52:53], off offset:1536
	ds_read_b128 v[50:53], v47 offset:12288
	ds_read_b128 v[54:57], v47 offset:4096
	v_pk_mul_f32 v[44:45], v[44:45], v[46:47] op_sel_hi:[1,0]
	v_pk_mul_f32 v[62:63], v[48:49], v[46:47] op_sel_hi:[1,0]
	ds_read_b128 v[58:61], v47 offset:13312
	s_waitcnt lgkmcnt(2)
	v_pk_add_f32 v[84:85], v[50:51], 1.0 op_sel_hi:[1,0]
	v_pk_add_f32 v[52:53], v[52:53], 1.0 op_sel_hi:[1,0]
	s_waitcnt lgkmcnt(1)
	v_pk_fma_f32 v[44:45], v[84:85], v[44:45], v[54:55]
	ds_read_b128 v[48:51], v47 offset:5120
	v_bfe_u32 v54, v44, 16, 1
	v_add3_u32 v44, v44, v54, s28
	v_bfe_u32 v54, v45, 16, 1
	v_pk_fma_f32 v[52:53], v[52:53], v[62:63], v[56:57]
	v_lshrrev_b32_e32 v44, 16, v44
	v_add3_u32 v45, v45, v54, s28
	v_and_or_b32 v44, v45, s29, v44
	v_bfe_u32 v45, v52, 16, 1
	v_add3_u32 v45, v52, v45, s28
	v_bfe_u32 v52, v53, 16, 1
	v_lshrrev_b32_e32 v45, 16, v45
	v_add3_u32 v52, v53, v52, s28
	v_and_or_b32 v45, v52, s29, v45
	v_pk_mul_f32 v[40:41], v[40:41], v[46:47] op_sel_hi:[1,0]
	s_waitcnt lgkmcnt(1)
	v_pk_add_f32 v[52:53], v[58:59], 1.0 op_sel_hi:[1,0]
	global_store_dwordx2 v[70:71], v[44:45], off offset:2048
	v_pk_mul_f32 v[42:43], v[42:43], v[46:47] op_sel_hi:[1,0]
	v_pk_add_f32 v[44:45], v[60:61], 1.0 op_sel_hi:[1,0]
	s_waitcnt lgkmcnt(0)
	v_pk_fma_f32 v[40:41], v[52:53], v[40:41], v[48:49]
	v_pk_fma_f32 v[42:43], v[44:45], v[42:43], v[50:51]
	v_bfe_u32 v44, v40, 16, 1
	v_add3_u32 v40, v40, v44, s28
	v_bfe_u32 v44, v41, 16, 1
	v_lshrrev_b32_e32 v40, 16, v40
	v_add3_u32 v41, v41, v44, s28
	v_and_or_b32 v40, v41, s29, v40
	v_bfe_u32 v41, v42, 16, 1
	v_add3_u32 v41, v42, v41, s28
	v_bfe_u32 v42, v43, 16, 1
	v_lshrrev_b32_e32 v41, 16, v41
	v_add3_u32 v42, v43, v42, s28
	v_and_or_b32 v41, v42, s29, v41
	global_store_dwordx2 v[70:71], v[40:41], off offset:2560
	ds_read_b128 v[40:43], v47 offset:14336
	ds_read_b128 v[48:51], v47 offset:6144
	v_pk_mul_f32 v[44:45], v[36:37], v[46:47] op_sel_hi:[1,0]
	v_pk_mul_f32 v[52:53], v[38:39], v[46:47] op_sel_hi:[1,0]
	ds_read_b128 v[36:39], v47 offset:15360
	s_waitcnt lgkmcnt(2)
	v_pk_add_f32 v[56:57], v[40:41], 1.0 op_sel_hi:[1,0]
	v_pk_add_f32 v[54:55], v[42:43], 1.0 op_sel_hi:[1,0]
	s_waitcnt lgkmcnt(1)
	v_pk_fma_f32 v[44:45], v[56:57], v[44:45], v[48:49]
	ds_read_b128 v[40:43], v47 offset:7168
	v_bfe_u32 v47, v44, 16, 1
	v_pk_fma_f32 v[50:51], v[54:55], v[52:53], v[50:51]
	v_add3_u32 v44, v44, v47, s28
	v_bfe_u32 v47, v45, 16, 1
	v_add3_u32 v45, v45, v47, s28
	v_bfe_u32 v47, v51, 16, 1
	v_add3_u32 v47, v51, v47, s28
	v_pk_mul_f32 v[32:33], v[32:33], v[46:47] op_sel_hi:[1,0]
	s_waitcnt lgkmcnt(1)
	v_pk_add_f32 v[36:37], v[36:37], 1.0 op_sel_hi:[1,0]
	v_pk_mul_f32 v[34:35], v[34:35], v[46:47] op_sel_hi:[1,0]
	s_waitcnt lgkmcnt(0)
	v_pk_fma_f32 v[32:33], v[36:37], v[32:33], v[40:41]
	v_pk_add_f32 v[38:39], v[38:39], 1.0 op_sel_hi:[1,0]
	v_bfe_u32 v36, v32, 16, 1
	v_add3_u32 v32, v32, v36, s28
	v_bfe_u32 v36, v33, 16, 1
	v_lshrrev_b32_e32 v44, 16, v44
	v_pk_fma_f32 v[34:35], v[38:39], v[34:35], v[42:43]
	v_lshrrev_b32_e32 v32, 16, v32
	v_add3_u32 v33, v33, v36, s28
	v_and_or_b32 v44, v45, s29, v44
	v_bfe_u32 v45, v50, 16, 1
	v_and_or_b32 v32, v33, s29, v32
	v_bfe_u32 v33, v34, 16, 1
	v_add3_u32 v45, v50, v45, s28
	v_add3_u32 v33, v34, v33, s28
	v_bfe_u32 v34, v35, 16, 1
	v_lshrrev_b32_e32 v45, 16, v45
	v_lshrrev_b32_e32 v33, 16, v33
	v_add3_u32 v34, v35, v34, s28
	v_and_or_b32 v45, v47, s29, v45
	v_and_or_b32 v33, v34, s29, v33
	s_andn2_b64 vcc, exec, s[24:25]
	global_store_dwordx2 v[70:71], v[44:45], off offset:3072
	global_store_dwordx2 v[70:71], v[32:33], off offset:3584
	s_cbranch_vccnz .LBB0_197
	v_mov_b32_e32 v32, v4
	v_mov_b32_e32 v33, v0
	v_mov_b32_e32 v34, v5
	v_mov_b32_e32 v35, v1
	v_pk_add_f32 v[32:33], v[32:33], v[34:35]
	v_mov_b32_e32 v34, v6
	v_mov_b32_e32 v35, v2
	v_mov_b32_e32 v36, v7
	v_mov_b32_e32 v37, v3
	v_pk_add_f32 v[34:35], v[34:35], v[36:37]
	v_mov_b32_e32 v36, v8
	v_pk_add_f32 v[32:33], v[32:33], v[34:35]
	v_mov_b32_e32 v34, v9
	v_mov_b32_e32 v35, v10
	v_mov_b32_e32 v37, v11
	v_pk_add_f32 v[34:35], v[34:35], v[36:37]
	v_add_f32_e32 v33, 0, v33
	v_pk_add_f32 v[34:35], v[34:35], v[34:35] op_sel_hi:[0,1]
	v_add_f32_e32 v33, v32, v33
	v_add_f32_e32 v37, v12, v13
	v_add_f32_e32 v39, v14, v15
	v_mov_b32_e32 v36, v16
	v_mov_b32_e32 v38, v17
	v_mov_b32_e32 v34, v18
	v_mov_b32_e32 v32, v19
	v_pk_add_f32 v[36:37], v[36:37], v[38:39]
	v_pk_add_f32 v[32:33], v[34:35], v[32:33]
	v_mov_b32_e32 v34, v21
	v_pk_add_f32 v[32:33], v[36:37], v[32:33]
	v_mov_b32_e32 v35, v22
	v_mov_b32_e32 v36, v20
	v_mov_b32_e32 v37, v23
	v_pk_add_f32 v[34:35], v[34:35], v[36:37]
	v_pk_add_f32 v[32:33], v[32:33], v[32:33] op_sel_hi:[0,1]
	v_pk_add_f32 v[34:35], v[34:35], v[34:35] op_sel_hi:[0,1]
	v_add_f32_e32 v37, v24, v25
	v_add_f32_e32 v39, v26, v27
	v_mov_b32_e32 v36, v28
	v_mov_b32_e32 v38, v29
	v_mov_b32_e32 v34, v30
	v_mov_b32_e32 v32, v31
	v_pk_add_f32 v[36:37], v[36:37], v[38:39]
	v_pk_add_f32 v[32:33], v[34:35], v[32:33]
	s_ashr_i32 s23, s22, 31
	v_pk_add_f32 v[32:33], v[36:37], v[32:33]
	s_nop 0
	v_add_f32_e32 v32, v32, v33
	s_waitcnt lgkmcnt(0)
	s_nop 1
	v_add_f32_dpp v32, v32, v32 quad_perm:[1,0,3,2] row_mask:0xf bank_mask:0xf
	s_nop 1
	v_add_f32_dpp v32, v32, v32 quad_perm:[2,3,0,1] row_mask:0xf bank_mask:0xf
	s_nop 1
	v_add_f32_dpp v32, v32, v32 row_half_mirror row_mask:0xf bank_mask:0xf
	s_nop 1
	v_add_f32_dpp v32, v32, v32 row_ror:8 row_mask:0xf bank_mask:0xf
	s_nop 0
	v_readlane_b32 s100, v32, 0
	v_readlane_b32 s101, v32, 16
	s_nop 0
	v_mov_b32_e32 v33, s100
	v_add_f32_e32 v33, s101, v33
	v_readlane_b32 s100, v32, 32
	v_readlane_b32 s101, v32, 48
	s_nop 0
	v_add_f32_e32 v33, s100, v33
	v_add_f32_e32 v60, s101, v33
	v_fmamk_f32 v85, v60, 0xba000000, v1
	v_fmamk_f32 v95, v60, 0xba000000, v5
	v_fmamk_f32 v63, v60, 0xba000000, v3
	v_fmamk_f32 v84, v60, 0xba000000, v0
	v_fmamk_f32 v93, v60, 0xba000000, v7
	v_fmamk_f32 v94, v60, 0xba000000, v4
	v_mov_b32_e32 v34, v85
	v_mov_b32_e32 v35, v95
	v_fmamk_f32 v62, v60, 0xba000000, v2
	v_fmamk_f32 v92, v60, 0xba000000, v6
	v_mov_b32_e32 v32, v84
	v_mov_b32_e32 v33, v94
	v_pk_mul_f32 v[34:35], v[34:35], v[34:35]
	v_mov_b32_e32 v36, v63
	v_mov_b32_e32 v37, v93
	v_pk_fma_f32 v[32:33], v[32:33], v[32:33], v[34:35]
	v_mov_b32_e32 v34, v62
	v_mov_b32_e32 v35, v92
	v_pk_mul_f32 v[36:37], v[36:37], v[36:37]
	v_fmamk_f32 v97, v60, 0xba000000, v9
	v_pk_fma_f32 v[34:35], v[34:35], v[34:35], v[36:37]
	v_fmamk_f32 v96, v60, 0xba000000, v8
	v_pk_add_f32 v[32:33], v[32:33], v[34:35]
	v_fmamk_f32 v99, v60, 0xba000000, v11
	v_fmamk_f32 v98, v60, 0xba000000, v10
	v_pk_add_f32 v[32:33], v[32:33], v[32:33] op_sel_hi:[0,1]
	v_pk_mul_f32 v[34:35], v[98:99], v[98:99]
	v_pk_mul_f32 v[36:37], v[96:97], v[96:97]
	v_fmamk_f32 v50, v60, 0xba000000, v12
	v_pk_mov_b32 v[38:39], v[36:37], v[34:35] op_sel:[1,0]
	v_mov_b32_e32 v37, v35
	v_fmamk_f32 v51, v60, 0xba000000, v13
	v_fmamk_f32 v52, v60, 0xba000000, v14
	v_mul_f32_e32 v32, v50, v50
	v_pk_add_f32 v[34:35], v[38:39], v[36:37]
	v_fmamk_f32 v53, v60, 0xba000000, v15
	v_pk_fma_f32 v[36:37], v[50:51], v[50:51], v[32:33] op_sel_hi:[1,1,0]
	v_mul_f32_e32 v32, v52, v52
	v_pk_add_f32 v[34:35], v[34:35], v[34:35] op_sel_hi:[0,1]
	v_pk_fma_f32 v[38:39], v[52:53], v[52:53], v[32:33] op_sel_hi:[1,1,0]
	v_fmamk_f32 v47, v60, 0xba000000, v19
	v_fmamk_f32 v46, v60, 0xba000000, v18
	v_fmamk_f32 v49, v60, 0xba000000, v17
	v_fmamk_f32 v48, v60, 0xba000000, v16
	v_mul_f32_e32 v36, v48, v48
	v_mul_f32_e32 v38, v49, v49
	v_mul_f32_e32 v34, v46, v46
	v_mul_f32_e32 v32, v47, v47
	v_pk_add_f32 v[36:37], v[36:37], v[38:39]
	v_pk_add_f32 v[32:33], v[34:35], v[32:33]
	v_fmamk_f32 v41, v60, 0xba000000, v21
	v_pk_add_f32 v[32:33], v[36:37], v[32:33]
	v_fmamk_f32 v40, v60, 0xba000000, v20
	v_fmamk_f32 v43, v60, 0xba000000, v23
	v_fmamk_f32 v42, v60, 0xba000000, v22
	v_pk_add_f32 v[44:45], v[32:33], v[32:33] op_sel_hi:[0,1]
	v_pk_mul_f32 v[32:33], v[42:43], v[42:43]
	v_pk_mul_f32 v[34:35], v[40:41], v[40:41]
	v_fmamk_f32 v38, v60, 0xba000000, v26
	v_pk_mov_b32 v[36:37], v[34:35], v[32:33] op_sel:[1,0]
	v_mov_b32_e32 v35, v33
	v_pk_add_f32 v[32:33], v[36:37], v[34:35]
	v_fmamk_f32 v36, v60, 0xba000000, v24
	v_pk_add_f32 v[54:55], v[32:33], v[32:33] op_sel_hi:[0,1]
	v_fmamk_f32 v37, v60, 0xba000000, v25
	v_mul_f32_e32 v32, v36, v36
	v_fmamk_f32 v39, v60, 0xba000000, v27
	v_pk_fma_f32 v[56:57], v[36:37], v[36:37], v[32:33] op_sel_hi:[1,1,0]
	v_mul_f32_e32 v32, v38, v38
	v_pk_fma_f32 v[58:59], v[38:39], v[38:39], v[32:33] op_sel_hi:[1,1,0]
	v_fmamk_f32 v33, v60, 0xba000000, v31
	v_fmamk_f32 v32, v60, 0xba000000, v30
	v_fmamk_f32 v35, v60, 0xba000000, v29
	v_fmamk_f32 v34, v60, 0xba000000, v28
	v_mul_f32_e32 v56, v34, v34
	v_mul_f32_e32 v58, v35, v35
	v_mul_f32_e32 v54, v32, v32
	v_mul_f32_e32 v44, v33, v33
	v_pk_add_f32 v[56:57], v[56:57], v[58:59]
	v_pk_add_f32 v[44:45], v[54:55], v[44:45]
	s_nop 0
	v_pk_add_f32 v[44:45], v[56:57], v[44:45]
	s_nop 0
	v_add_f32_e32 v44, v44, v45
	s_waitcnt lgkmcnt(0)
	s_nop 1
	v_add_f32_dpp v44, v44, v44 quad_perm:[1,0,3,2] row_mask:0xf bank_mask:0xf
	s_nop 1
	v_add_f32_dpp v44, v44, v44 quad_perm:[2,3,0,1] row_mask:0xf bank_mask:0xf
	s_nop 1
	v_add_f32_dpp v44, v44, v44 row_half_mirror row_mask:0xf bank_mask:0xf
	s_nop 1
	v_add_f32_dpp v44, v44, v44 row_ror:8 row_mask:0xf bank_mask:0xf
	s_nop 0
	v_readlane_b32 s100, v44, 0
	v_readlane_b32 s101, v44, 16
	s_nop 0
	v_mov_b32_e32 v45, s100
	v_add_f32_e32 v45, s101, v45
	v_readlane_b32 s100, v44, 32
	v_readlane_b32 s101, v44, 48
	s_nop 0
	v_add_f32_e32 v45, s100, v45
	v_add_f32_e32 v44, s101, v45
	v_fmamk_f32 v44, v44, 0x3a000000, v82
	v_mul_f32_e32 v45, 0x4f800000, v44
	v_cmp_gt_f32_e32 vcc, s3, v44
	s_nop 1
	v_cndmask_b32_e32 v44, v44, v45, vcc
	v_sqrt_f32_e32 v45, v44
	s_nop 0
	v_add_u32_e32 v54, -1, v45
	v_fma_f32 v55, -v54, v45, v44
	v_cmp_ge_f32_e64 s[4:5], 0, v55
	v_add_u32_e32 v55, 1, v45
	s_nop 0
	v_cndmask_b32_e64 v54, v45, v54, s[4:5]
	v_fma_f32 v45, -v55, v45, v44
	v_cmp_lt_f32_e64 s[4:5], 0, v45
	s_nop 1
	v_cndmask_b32_e64 v45, v54, v55, s[4:5]
	v_mul_f32_e32 v54, 0x37800000, v45
	v_cndmask_b32_e32 v45, v45, v54, vcc
	v_cmp_class_f32_e32 vcc, v44, v83
	s_nop 1
	v_cndmask_b32_e32 v44, v45, v44, vcc
	v_div_scale_f32 v45, s[4:5], v44, v44, 1.0
	v_rcp_f32_e32 v54, v45
	s_min_i32 s4, s22, 0x4000
	s_and_b32 s8, s4, 0x3ffff000
	s_lshl_b64 s[4:5], s[22:23], 12
	v_fma_f32 v55, -v45, v54, 1.0
	v_fmac_f32_e32 v54, v55, v54
	v_div_scale_f32 v55, vcc, 1.0, v44, 1.0
	v_mul_f32_e32 v56, v55, v54
	v_fma_f32 v57, -v45, v56, v55
	v_fmac_f32_e32 v56, v57, v54
	v_fma_f32 v45, -v45, v56, v55
	v_div_fmas_f32 v45, v45, v54, v56
	v_div_fixup_f32 v44, v45, v44, 1.0
	v_lshl_add_u32 v45, s8, 2, v77
	ds_read_b128 v[54:57], v45 offset:8192
	ds_read_b128 v[58:61], v45
	v_pk_mul_f32 v[100:101], v[84:85], v[44:45] op_sel_hi:[1,0]
	v_pk_mul_f32 v[62:63], v[62:63], v[44:45] op_sel_hi:[1,0]
	ds_read_b128 v[84:87], v45 offset:9216
	ds_read_b128 v[88:91], v45 offset:1024
	s_waitcnt lgkmcnt(3)
	v_pk_add_f32 v[54:55], v[54:55], 1.0 op_sel_hi:[1,0]
	v_pk_add_f32 v[56:57], v[56:57], 1.0 op_sel_hi:[1,0]
	s_waitcnt lgkmcnt(2)
	v_pk_fma_f32 v[54:55], v[54:55], v[100:101], v[58:59]
	v_pk_fma_f32 v[56:57], v[56:57], v[62:63], v[60:61]
	v_bfe_u32 v58, v54, 16, 1
	v_add3_u32 v54, v54, v58, s28
	v_bfe_u32 v58, v55, 16, 1
	v_lshrrev_b32_e32 v54, 16, v54
	v_add3_u32 v55, v55, v58, s28
	v_and_or_b32 v58, v55, s29, v54
	v_bfe_u32 v54, v56, 16, 1
	v_add3_u32 v54, v56, v54, s28
	v_bfe_u32 v55, v57, 16, 1
	v_lshrrev_b32_e32 v54, 16, v54
	v_add3_u32 v55, v57, v55, s28
	v_and_or_b32 v59, v55, s29, v54
	v_lshl_add_u64 v[54:55], v[68:69], 0, s[4:5]
	v_pk_mul_f32 v[56:57], v[94:95], v[44:45] op_sel_hi:[1,0]
	s_waitcnt lgkmcnt(1)
	v_pk_add_f32 v[62:63], v[84:85], 1.0 op_sel_hi:[1,0]
	global_store_dwordx2 v[54:55], v[58:59], off
	v_pk_mul_f32 v[58:59], v[92:93], v[44:45] op_sel_hi:[1,0]
	v_pk_add_f32 v[60:61], v[86:87], 1.0 op_sel_hi:[1,0]
	s_waitcnt lgkmcnt(0)
	v_pk_fma_f32 v[56:57], v[62:63], v[56:57], v[88:89]
	v_pk_fma_f32 v[58:59], v[60:61], v[58:59], v[90:91]
	v_bfe_u32 v60, v56, 16, 1
	v_add3_u32 v56, v56, v60, s28
	v_bfe_u32 v60, v57, 16, 1
	v_lshrrev_b32_e32 v56, 16, v56
	v_add3_u32 v57, v57, v60, s28
	v_and_or_b32 v56, v57, s29, v56
	v_bfe_u32 v57, v58, 16, 1
	v_add3_u32 v57, v58, v57, s28
	v_bfe_u32 v58, v59, 16, 1
	v_lshrrev_b32_e32 v57, 16, v57
	v_add3_u32 v58, v59, v58, s28
	v_and_or_b32 v57, v58, s29, v57
	global_store_dwordx2 v[54:55], v[56:57], off offset:512
	ds_read_b128 v[56:59], v45 offset:10240
	ds_read_b128 v[60:63], v45 offset:2048
	v_pk_mul_f32 v[88:89], v[96:97], v[44:45] op_sel_hi:[1,0]
	v_pk_mul_f32 v[90:91], v[98:99], v[44:45] op_sel_hi:[1,0]
	ds_read_b128 v[84:87], v45 offset:11264
	s_waitcnt lgkmcnt(2)
	v_pk_add_f32 v[94:95], v[56:57], 1.0 op_sel_hi:[1,0]
	v_pk_add_f32 v[92:93], v[58:59], 1.0 op_sel_hi:[1,0]
	s_waitcnt lgkmcnt(1)
	v_pk_fma_f32 v[60:61], v[94:95], v[88:89], v[60:61]
	ds_read_b128 v[56:59], v45 offset:3072
	v_bfe_u32 v88, v60, 16, 1
	v_add3_u32 v60, v60, v88, s28
	v_bfe_u32 v88, v61, 16, 1
	v_pk_fma_f32 v[62:63], v[92:93], v[90:91], v[62:63]
	v_lshrrev_b32_e32 v60, 16, v60
	v_add3_u32 v61, v61, v88, s28
	v_and_or_b32 v60, v61, s29, v60
	v_bfe_u32 v61, v62, 16, 1
	v_add3_u32 v61, v62, v61, s28
	v_bfe_u32 v62, v63, 16, 1
	v_lshrrev_b32_e32 v61, 16, v61
	v_add3_u32 v62, v63, v62, s28
	v_and_or_b32 v61, v62, s29, v61
	v_pk_mul_f32 v[50:51], v[50:51], v[44:45] op_sel_hi:[1,0]
	s_waitcnt lgkmcnt(1)
	v_pk_add_f32 v[62:63], v[84:85], 1.0 op_sel_hi:[1,0]
	global_store_dwordx2 v[54:55], v[60:61], off offset:1024
	s_waitcnt lgkmcnt(0)
	v_pk_fma_f32 v[50:51], v[62:63], v[50:51], v[56:57]
	v_pk_mul_f32 v[52:53], v[52:53], v[44:45] op_sel_hi:[1,0]
	v_bfe_u32 v56, v50, 16, 1
	v_pk_add_f32 v[60:61], v[86:87], 1.0 op_sel_hi:[1,0]
	v_add3_u32 v50, v50, v56, s28
	v_bfe_u32 v56, v51, 16, 1
	v_pk_fma_f32 v[52:53], v[60:61], v[52:53], v[58:59]
	v_lshrrev_b32_e32 v50, 16, v50
	v_add3_u32 v51, v51, v56, s28
	v_and_or_b32 v50, v51, s29, v50
	v_bfe_u32 v51, v52, 16, 1
	v_add3_u32 v51, v52, v51, s28
	v_bfe_u32 v52, v53, 16, 1
	v_lshrrev_b32_e32 v51, 16, v51
	v_add3_u32 v52, v53, v52, s28
	v_and_or_b32 v51, v52, s29, v51
	global_store_dwordx2 v[54:55], v[50:51], off offset:1536
	ds_read_b128 v[50:53], v45 offset:12288
	ds_read_b128 v[56:59], v45 offset:4096
	v_pk_mul_f32 v[60:61], v[48:49], v[44:45] op_sel_hi:[1,0]
	v_pk_mul_f32 v[62:63], v[46:47], v[44:45] op_sel_hi:[1,0]
	ds_read_b128 v[46:49], v45 offset:13312
	s_waitcnt lgkmcnt(2)
	v_pk_add_f32 v[84:85], v[52:53], 1.0 op_sel_hi:[1,0]
	v_pk_add_f32 v[86:87], v[50:51], 1.0 op_sel_hi:[1,0]
	ds_read_b128 v[50:53], v45 offset:5120
	v_pk_mul_f32 v[40:41], v[40:41], v[44:45] op_sel_hi:[1,0]
	s_waitcnt lgkmcnt(1)
	v_pk_add_f32 v[46:47], v[46:47], 1.0 op_sel_hi:[1,0]
	v_pk_fma_f32 v[56:57], v[86:87], v[60:61], v[56:57]
	v_pk_mul_f32 v[42:43], v[42:43], v[44:45] op_sel_hi:[1,0]
	s_waitcnt lgkmcnt(0)
	v_pk_fma_f32 v[40:41], v[46:47], v[40:41], v[50:51]
	v_bfe_u32 v60, v56, 16, 1
	v_bfe_u32 v46, v40, 16, 1
	v_add3_u32 v56, v56, v60, s28
	v_bfe_u32 v60, v57, 16, 1
	v_pk_add_f32 v[48:49], v[48:49], 1.0 op_sel_hi:[1,0]
	v_add3_u32 v40, v40, v46, s28
	v_bfe_u32 v46, v41, 16, 1
	v_pk_fma_f32 v[58:59], v[84:85], v[62:63], v[58:59]
	v_lshrrev_b32_e32 v56, 16, v56
	v_add3_u32 v57, v57, v60, s28
	v_pk_fma_f32 v[42:43], v[48:49], v[42:43], v[52:53]
	v_lshrrev_b32_e32 v40, 16, v40
	v_add3_u32 v41, v41, v46, s28
	v_and_or_b32 v56, v57, s29, v56
	v_bfe_u32 v57, v58, 16, 1
	v_and_or_b32 v40, v41, s29, v40
	v_bfe_u32 v41, v42, 16, 1
	v_add3_u32 v57, v58, v57, s28
	v_bfe_u32 v58, v59, 16, 1
	v_add3_u32 v41, v42, v41, s28
	v_bfe_u32 v42, v43, 16, 1
	v_lshrrev_b32_e32 v57, 16, v57
	v_add3_u32 v58, v59, v58, s28
	v_lshrrev_b32_e32 v41, 16, v41
	v_add3_u32 v42, v43, v42, s28
	v_and_or_b32 v57, v58, s29, v57
	v_and_or_b32 v41, v42, s29, v41
	global_store_dwordx2 v[54:55], v[56:57], off offset:2048
	global_store_dwordx2 v[54:55], v[40:41], off offset:2560
	ds_read_b128 v[40:43], v45 offset:14336
	ds_read_b128 v[46:49], v45 offset:6144
	v_pk_mul_f32 v[50:51], v[36:37], v[44:45] op_sel_hi:[1,0]
	v_pk_mul_f32 v[52:53], v[38:39], v[44:45] op_sel_hi:[1,0]
	ds_read_b128 v[36:39], v45 offset:15360
	s_waitcnt lgkmcnt(2)
	v_pk_add_f32 v[58:59], v[40:41], 1.0 op_sel_hi:[1,0]
	v_pk_add_f32 v[56:57], v[42:43], 1.0 op_sel_hi:[1,0]
	s_waitcnt lgkmcnt(1)
	v_pk_fma_f32 v[46:47], v[58:59], v[50:51], v[46:47]
	ds_read_b128 v[40:43], v45 offset:7168
	v_bfe_u32 v45, v46, 16, 1
	v_add3_u32 v45, v46, v45, s28
	v_bfe_u32 v46, v47, 16, 1
	v_pk_fma_f32 v[48:49], v[56:57], v[52:53], v[48:49]
	v_lshrrev_b32_e32 v45, 16, v45
	v_add3_u32 v46, v47, v46, s28
	v_and_or_b32 v46, v46, s29, v45
	v_bfe_u32 v45, v48, 16, 1
	v_add3_u32 v45, v48, v45, s28
	v_lshrrev_b32_e32 v45, 16, v45
	v_pk_mul_f32 v[34:35], v[34:35], v[44:45] op_sel_hi:[1,0]
	s_waitcnt lgkmcnt(1)
	v_pk_add_f32 v[36:37], v[36:37], 1.0 op_sel_hi:[1,0]
	v_pk_mul_f32 v[32:33], v[32:33], v[44:45] op_sel_hi:[1,0]
	s_waitcnt lgkmcnt(0)
	v_pk_fma_f32 v[34:35], v[36:37], v[34:35], v[40:41]
	v_pk_add_f32 v[38:39], v[38:39], 1.0 op_sel_hi:[1,0]
	v_bfe_u32 v36, v34, 16, 1
	v_add3_u32 v34, v34, v36, s28
	v_bfe_u32 v36, v35, 16, 1
	v_pk_fma_f32 v[32:33], v[38:39], v[32:33], v[42:43]
	v_lshrrev_b32_e32 v34, 16, v34
	v_add3_u32 v35, v35, v36, s28
	v_and_or_b32 v34, v35, s29, v34
	v_bfe_u32 v35, v32, 16, 1
	v_bfe_u32 v47, v49, 16, 1
	v_add3_u32 v32, v32, v35, s28
	v_bfe_u32 v35, v33, 16, 1
	v_add3_u32 v47, v49, v47, s28
	v_lshrrev_b32_e32 v32, 16, v32
	v_add3_u32 v33, v33, v35, s28
	v_and_or_b32 v47, v47, s29, v45
	v_and_or_b32 v35, v33, s29, v32
	global_store_dwordx2 v[54:55], v[46:47], off offset:3072
	global_store_dwordx2 v[54:55], v[34:35], off offset:3584
	s_branch .LBB0_197

.LBB0_921:
	s_waitcnt vmcnt(15)
	v_cvt_f32_f16_sdwa v181, v166 dst_sel:DWORD dst_unused:UNUSED_PAD src0_sel:WORD_1
	v_cvt_f32_f16_e32 v180, v166
	s_waitcnt vmcnt(14)
	v_lshlrev_b32_e32 v178, 16, v168
	v_and_b32_e32 v179, 0xffff0000, v168
	v_lshlrev_b32_e32 v168, 16, v169
	v_and_b32_e32 v169, 0xffff0000, v169
	v_cvt_f32_f16_sdwa v183, v167 dst_sel:DWORD dst_unused:UNUSED_PAD src0_sel:WORD_1
	v_cvt_f32_f16_e32 v182, v167
	s_waitcnt lgkmcnt(7)
	v_pk_mul_f32 v[166:167], v[124:125], v[178:179]
	v_pk_mul_f32 v[124:125], v[126:127], v[168:169]
	s_waitcnt vmcnt(10)
	v_cvt_f32_f16_sdwa v169, v164 dst_sel:DWORD dst_unused:UNUSED_PAD src0_sel:WORD_1
	v_cvt_f32_f16_e32 v168, v164
	v_pk_fma_f32 v[126:127], v[180:181], s[30:31], v[166:167] op_sel_hi:[1,0,1]
	v_lshlrev_b32_e32 v166, 16, v162
	v_and_b32_e32 v167, 0xffff0000, v162
	v_lshlrev_b32_e32 v162, 16, v163
	v_and_b32_e32 v163, 0xffff0000, v163
	v_cvt_f32_f16_sdwa v179, v165 dst_sel:DWORD dst_unused:UNUSED_PAD src0_sel:WORD_1
	v_cvt_f32_f16_e32 v178, v165
	s_waitcnt lgkmcnt(6)
	v_pk_mul_f32 v[164:165], v[120:121], v[166:167]
	v_pk_mul_f32 v[120:121], v[122:123], v[162:163]
	v_pk_fma_f32 v[122:123], v[168:169], s[30:31], v[164:165] op_sel_hi:[1,0,1]
	s_waitcnt vmcnt(9)
	v_cvt_f32_f16_sdwa v165, v160 dst_sel:DWORD dst_unused:UNUSED_PAD src0_sel:WORD_1
	v_cvt_f32_f16_e32 v164, v160
	v_lshlrev_b32_e32 v162, 16, v158
	v_and_b32_e32 v163, 0xffff0000, v158
	v_lshlrev_b32_e32 v158, 16, v159
	v_and_b32_e32 v159, 0xffff0000, v159
	v_cvt_f32_f16_sdwa v167, v161 dst_sel:DWORD dst_unused:UNUSED_PAD src0_sel:WORD_1
	v_cvt_f32_f16_e32 v166, v161
	s_waitcnt lgkmcnt(5)
	v_pk_mul_f32 v[160:161], v[116:117], v[162:163]
	v_pk_mul_f32 v[116:117], v[118:119], v[158:159]
	v_pk_fma_f32 v[118:119], v[164:165], s[30:31], v[160:161] op_sel_hi:[1,0,1]
	s_waitcnt vmcnt(8)
	v_cvt_f32_f16_sdwa v161, v154 dst_sel:DWORD dst_unused:UNUSED_PAD src0_sel:WORD_1
	v_cvt_f32_f16_e32 v160, v154
	v_lshlrev_b32_e32 v158, 16, v156
	v_and_b32_e32 v159, 0xffff0000, v156
	v_lshlrev_b32_e32 v156, 16, v157
	v_and_b32_e32 v157, 0xffff0000, v157
	v_cvt_f32_f16_sdwa v163, v155 dst_sel:DWORD dst_unused:UNUSED_PAD src0_sel:WORD_1
	v_cvt_f32_f16_e32 v162, v155
	s_waitcnt lgkmcnt(4)
	v_pk_mul_f32 v[154:155], v[112:113], v[158:159]
	v_pk_mul_f32 v[112:113], v[114:115], v[156:157]
	v_pk_fma_f32 v[114:115], v[160:161], s[30:31], v[154:155] op_sel_hi:[1,0,1]
	s_waitcnt vmcnt(6)
	v_lshlrev_b32_e32 v154, 16, v152
	v_and_b32_e32 v155, 0xffff0000, v152
	v_lshlrev_b32_e32 v152, 16, v153
	v_and_b32_e32 v153, 0xffff0000, v153
	s_waitcnt lgkmcnt(3)
	v_pk_mul_f32 v[110:111], v[110:111], v[152:153]
	s_waitcnt vmcnt(2)
	v_cvt_f32_f16_sdwa v153, v148 dst_sel:DWORD dst_unused:UNUSED_PAD src0_sel:WORD_1
	v_cvt_f32_f16_e32 v152, v148
	v_cvt_f32_f16_sdwa v157, v150 dst_sel:DWORD dst_unused:UNUSED_PAD src0_sel:WORD_1
	v_cvt_f32_f16_sdwa v159, v151 dst_sel:DWORD dst_unused:UNUSED_PAD src0_sel:WORD_1
	v_cvt_f32_f16_e32 v158, v151
	v_cvt_f32_f16_e32 v156, v150
	v_lshlrev_b32_e32 v150, 16, v146
	v_and_b32_e32 v151, 0xffff0000, v146
	v_pk_mul_f32 v[108:109], v[108:109], v[154:155]
	v_lshlrev_b32_e32 v146, 16, v147
	v_and_b32_e32 v147, 0xffff0000, v147
	v_cvt_f32_f16_sdwa v155, v149 dst_sel:DWORD dst_unused:UNUSED_PAD src0_sel:WORD_1
	v_cvt_f32_f16_e32 v154, v149
	s_waitcnt lgkmcnt(2)
	v_pk_mul_f32 v[148:149], v[104:105], v[150:151]
	v_pk_mul_f32 v[104:105], v[106:107], v[146:147]
	v_pk_fma_f32 v[106:107], v[152:153], s[30:31], v[148:149] op_sel_hi:[1,0,1]
	s_waitcnt vmcnt(1)
	v_cvt_f32_f16_sdwa v149, v142 dst_sel:DWORD dst_unused:UNUSED_PAD src0_sel:WORD_1
	v_cvt_f32_f16_e32 v148, v142
	v_lshlrev_b32_e32 v146, 16, v140
	v_and_b32_e32 v147, 0xffff0000, v140
	v_lshlrev_b32_e32 v140, 16, v141
	v_and_b32_e32 v141, 0xffff0000, v141
	v_cvt_f32_f16_sdwa v151, v143 dst_sel:DWORD dst_unused:UNUSED_PAD src0_sel:WORD_1
	v_cvt_f32_f16_e32 v150, v143
	s_waitcnt lgkmcnt(1)
	v_pk_mul_f32 v[142:143], v[100:101], v[146:147]
	v_pk_mul_f32 v[100:101], v[102:103], v[140:141]
	v_lshlrev_b32_e32 v140, 16, v138
	v_and_b32_e32 v141, 0xffff0000, v138
	v_lshlrev_b32_e32 v138, 16, v139
	v_and_b32_e32 v139, 0xffff0000, v139
	v_pk_fma_f32 v[124:125], v[182:183], s[30:31], v[124:125] op_sel_hi:[1,0,1]
	v_pk_fma_f32 v[120:121], v[178:179], s[30:31], v[120:121] op_sel_hi:[1,0,1]
	v_pk_fma_f32 v[102:103], v[148:149], s[30:31], v[142:143] op_sel_hi:[1,0,1]
	s_waitcnt vmcnt(0)
	v_cvt_f32_f16_sdwa v143, v136 dst_sel:DWORD dst_unused:UNUSED_PAD src0_sel:WORD_1
	v_cvt_f32_f16_sdwa v147, v137 dst_sel:DWORD dst_unused:UNUSED_PAD src0_sel:WORD_1
	v_cvt_f32_f16_e32 v146, v137
	v_cvt_f32_f16_e32 v142, v136
	s_waitcnt lgkmcnt(0)
	v_pk_mul_f32 v[98:99], v[98:99], v[138:139]
	v_mov_b32_e32 v136, v126
	v_mov_b32_e32 v137, v122
	v_mov_b32_e32 v138, v127
	v_mov_b32_e32 v139, v123
	v_pk_mul_f32 v[96:97], v[96:97], v[140:141]
	v_pk_add_f32 v[136:137], v[136:137], v[138:139]
	v_mov_b32_e32 v138, v124
	v_mov_b32_e32 v139, v120
	v_mov_b32_e32 v140, v125
	v_mov_b32_e32 v141, v121
	v_pk_fma_f32 v[116:117], v[166:167], s[30:31], v[116:117] op_sel_hi:[1,0,1]
	v_pk_add_f32 v[138:139], v[138:139], v[140:141]
	v_mov_b32_e32 v140, v118
	v_pk_add_f32 v[136:137], v[136:137], v[138:139]
	v_pk_mov_b32 v[138:139], v[118:119], v[116:117] op_sel:[1,0]
	v_mov_b32_e32 v141, v117
	v_pk_add_f32 v[138:139], v[138:139], v[140:141]
	v_pk_fma_f32 v[112:113], v[162:163], s[30:31], v[112:113] op_sel_hi:[1,0,1]
	v_pk_fma_f32 v[110:111], v[158:159], s[30:31], v[110:111] op_sel_hi:[1,0,1]
	v_pk_fma_f32 v[108:109], v[156:157], s[30:31], v[108:109] op_sel_hi:[1,0,1]
	v_add_f32_e32 v136, 0, v136
	v_pk_add_f32 v[138:139], v[138:139], v[138:139] op_sel:[0,1] op_sel_hi:[1,0]
	v_pk_fma_f32 v[96:97], v[142:143], s[30:31], v[96:97] op_sel_hi:[1,0,1]
	v_add_f32_e32 v136, v136, v137
	v_add_f32_e32 v140, v114, v115
	v_add_f32_e32 v142, v112, v113
	v_mov_b32_e32 v137, v108
	v_mov_b32_e32 v139, v109
	v_mov_b32_e32 v141, v110
	v_mov_b32_e32 v143, v111
	v_pk_fma_f32 v[104:105], v[154:155], s[30:31], v[104:105] op_sel_hi:[1,0,1]
	v_pk_add_f32 v[136:137], v[136:137], v[138:139]
	v_pk_add_f32 v[138:139], v[140:141], v[142:143]
	v_mov_b32_e32 v140, v106
	v_pk_add_f32 v[136:137], v[136:137], v[138:139]
	v_pk_mov_b32 v[138:139], v[106:107], v[104:105] op_sel:[1,0]
	v_mov_b32_e32 v141, v105
	v_pk_add_f32 v[138:139], v[138:139], v[140:141]
	v_pk_fma_f32 v[100:101], v[150:151], s[30:31], v[100:101] op_sel_hi:[1,0,1]
	v_pk_fma_f32 v[98:99], v[146:147], s[30:31], v[98:99] op_sel_hi:[1,0,1]
	v_pk_add_f32 v[136:137], v[136:137], v[136:137] op_sel:[0,1] op_sel_hi:[1,0]
	v_pk_add_f32 v[138:139], v[138:139], v[138:139] op_sel:[0,1] op_sel_hi:[1,0]
	v_add_f32_e32 v140, v102, v103
	v_add_f32_e32 v142, v100, v101
	v_mov_b32_e32 v137, v96
	v_mov_b32_e32 v139, v97
	v_mov_b32_e32 v141, v98
	v_mov_b32_e32 v143, v99
	v_pk_add_f32 v[136:137], v[136:137], v[138:139]
	v_pk_add_f32 v[138:139], v[140:141], v[142:143]
	v_lshl_add_u64 v[164:165], v[134:135], 0, s[24:25]
	v_pk_add_f32 v[136:137], v[136:137], v[138:139]
	v_lshl_add_u64 v[168:169], v[134:135], 0, s[28:29]
	v_add_f32_e32 v136, v136, v137
	s_waitcnt lgkmcnt(0)
	s_nop 1
	v_add_f32_dpp v136, v136, v136 quad_perm:[1,0,3,2] row_mask:0xf bank_mask:0xf
	s_nop 1
	v_add_f32_dpp v136, v136, v136 quad_perm:[2,3,0,1] row_mask:0xf bank_mask:0xf
	s_nop 1
	v_add_f32_dpp v136, v136, v136 row_half_mirror row_mask:0xf bank_mask:0xf
	s_nop 1
	v_add_f32_dpp v136, v136, v136 row_ror:8 row_mask:0xf bank_mask:0xf
	s_nop 0
	v_readlane_b32 s100, v136, 0
	v_readlane_b32 s101, v136, 16
	s_nop 0
	v_mov_b32_e32 v137, s100
	v_add_f32_e32 v137, s101, v137
	v_readlane_b32 s100, v136, 32
	v_readlane_b32 s101, v136, 48
	s_nop 0
	v_add_f32_e32 v137, s100, v137
	v_add_f32_e32 v146, s101, v137
	v_fmamk_f32 v127, v146, 0xba000000, v127
	v_fmamk_f32 v123, v146, 0xba000000, v123
	v_fmamk_f32 v125, v146, 0xba000000, v125
	v_fmac_f32_e32 v126, 0xba000000, v146
	v_fmamk_f32 v121, v146, 0xba000000, v121
	v_fmac_f32_e32 v122, 0xba000000, v146
	v_mov_b32_e32 v138, v127
	v_mov_b32_e32 v139, v123
	v_fmac_f32_e32 v124, 0xba000000, v146
	v_fmac_f32_e32 v120, 0xba000000, v146
	v_mov_b32_e32 v136, v126
	v_mov_b32_e32 v137, v122
	v_pk_mul_f32 v[138:139], v[138:139], v[138:139]
	v_mov_b32_e32 v140, v125
	v_mov_b32_e32 v141, v121
	v_pk_fma_f32 v[136:137], v[136:137], v[136:137], v[138:139]
	v_mov_b32_e32 v138, v124
	v_mov_b32_e32 v139, v120
	v_pk_mul_f32 v[140:141], v[140:141], v[140:141]
	v_fmamk_f32 v119, v146, 0xba000000, v119
	v_pk_fma_f32 v[138:139], v[138:139], v[138:139], v[140:141]
	v_fmac_f32_e32 v118, 0xba000000, v146
	v_pk_add_f32 v[136:137], v[136:137], v[138:139]
	v_fmamk_f32 v117, v146, 0xba000000, v117
	v_fmac_f32_e32 v116, 0xba000000, v146
	v_pk_add_f32 v[136:137], v[136:137], v[136:137] op_sel_hi:[0,1]
	v_pk_mul_f32 v[138:139], v[116:117], v[116:117]
	v_pk_mul_f32 v[140:141], v[118:119], v[118:119]
	v_fmac_f32_e32 v114, 0xba000000, v146
	v_pk_mov_b32 v[142:143], v[140:141], v[138:139] op_sel:[1,0]
	v_mov_b32_e32 v141, v139
	v_fmamk_f32 v115, v146, 0xba000000, v115
	v_fmac_f32_e32 v112, 0xba000000, v146
	v_mul_f32_e32 v136, v114, v114
	v_pk_add_f32 v[138:139], v[142:143], v[140:141]
	v_fmamk_f32 v113, v146, 0xba000000, v113
	v_pk_fma_f32 v[140:141], v[114:115], v[114:115], v[136:137] op_sel_hi:[1,1,0]
	v_mul_f32_e32 v136, v112, v112
	v_pk_add_f32 v[138:139], v[138:139], v[138:139] op_sel_hi:[0,1]
	v_pk_fma_f32 v[142:143], v[112:113], v[112:113], v[136:137] op_sel_hi:[1,1,0]
	v_fmamk_f32 v111, v146, 0xba000000, v111
	v_fmac_f32_e32 v110, 0xba000000, v146
	v_fmamk_f32 v109, v146, 0xba000000, v109
	v_fmac_f32_e32 v108, 0xba000000, v146
	v_mul_f32_e32 v140, v108, v108
	v_mul_f32_e32 v142, v109, v109
	v_mul_f32_e32 v138, v110, v110
	v_mul_f32_e32 v136, v111, v111
	v_pk_add_f32 v[140:141], v[140:141], v[142:143]
	v_pk_add_f32 v[136:137], v[138:139], v[136:137]
	v_fmamk_f32 v107, v146, 0xba000000, v107
	v_pk_add_f32 v[136:137], v[140:141], v[136:137]
	v_fmac_f32_e32 v106, 0xba000000, v146
	v_fmamk_f32 v105, v146, 0xba000000, v105
	v_fmac_f32_e32 v104, 0xba000000, v146
	v_pk_add_f32 v[136:137], v[136:137], v[136:137] op_sel_hi:[0,1]
	v_pk_mul_f32 v[138:139], v[104:105], v[104:105]
	v_pk_mul_f32 v[140:141], v[106:107], v[106:107]
	v_fmac_f32_e32 v102, 0xba000000, v146
	v_pk_mov_b32 v[142:143], v[140:141], v[138:139] op_sel:[1,0]
	v_mov_b32_e32 v141, v139
	v_fmamk_f32 v103, v146, 0xba000000, v103
	v_fmac_f32_e32 v100, 0xba000000, v146
	v_mul_f32_e32 v136, v102, v102
	v_pk_add_f32 v[138:139], v[142:143], v[140:141]
	v_fmamk_f32 v101, v146, 0xba000000, v101
	v_pk_fma_f32 v[140:141], v[102:103], v[102:103], v[136:137] op_sel_hi:[1,1,0]
	v_mul_f32_e32 v136, v100, v100
	v_pk_add_f32 v[138:139], v[138:139], v[138:139] op_sel_hi:[0,1]
	v_pk_fma_f32 v[142:143], v[100:101], v[100:101], v[136:137] op_sel_hi:[1,1,0]
	v_fmamk_f32 v99, v146, 0xba000000, v99
	v_fmac_f32_e32 v98, 0xba000000, v146
	v_fmamk_f32 v97, v146, 0xba000000, v97
	v_fmac_f32_e32 v96, 0xba000000, v146
	v_mul_f32_e32 v140, v96, v96
	v_mul_f32_e32 v142, v97, v97
	v_mul_f32_e32 v138, v98, v98
	v_mul_f32_e32 v136, v99, v99
	v_pk_add_f32 v[140:141], v[140:141], v[142:143]
	v_pk_add_f32 v[136:137], v[138:139], v[136:137]
	s_nop 0
	v_pk_add_f32 v[136:137], v[140:141], v[136:137]
	s_nop 0
	v_add_f32_e32 v136, v136, v137
	s_waitcnt lgkmcnt(0)
	s_nop 1
	v_add_f32_dpp v136, v136, v136 quad_perm:[1,0,3,2] row_mask:0xf bank_mask:0xf
	s_nop 1
	v_add_f32_dpp v136, v136, v136 quad_perm:[2,3,0,1] row_mask:0xf bank_mask:0xf
	s_nop 1
	v_add_f32_dpp v136, v136, v136 row_half_mirror row_mask:0xf bank_mask:0xf
	s_nop 1
	v_add_f32_dpp v136, v136, v136 row_ror:8 row_mask:0xf bank_mask:0xf
	s_nop 0
	v_readlane_b32 s100, v136, 0
	v_readlane_b32 s101, v136, 16
	s_nop 0
	v_mov_b32_e32 v137, s100
	v_add_f32_e32 v137, s101, v137
	v_readlane_b32 s100, v136, 32
	v_readlane_b32 s101, v136, 48
	s_nop 0
	v_add_f32_e32 v137, s100, v137
	v_add_f32_e32 v136, s101, v137
	v_fmamk_f32 v136, v136, 0x3a000000, v229
	v_mul_f32_e32 v137, 0x4f800000, v136
	v_cmp_gt_f32_e32 vcc, s5, v136
	s_nop 1
	v_cndmask_b32_e32 v136, v136, v137, vcc
	v_sqrt_f32_e32 v137, v136
	s_nop 0
	v_add_u32_e32 v138, -1, v137
	v_fma_f32 v139, -v138, v137, v136
	v_cmp_ge_f32_e64 s[6:7], 0, v139
	v_add_u32_e32 v139, 1, v137
	s_nop 0
	v_cndmask_b32_e64 v138, v137, v138, s[6:7]
	v_fma_f32 v137, -v139, v137, v136
	v_cmp_lt_f32_e64 s[6:7], 0, v137
	s_nop 1
	v_cndmask_b32_e64 v137, v138, v139, s[6:7]
	v_mul_f32_e32 v138, 0x37800000, v137
	v_cndmask_b32_e32 v137, v137, v138, vcc
	v_cmp_class_f32_e32 vcc, v136, v230
	s_nop 1
	v_cndmask_b32_e32 v136, v137, v136, vcc
	v_div_scale_f32 v137, s[6:7], v136, v136, 1.0
	v_rcp_f32_e32 v138, v137
	s_nop 0
	v_fma_f32 v139, -v137, v138, 1.0
	v_fmac_f32_e32 v138, v139, v138
	v_div_scale_f32 v139, vcc, 1.0, v136, 1.0
	v_mul_f32_e32 v140, v139, v138
	v_fma_f32 v141, -v137, v140, v139
	v_fmac_f32_e32 v140, v141, v138
	v_fma_f32 v137, -v137, v140, v139
	v_div_fmas_f32 v137, v137, v138, v140
	v_div_fixup_f32 v136, v137, v136, 1.0
	v_pk_mul_f32 v[138:139], v[124:125], v[136:137] op_sel_hi:[1,0]
	v_pk_mul_f32 v[124:125], v[126:127], v[136:137] op_sel_hi:[1,0]
	v_pk_fma_f32 v[126:127], v[2:3], v[138:139], v[10:11]
	v_pk_mul_f32 v[138:139], v[120:121], v[136:137] op_sel_hi:[1,0]
	v_pk_mul_f32 v[120:121], v[122:123], v[136:137] op_sel_hi:[1,0]
	v_pk_fma_f32 v[122:123], v[6:7], v[138:139], v[14:15]
	v_pk_mul_f32 v[138:139], v[116:117], v[136:137] op_sel_hi:[1,0]
	v_pk_mul_f32 v[116:117], v[118:119], v[136:137] op_sel_hi:[1,0]
	v_pk_fma_f32 v[118:119], v[18:19], v[138:139], v[26:27]
	v_pk_mul_f32 v[138:139], v[112:113], v[136:137] op_sel_hi:[1,0]
	v_pk_mul_f32 v[112:113], v[114:115], v[136:137] op_sel_hi:[1,0]
	v_pk_fma_f32 v[114:115], v[22:23], v[138:139], v[30:31]
	v_pk_mul_f32 v[138:139], v[104:105], v[136:137] op_sel_hi:[1,0]
	v_pk_fma_f32 v[124:125], v[0:1], v[124:125], v[8:9]
	v_pk_fma_f32 v[120:121], v[4:5], v[120:121], v[12:13]
	v_pk_mul_f32 v[104:105], v[106:107], v[136:137] op_sel_hi:[1,0]
	v_pk_fma_f32 v[106:107], v[38:39], v[138:139], v[46:47]
	v_pk_mul_f32 v[138:139], v[100:101], v[136:137] op_sel_hi:[1,0]
	v_pk_mul_f32 v[110:111], v[110:111], v[136:137] op_sel_hi:[1,0]
	v_pk_mul_f32 v[108:109], v[108:109], v[136:137] op_sel_hi:[1,0]
	v_pk_mul_f32 v[100:101], v[102:103], v[136:137] op_sel_hi:[1,0]
	v_pk_fma_f32 v[102:103], v[50:51], v[138:139], v[58:59]
	v_pk_mul_f32 v[98:99], v[98:99], v[136:137] op_sel_hi:[1,0]
	v_pk_mul_f32 v[96:97], v[96:97], v[136:137] op_sel_hi:[1,0]
	v_mov_b32_e32 v136, v120
	v_mov_b32_e32 v137, v124
	v_mov_b32_e32 v138, v121
	v_mov_b32_e32 v139, v125
	v_pk_add_f32 v[136:137], v[136:137], v[138:139]
	v_mov_b32_e32 v138, v122
	v_mov_b32_e32 v139, v126
	v_mov_b32_e32 v140, v123
	v_mov_b32_e32 v141, v127
	v_pk_fma_f32 v[116:117], v[16:17], v[116:117], v[24:25]
	v_pk_add_f32 v[138:139], v[138:139], v[140:141]
	v_mov_b32_e32 v140, v116
	v_pk_add_f32 v[136:137], v[136:137], v[138:139]
	v_pk_mov_b32 v[138:139], v[116:117], v[118:119] op_sel:[1,0]
	v_mov_b32_e32 v141, v119
	v_pk_add_f32 v[138:139], v[138:139], v[140:141]
	v_pk_fma_f32 v[112:113], v[20:21], v[112:113], v[28:29]
	v_pk_fma_f32 v[108:109], v[32:33], v[108:109], v[40:41]
	v_pk_fma_f32 v[110:111], v[34:35], v[110:111], v[42:43]
	v_add_f32_e32 v137, 0, v137
	v_pk_add_f32 v[138:139], v[138:139], v[138:139] op_sel_hi:[0,1]
	v_add_f32_e32 v137, v136, v137
	v_add_f32_e32 v141, v112, v113
	v_add_f32_e32 v143, v114, v115
	v_mov_b32_e32 v140, v108
	v_mov_b32_e32 v142, v109
	v_mov_b32_e32 v138, v110
	v_mov_b32_e32 v136, v111
	v_pk_fma_f32 v[104:105], v[36:37], v[104:105], v[44:45]
	v_pk_add_f32 v[140:141], v[140:141], v[142:143]
	v_pk_add_f32 v[136:137], v[138:139], v[136:137]
	v_pk_mov_b32 v[138:139], v[104:105], v[106:107] op_sel:[1,0]
	v_pk_add_f32 v[136:137], v[140:141], v[136:137]
	v_mov_b32_e32 v140, v104
	v_mov_b32_e32 v141, v107
	v_pk_add_f32 v[138:139], v[138:139], v[140:141]
	v_pk_fma_f32 v[100:101], v[48:49], v[100:101], v[56:57]
	v_pk_fma_f32 v[96:97], v[52:53], v[96:97], v[60:61]
	v_pk_fma_f32 v[98:99], v[54:55], v[98:99], v[62:63]
	v_pk_add_f32 v[136:137], v[136:137], v[136:137] op_sel_hi:[0,1]
	v_pk_add_f32 v[138:139], v[138:139], v[138:139] op_sel_hi:[0,1]
	v_add_f32_e32 v141, v100, v101
	v_add_f32_e32 v143, v102, v103
	v_mov_b32_e32 v140, v96
	v_mov_b32_e32 v142, v97
	v_mov_b32_e32 v138, v98
	v_mov_b32_e32 v136, v99
	v_pk_add_f32 v[140:141], v[140:141], v[142:143]
	v_pk_add_f32 v[136:137], v[138:139], v[136:137]
	v_cvt_pk_f16_f32 v138, v120, v121
	v_pk_add_f32 v[136:137], v[140:141], v[136:137]
	v_cvt_pk_f16_f32 v139, v122, v123
	v_add_f32_e32 v136, v136, v137
	s_waitcnt lgkmcnt(0)
	s_nop 1
	v_add_f32_dpp v136, v136, v136 quad_perm:[1,0,3,2] row_mask:0xf bank_mask:0xf
	s_nop 1
	v_add_f32_dpp v136, v136, v136 quad_perm:[2,3,0,1] row_mask:0xf bank_mask:0xf
	s_nop 1
	v_add_f32_dpp v136, v136, v136 row_half_mirror row_mask:0xf bank_mask:0xf
	s_nop 1
	v_add_f32_dpp v136, v136, v136 row_ror:8 row_mask:0xf bank_mask:0xf
	s_nop 0
	v_readlane_b32 s100, v136, 0
	v_readlane_b32 s101, v136, 16
	s_nop 0
	v_mov_b32_e32 v137, s100
	v_add_f32_e32 v137, s101, v137
	v_readlane_b32 s100, v136, 32
	v_readlane_b32 s101, v136, 48
	s_nop 0
	v_add_f32_e32 v137, s100, v137
	v_add_f32_e32 v162, s101, v137
	v_cvt_pk_f16_f32 v142, v112, v113
	v_cvt_pk_f16_f32 v143, v114, v115
	v_cvt_pk_f16_f32 v149, v106, v107
	v_cvt_pk_f16_f32 v148, v104, v105
	v_cvt_pk_f16_f32 v153, v98, v99
	v_cvt_pk_f16_f32 v152, v96, v97
	v_cvt_pk_f16_f32 v136, v124, v125
	v_cvt_pk_f16_f32 v137, v126, v127
	v_cvt_pk_f16_f32 v141, v118, v119
	v_cvt_pk_f16_f32 v140, v116, v117
	v_cvt_pk_f16_f32 v147, v110, v111
	v_cvt_pk_f16_f32 v146, v108, v109
	v_cvt_pk_f16_f32 v150, v100, v101
	v_cvt_pk_f16_f32 v151, v102, v103
	v_fmamk_f32 v125, v162, 0xba000000, v125
	v_fmamk_f32 v121, v162, 0xba000000, v121
	v_fmamk_f32 v127, v162, 0xba000000, v127
	v_fmac_f32_e32 v124, 0xba000000, v162
	v_fmamk_f32 v123, v162, 0xba000000, v123
	v_fmac_f32_e32 v120, 0xba000000, v162
	v_mov_b32_e32 v156, v125
	v_mov_b32_e32 v157, v121
	v_fmac_f32_e32 v126, 0xba000000, v162
	v_fmac_f32_e32 v122, 0xba000000, v162
	v_mov_b32_e32 v154, v124
	v_mov_b32_e32 v155, v120
	v_pk_mul_f32 v[156:157], v[156:157], v[156:157]
	v_mov_b32_e32 v158, v127
	v_mov_b32_e32 v159, v123
	v_pk_fma_f32 v[154:155], v[154:155], v[154:155], v[156:157]
	v_mov_b32_e32 v156, v126
	v_mov_b32_e32 v157, v122
	v_pk_mul_f32 v[158:159], v[158:159], v[158:159]
	v_fmamk_f32 v117, v162, 0xba000000, v117
	v_pk_fma_f32 v[156:157], v[156:157], v[156:157], v[158:159]
	v_fmac_f32_e32 v116, 0xba000000, v162
	v_pk_add_f32 v[154:155], v[154:155], v[156:157]
	v_fmamk_f32 v119, v162, 0xba000000, v119
	v_fmac_f32_e32 v118, 0xba000000, v162
	v_pk_add_f32 v[154:155], v[154:155], v[154:155] op_sel_hi:[0,1]
	v_pk_mul_f32 v[156:157], v[118:119], v[118:119]
	v_pk_mul_f32 v[158:159], v[116:117], v[116:117]
	v_fmac_f32_e32 v112, 0xba000000, v162
	v_pk_mov_b32 v[160:161], v[158:159], v[156:157] op_sel:[1,0]
	v_mov_b32_e32 v159, v157
	v_fmamk_f32 v113, v162, 0xba000000, v113
	v_fmac_f32_e32 v114, 0xba000000, v162
	v_mul_f32_e32 v154, v112, v112
	v_pk_add_f32 v[156:157], v[160:161], v[158:159]
	v_fmamk_f32 v115, v162, 0xba000000, v115
	v_pk_fma_f32 v[158:159], v[112:113], v[112:113], v[154:155] op_sel_hi:[1,1,0]
	v_mul_f32_e32 v154, v114, v114
	v_pk_add_f32 v[156:157], v[156:157], v[156:157] op_sel_hi:[0,1]
	v_pk_fma_f32 v[160:161], v[114:115], v[114:115], v[154:155] op_sel_hi:[1,1,0]
	v_fmamk_f32 v111, v162, 0xba000000, v111
	v_fmac_f32_e32 v110, 0xba000000, v162
	v_fmamk_f32 v109, v162, 0xba000000, v109
	v_fmac_f32_e32 v108, 0xba000000, v162
	v_mul_f32_e32 v158, v108, v108
	v_mul_f32_e32 v160, v109, v109
	v_mul_f32_e32 v156, v110, v110
	v_mul_f32_e32 v154, v111, v111
	v_pk_add_f32 v[158:159], v[158:159], v[160:161]
	v_pk_add_f32 v[154:155], v[156:157], v[154:155]
	v_fmamk_f32 v105, v162, 0xba000000, v105
	v_pk_add_f32 v[154:155], v[158:159], v[154:155]
	v_fmac_f32_e32 v104, 0xba000000, v162
	v_fmamk_f32 v107, v162, 0xba000000, v107
	v_fmac_f32_e32 v106, 0xba000000, v162
	v_pk_add_f32 v[154:155], v[154:155], v[154:155] op_sel_hi:[0,1]
	v_pk_mul_f32 v[156:157], v[106:107], v[106:107]
	v_pk_mul_f32 v[158:159], v[104:105], v[104:105]
	v_fmac_f32_e32 v100, 0xba000000, v162
	v_pk_mov_b32 v[160:161], v[158:159], v[156:157] op_sel:[1,0]
	v_mov_b32_e32 v159, v157
	v_fmamk_f32 v101, v162, 0xba000000, v101
	v_fmac_f32_e32 v102, 0xba000000, v162
	v_mul_f32_e32 v154, v100, v100
	v_pk_add_f32 v[156:157], v[160:161], v[158:159]
	v_fmamk_f32 v103, v162, 0xba000000, v103
	v_pk_fma_f32 v[158:159], v[100:101], v[100:101], v[154:155] op_sel_hi:[1,1,0]
	v_mul_f32_e32 v154, v102, v102
	v_pk_add_f32 v[156:157], v[156:157], v[156:157] op_sel_hi:[0,1]
	v_pk_fma_f32 v[160:161], v[102:103], v[102:103], v[154:155] op_sel_hi:[1,1,0]
	v_fmamk_f32 v99, v162, 0xba000000, v99
	v_fmac_f32_e32 v98, 0xba000000, v162
	v_fmamk_f32 v97, v162, 0xba000000, v97
	v_fmac_f32_e32 v96, 0xba000000, v162
	v_mul_f32_e32 v158, v96, v96
	v_mul_f32_e32 v160, v97, v97
	v_mul_f32_e32 v156, v98, v98
	v_mul_f32_e32 v154, v99, v99
	v_pk_add_f32 v[158:159], v[158:159], v[160:161]
	v_pk_add_f32 v[154:155], v[156:157], v[154:155]
	v_lshl_add_u64 v[156:157], v[134:135], 0, s[10:11]
	v_pk_add_f32 v[154:155], v[158:159], v[154:155]
	v_lshl_add_u64 v[160:161], v[134:135], 0, s[20:21]
	v_add_f32_e32 v154, v154, v155
	ds_bpermute_b32 v155, v170, v154
	v_lshl_add_u64 v[162:163], v[134:135], 0, s[22:23]
	s_waitcnt lgkmcnt(0)
	v_add_f32_e32 v154, v154, v155
	ds_bpermute_b32 v155, v171, v154
	s_waitcnt lgkmcnt(0)
	v_add_f32_e32 v154, v154, v155
	ds_bpermute_b32 v155, v172, v154
	s_waitcnt lgkmcnt(0)
	v_add_f32_e32 v158, v154, v155
	ds_bpermute_b32 v159, v173, v158
	v_lshl_add_u64 v[154:155], v[134:135], 0, s[8:9]
	global_store_dwordx2 v[154:155], v[136:137], off
	global_store_dwordx2 v[156:157], v[138:139], off
	s_waitcnt lgkmcnt(0)
	v_add_f32_e32 v166, v158, v159
	ds_bpermute_b32 v167, v174, v166
	v_lshl_add_u64 v[158:159], v[134:135], 0, s[12:13]
	global_store_dwordx2 v[158:159], v[140:141], off
	global_store_dwordx2 v[160:161], v[142:143], off
	global_store_dwordx2 v[162:163], v[146:147], off
	s_waitcnt lgkmcnt(0)
	v_add_f32_e32 v177, v166, v167
	ds_bpermute_b32 v178, v175, v177
	v_lshl_add_u64 v[166:167], v[134:135], 0, s[26:27]
	global_store_dwordx2 v[164:165], v[148:149], off
	global_store_dwordx2 v[166:167], v[150:151], off
	global_store_dwordx2 v[168:169], v[152:153], off
	s_waitcnt lgkmcnt(0)
	v_add_f32_e32 v136, v177, v178
	v_fmamk_f32 v136, v136, 0x3a000000, v229
	v_mul_f32_e32 v137, 0x4f800000, v136
	v_cmp_gt_f32_e32 vcc, s5, v136
	s_nop 1
	v_cndmask_b32_e32 v136, v136, v137, vcc
	v_sqrt_f32_e32 v137, v136
	s_nop 0
	v_add_u32_e32 v138, -1, v137
	v_fma_f32 v139, -v138, v137, v136
	v_cmp_ge_f32_e64 s[6:7], 0, v139
	v_add_u32_e32 v139, 1, v137
	s_nop 0
	v_cndmask_b32_e64 v138, v137, v138, s[6:7]
	v_fma_f32 v137, -v139, v137, v136
	v_cmp_lt_f32_e64 s[6:7], 0, v137
	s_nop 1
	v_cndmask_b32_e64 v137, v138, v139, s[6:7]
	v_mul_f32_e32 v138, 0x37800000, v137
	v_cndmask_b32_e32 v137, v137, v138, vcc
	v_cmp_class_f32_e32 vcc, v136, v230
	s_nop 1
	v_cndmask_b32_e32 v136, v137, v136, vcc
	v_div_scale_f32 v137, s[6:7], v136, v136, 1.0
	v_rcp_f32_e32 v138, v137
	s_nop 0
	v_fma_f32 v139, -v137, v138, 1.0
	v_fmac_f32_e32 v138, v139, v138
	v_div_scale_f32 v139, vcc, 1.0, v136, 1.0
	v_mul_f32_e32 v140, v139, v138
	v_fma_f32 v141, -v137, v140, v139
	v_fmac_f32_e32 v140, v141, v138
	v_fma_f32 v137, -v137, v140, v139
	v_div_fmas_f32 v137, v137, v138, v140
	ds_read_b128 v[138:141], v144 offset:32768
	ds_read_b128 v[146:149], v144 offset:24576
	v_div_fixup_f32 v136, v137, v136, 1.0
	v_pk_mul_f32 v[142:143], v[124:125], v[136:137] op_sel_hi:[1,0]
	v_pk_mul_f32 v[150:151], v[126:127], v[136:137] op_sel_hi:[1,0]
	s_waitcnt lgkmcnt(1)
	v_pk_add_f32 v[154:155], v[138:139], 1.0 op_sel_hi:[1,0]
	ds_read_b128 v[124:127], v144 offset:33792
	s_waitcnt lgkmcnt(1)
	v_pk_fma_f32 v[142:143], v[154:155], v[142:143], v[146:147]
	v_pk_add_f32 v[152:153], v[140:141], 1.0 op_sel_hi:[1,0]
	v_bfe_u32 v137, v142, 16, 1
	v_add3_u32 v137, v142, v137, s69
	v_bfe_u32 v142, v143, 16, 1
	ds_read_b128 v[138:141], v144 offset:25600
	v_pk_fma_f32 v[148:149], v[152:153], v[150:151], v[148:149]
	v_lshrrev_b32_e32 v137, 16, v137
	v_add3_u32 v142, v143, v142, s69
	v_and_or_b32 v142, v142, s4, v137
	v_bfe_u32 v137, v148, 16, 1
	v_add3_u32 v137, v148, v137, s69
	v_lshrrev_b32_e32 v137, 16, v137
	v_pk_mul_f32 v[120:121], v[120:121], v[136:137] op_sel_hi:[1,0]
	s_waitcnt lgkmcnt(1)
	v_pk_add_f32 v[124:125], v[124:125], 1.0 op_sel_hi:[1,0]
	v_pk_mul_f32 v[122:123], v[122:123], v[136:137] op_sel_hi:[1,0]
	s_waitcnt lgkmcnt(0)
	v_pk_fma_f32 v[120:121], v[124:125], v[120:121], v[138:139]
	v_pk_add_f32 v[126:127], v[126:127], 1.0 op_sel_hi:[1,0]
	v_bfe_u32 v124, v120, 16, 1
	v_add3_u32 v120, v120, v124, s69
	v_bfe_u32 v124, v121, 16, 1
	v_pk_fma_f32 v[122:123], v[126:127], v[122:123], v[140:141]
	v_lshrrev_b32_e32 v120, 16, v120
	v_add3_u32 v121, v121, v124, s69
	v_and_or_b32 v120, v121, s4, v120
	v_bfe_u32 v121, v122, 16, 1
	v_bfe_u32 v143, v149, 16, 1
	v_add3_u32 v121, v122, v121, s69
	v_bfe_u32 v122, v123, 16, 1
	v_add3_u32 v143, v149, v143, s69
	v_lshrrev_b32_e32 v121, 16, v121
	v_add3_u32 v122, v123, v122, s69
	v_and_or_b32 v143, v143, s4, v137
	v_and_or_b32 v121, v122, s4, v121
	global_store_dwordx2 v[134:135], v[142:143], off
	global_store_dwordx2 v[134:135], v[120:121], off offset:512
	ds_read_b128 v[120:123], v144 offset:34816
	ds_read_b128 v[124:127], v144 offset:26624
	v_pk_mul_f32 v[138:139], v[116:117], v[136:137] op_sel_hi:[1,0]
	v_pk_mul_f32 v[140:141], v[118:119], v[136:137] op_sel_hi:[1,0]
	ds_read_b128 v[116:119], v144 offset:35840
	s_waitcnt lgkmcnt(2)
	v_pk_add_f32 v[142:143], v[122:123], 1.0 op_sel_hi:[1,0]
	v_pk_add_f32 v[146:147], v[120:121], 1.0 op_sel_hi:[1,0]
	ds_read_b128 v[120:123], v144 offset:27648
	s_waitcnt lgkmcnt(2)
	v_pk_fma_f32 v[124:125], v[146:147], v[138:139], v[124:125]
	s_waitcnt lgkmcnt(1)
	v_pk_add_f32 v[116:117], v[116:117], 1.0 op_sel_hi:[1,0]
	v_bfe_u32 v137, v124, 16, 1
	v_add3_u32 v124, v124, v137, s69
	v_bfe_u32 v137, v125, 16, 1
	v_pk_mul_f32 v[112:113], v[112:113], v[136:137] op_sel_hi:[1,0]
	v_pk_mul_f32 v[114:115], v[114:115], v[136:137] op_sel_hi:[1,0]
	s_waitcnt lgkmcnt(0)
	v_pk_fma_f32 v[112:113], v[116:117], v[112:113], v[120:121]
	v_pk_add_f32 v[118:119], v[118:119], 1.0 op_sel_hi:[1,0]
	v_bfe_u32 v116, v112, 16, 1
	v_add3_u32 v112, v112, v116, s69
	v_bfe_u32 v116, v113, 16, 1
	v_pk_fma_f32 v[126:127], v[142:143], v[140:141], v[126:127]
	v_lshrrev_b32_e32 v124, 16, v124
	v_add3_u32 v125, v125, v137, s69
	v_pk_fma_f32 v[114:115], v[118:119], v[114:115], v[122:123]
	v_lshrrev_b32_e32 v112, 16, v112
	v_add3_u32 v113, v113, v116, s69
	v_and_or_b32 v124, v125, s4, v124
	v_bfe_u32 v125, v126, 16, 1
	v_and_or_b32 v112, v113, s4, v112
	v_bfe_u32 v113, v114, 16, 1
	v_add3_u32 v125, v126, v125, s69
	v_bfe_u32 v126, v127, 16, 1
	v_add3_u32 v113, v114, v113, s69
	v_bfe_u32 v114, v115, 16, 1
	v_lshrrev_b32_e32 v125, 16, v125
	v_add3_u32 v126, v127, v126, s69
	v_lshrrev_b32_e32 v113, 16, v113
	v_add3_u32 v114, v115, v114, s69
	v_and_or_b32 v125, v126, s4, v125
	v_and_or_b32 v113, v114, s4, v113
	global_store_dwordx2 v[134:135], v[124:125], off offset:1024
	global_store_dwordx2 v[134:135], v[112:113], off offset:1536
	ds_read_b128 v[112:115], v144 offset:36864
	ds_read_b128 v[116:119], v144 offset:28672
	v_pk_mul_f32 v[120:121], v[108:109], v[136:137] op_sel_hi:[1,0]
	v_pk_mul_f32 v[122:123], v[110:111], v[136:137] op_sel_hi:[1,0]
	ds_read_b128 v[108:111], v144 offset:37888
	s_waitcnt lgkmcnt(2)
	v_pk_add_f32 v[124:125], v[114:115], 1.0 op_sel_hi:[1,0]
	v_pk_add_f32 v[126:127], v[112:113], 1.0 op_sel_hi:[1,0]
	ds_read_b128 v[112:115], v144 offset:29696
	v_pk_mul_f32 v[104:105], v[104:105], v[136:137] op_sel_hi:[1,0]
	s_waitcnt lgkmcnt(1)
	v_pk_add_f32 v[108:109], v[108:109], 1.0 op_sel_hi:[1,0]
	v_pk_fma_f32 v[116:117], v[126:127], v[120:121], v[116:117]
	v_pk_mul_f32 v[106:107], v[106:107], v[136:137] op_sel_hi:[1,0]
	s_waitcnt lgkmcnt(0)
	v_pk_fma_f32 v[104:105], v[108:109], v[104:105], v[112:113]
	v_bfe_u32 v120, v116, 16, 1
	v_bfe_u32 v108, v104, 16, 1
	v_add3_u32 v116, v116, v120, s69
	v_bfe_u32 v120, v117, 16, 1
	v_pk_add_f32 v[110:111], v[110:111], 1.0 op_sel_hi:[1,0]
	v_add3_u32 v104, v104, v108, s69
	v_bfe_u32 v108, v105, 16, 1
	v_pk_fma_f32 v[118:119], v[124:125], v[122:123], v[118:119]
	v_lshrrev_b32_e32 v116, 16, v116
	v_add3_u32 v117, v117, v120, s69
	v_pk_fma_f32 v[106:107], v[110:111], v[106:107], v[114:115]
	v_lshrrev_b32_e32 v104, 16, v104
	v_add3_u32 v105, v105, v108, s69
	v_and_or_b32 v116, v117, s4, v116
	v_bfe_u32 v117, v118, 16, 1
	v_and_or_b32 v104, v105, s4, v104
	v_bfe_u32 v105, v106, 16, 1
	v_add3_u32 v117, v118, v117, s69
	v_bfe_u32 v118, v119, 16, 1
	v_add3_u32 v105, v106, v105, s69
	v_bfe_u32 v106, v107, 16, 1
	v_lshrrev_b32_e32 v117, 16, v117
	v_add3_u32 v118, v119, v118, s69
	v_lshrrev_b32_e32 v105, 16, v105
	v_add3_u32 v106, v107, v106, s69
	v_and_or_b32 v117, v118, s4, v117
	v_and_or_b32 v105, v106, s4, v105
	global_store_dwordx2 v[134:135], v[116:117], off offset:2048
	global_store_dwordx2 v[134:135], v[104:105], off offset:2560
	ds_read_b128 v[104:107], v144 offset:38912
	ds_read_b128 v[108:111], v144 offset:30720
	v_pk_mul_f32 v[112:113], v[100:101], v[136:137] op_sel_hi:[1,0]
	v_pk_mul_f32 v[114:115], v[102:103], v[136:137] op_sel_hi:[1,0]
	ds_read_b128 v[100:103], v144 offset:39936
	s_waitcnt lgkmcnt(2)
	v_pk_add_f32 v[116:117], v[106:107], 1.0 op_sel_hi:[1,0]
	v_pk_add_f32 v[118:119], v[104:105], 1.0 op_sel_hi:[1,0]
	ds_read_b128 v[104:107], v144 offset:31744
	v_pk_mul_f32 v[96:97], v[96:97], v[136:137] op_sel_hi:[1,0]
	s_waitcnt lgkmcnt(1)
	v_pk_add_f32 v[100:101], v[100:101], 1.0 op_sel_hi:[1,0]
	v_pk_fma_f32 v[108:109], v[118:119], v[112:113], v[108:109]
	v_pk_mul_f32 v[98:99], v[98:99], v[136:137] op_sel_hi:[1,0]
	s_waitcnt lgkmcnt(0)
	v_pk_fma_f32 v[96:97], v[100:101], v[96:97], v[104:105]
	v_bfe_u32 v112, v108, 16, 1
	v_bfe_u32 v100, v96, 16, 1
	v_add3_u32 v108, v108, v112, s69
	v_bfe_u32 v112, v109, 16, 1
	v_pk_add_f32 v[102:103], v[102:103], 1.0 op_sel_hi:[1,0]
	v_add3_u32 v96, v96, v100, s69
	v_bfe_u32 v100, v97, 16, 1
	v_pk_fma_f32 v[110:111], v[116:117], v[114:115], v[110:111]
	v_lshrrev_b32_e32 v108, 16, v108
	v_add3_u32 v109, v109, v112, s69
	v_pk_fma_f32 v[98:99], v[102:103], v[98:99], v[106:107]
	v_lshrrev_b32_e32 v96, 16, v96
	v_add3_u32 v97, v97, v100, s69
	v_and_or_b32 v108, v109, s4, v108
	v_bfe_u32 v109, v110, 16, 1
	v_and_or_b32 v96, v97, s4, v96
	v_bfe_u32 v97, v98, 16, 1
	v_add3_u32 v109, v110, v109, s69
	v_bfe_u32 v110, v111, 16, 1
	v_add3_u32 v97, v98, v97, s69
	v_bfe_u32 v98, v99, 16, 1
	v_lshrrev_b32_e32 v109, 16, v109
	v_add3_u32 v110, v111, v110, s69
	v_lshrrev_b32_e32 v97, 16, v97
	v_add3_u32 v98, v99, v98, s69
	v_and_or_b32 v109, v110, s4, v109
	v_and_or_b32 v97, v98, s4, v97
	s_andn2_b64 vcc, exec, s[16:17]
	global_store_dwordx2 v[134:135], v[108:109], off offset:3072
	global_store_dwordx2 v[134:135], v[96:97], off offset:3584
	s_cbranch_vccnz .LBB0_918
	v_mov_b32_e32 v96, v68
	v_mov_b32_e32 v97, v64
	v_mov_b32_e32 v98, v69
	v_mov_b32_e32 v99, v65
	v_pk_add_f32 v[96:97], v[96:97], v[98:99]
	v_mov_b32_e32 v98, v70
	v_mov_b32_e32 v99, v66
	v_mov_b32_e32 v100, v71
	v_mov_b32_e32 v101, v67
	v_pk_add_f32 v[98:99], v[98:99], v[100:101]
	v_mov_b32_e32 v100, v72
	v_pk_add_f32 v[96:97], v[96:97], v[98:99]
	v_mov_b32_e32 v98, v73
	v_mov_b32_e32 v99, v74
	v_mov_b32_e32 v101, v75
	v_pk_add_f32 v[98:99], v[98:99], v[100:101]
	v_add_f32_e32 v97, 0, v97
	v_pk_add_f32 v[98:99], v[98:99], v[98:99] op_sel_hi:[0,1]
	v_add_f32_e32 v97, v96, v97
	v_add_f32_e32 v101, v76, v77
	v_add_f32_e32 v103, v78, v79
	v_mov_b32_e32 v100, v80
	v_mov_b32_e32 v102, v81
	v_mov_b32_e32 v98, v82
	v_mov_b32_e32 v96, v83
	v_pk_add_f32 v[100:101], v[100:101], v[102:103]
	v_pk_add_f32 v[96:97], v[98:99], v[96:97]
	v_mov_b32_e32 v98, v85
	v_pk_add_f32 v[96:97], v[100:101], v[96:97]
	v_mov_b32_e32 v99, v86
	v_mov_b32_e32 v100, v84
	v_mov_b32_e32 v101, v87
	v_pk_add_f32 v[98:99], v[98:99], v[100:101]
	v_pk_add_f32 v[96:97], v[96:97], v[96:97] op_sel_hi:[0,1]
	v_pk_add_f32 v[98:99], v[98:99], v[98:99] op_sel_hi:[0,1]
	v_add_f32_e32 v101, v88, v89
	v_add_f32_e32 v103, v90, v91
	v_mov_b32_e32 v100, v92
	v_mov_b32_e32 v102, v93
	v_mov_b32_e32 v98, v94
	v_mov_b32_e32 v96, v95
	v_pk_add_f32 v[100:101], v[100:101], v[102:103]
	v_pk_add_f32 v[96:97], v[98:99], v[96:97]
	s_ashr_i32 s15, s14, 31
	v_pk_add_f32 v[96:97], v[100:101], v[96:97]
	s_lshl_b64 s[16:17], s[14:15], 12
	v_add_f32_e32 v96, v96, v97
	ds_bpermute_b32 v97, v170, v96
	s_lshr_b32 s14, s14, 12
	s_mulk_i32 s14, 0x6000
	s_waitcnt lgkmcnt(0)
	v_add_f32_e32 v96, v96, v97
	ds_bpermute_b32 v97, v171, v96
	s_waitcnt lgkmcnt(0)
	v_add_f32_e32 v96, v96, v97
	ds_bpermute_b32 v97, v172, v96
	s_waitcnt lgkmcnt(0)
	v_add_f32_e32 v96, v96, v97
	ds_bpermute_b32 v97, v173, v96
	s_waitcnt lgkmcnt(0)
	v_add_f32_e32 v96, v96, v97
	ds_bpermute_b32 v97, v174, v96
	s_waitcnt lgkmcnt(0)
	v_add_f32_e32 v96, v96, v97
	ds_bpermute_b32 v97, v175, v96
	s_waitcnt lgkmcnt(0)
	v_add_f32_e32 v104, v96, v97
	v_fmamk_f32 v65, v104, 0xba000000, v65
	v_fmamk_f32 v69, v104, 0xba000000, v69
	v_fmamk_f32 v67, v104, 0xba000000, v67
	v_fmac_f32_e32 v64, 0xba000000, v104
	v_fmamk_f32 v71, v104, 0xba000000, v71
	v_fmac_f32_e32 v68, 0xba000000, v104
	v_mov_b32_e32 v98, v65
	v_mov_b32_e32 v99, v69
	v_fmamk_f32 v66, v104, 0xba000000, v66
	v_fmamk_f32 v70, v104, 0xba000000, v70
	v_mov_b32_e32 v96, v64
	v_mov_b32_e32 v97, v68
	v_pk_mul_f32 v[98:99], v[98:99], v[98:99]
	v_mov_b32_e32 v100, v67
	v_mov_b32_e32 v101, v71
	v_pk_fma_f32 v[96:97], v[96:97], v[96:97], v[98:99]
	v_mov_b32_e32 v98, v66
	v_mov_b32_e32 v99, v70
	v_pk_mul_f32 v[100:101], v[100:101], v[100:101]
	v_fmamk_f32 v73, v104, 0xba000000, v73
	v_pk_fma_f32 v[98:99], v[98:99], v[98:99], v[100:101]
	v_fmamk_f32 v72, v104, 0xba000000, v72
	v_pk_add_f32 v[96:97], v[96:97], v[98:99]
	v_fmamk_f32 v75, v104, 0xba000000, v75
	v_fmac_f32_e32 v74, 0xba000000, v104
	v_pk_add_f32 v[96:97], v[96:97], v[96:97] op_sel_hi:[0,1]
	v_pk_mul_f32 v[98:99], v[74:75], v[74:75]
	v_pk_mul_f32 v[100:101], v[72:73], v[72:73]
	v_fmamk_f32 v76, v104, 0xba000000, v76
	v_pk_mov_b32 v[102:103], v[100:101], v[98:99] op_sel:[1,0]
	v_mov_b32_e32 v101, v99
	v_fmamk_f32 v77, v104, 0xba000000, v77
	v_fmac_f32_e32 v78, 0xba000000, v104
	v_mul_f32_e32 v96, v76, v76
	v_pk_add_f32 v[98:99], v[102:103], v[100:101]
	v_fmamk_f32 v79, v104, 0xba000000, v79
	v_pk_fma_f32 v[100:101], v[76:77], v[76:77], v[96:97] op_sel_hi:[1,1,0]
	v_mul_f32_e32 v96, v78, v78
	v_pk_add_f32 v[98:99], v[98:99], v[98:99] op_sel_hi:[0,1]
	v_pk_fma_f32 v[102:103], v[78:79], v[78:79], v[96:97] op_sel_hi:[1,1,0]
	v_fmamk_f32 v83, v104, 0xba000000, v83
	v_fmamk_f32 v82, v104, 0xba000000, v82
	v_fmamk_f32 v81, v104, 0xba000000, v81
	v_fmac_f32_e32 v80, 0xba000000, v104
	v_mul_f32_e32 v100, v80, v80
	v_mul_f32_e32 v102, v81, v81
	v_mul_f32_e32 v98, v82, v82
	v_mul_f32_e32 v96, v83, v83
	v_pk_add_f32 v[100:101], v[100:101], v[102:103]
	v_pk_add_f32 v[96:97], v[98:99], v[96:97]
	v_fmamk_f32 v85, v104, 0xba000000, v85
	v_pk_add_f32 v[96:97], v[100:101], v[96:97]
	v_fmamk_f32 v84, v104, 0xba000000, v84
	v_fmamk_f32 v87, v104, 0xba000000, v87
	v_fmac_f32_e32 v86, 0xba000000, v104
	v_pk_add_f32 v[96:97], v[96:97], v[96:97] op_sel_hi:[0,1]
	v_pk_mul_f32 v[98:99], v[86:87], v[86:87]
	v_pk_mul_f32 v[100:101], v[84:85], v[84:85]
	v_fmamk_f32 v88, v104, 0xba000000, v88
	v_pk_mov_b32 v[102:103], v[100:101], v[98:99] op_sel:[1,0]
	v_mov_b32_e32 v101, v99
	v_fmamk_f32 v89, v104, 0xba000000, v89
	v_fmac_f32_e32 v90, 0xba000000, v104
	v_mul_f32_e32 v96, v88, v88
	v_pk_add_f32 v[98:99], v[102:103], v[100:101]
	v_fmamk_f32 v91, v104, 0xba000000, v91
	v_pk_fma_f32 v[100:101], v[88:89], v[88:89], v[96:97] op_sel_hi:[1,1,0]
	v_mul_f32_e32 v96, v90, v90
	v_pk_add_f32 v[98:99], v[98:99], v[98:99] op_sel_hi:[0,1]
	v_pk_fma_f32 v[102:103], v[90:91], v[90:91], v[96:97] op_sel_hi:[1,1,0]
	v_fmamk_f32 v95, v104, 0xba000000, v95
	v_fmamk_f32 v94, v104, 0xba000000, v94
	v_fmamk_f32 v93, v104, 0xba000000, v93
	v_fmac_f32_e32 v92, 0xba000000, v104
	v_mul_f32_e32 v100, v92, v92
	v_mul_f32_e32 v102, v93, v93
	v_mul_f32_e32 v98, v94, v94
	v_mul_f32_e32 v96, v95, v95
	v_pk_add_f32 v[100:101], v[100:101], v[102:103]
	v_pk_add_f32 v[96:97], v[98:99], v[96:97]
	s_nop 0
	v_pk_add_f32 v[96:97], v[100:101], v[96:97]
	s_nop 0
	v_add_f32_e32 v96, v96, v97
	s_waitcnt lgkmcnt(0)
	s_nop 1
	v_add_f32_dpp v96, v96, v96 quad_perm:[1,0,3,2] row_mask:0xf bank_mask:0xf
	s_nop 1
	v_add_f32_dpp v96, v96, v96 quad_perm:[2,3,0,1] row_mask:0xf bank_mask:0xf
	s_nop 1
	v_add_f32_dpp v96, v96, v96 row_half_mirror row_mask:0xf bank_mask:0xf
	s_nop 1
	v_add_f32_dpp v96, v96, v96 row_ror:8 row_mask:0xf bank_mask:0xf
	s_nop 0
	v_readlane_b32 s100, v96, 0
	v_readlane_b32 s101, v96, 16
	s_nop 0
	v_mov_b32_e32 v97, s100
	v_add_f32_e32 v97, s101, v97
	v_readlane_b32 s100, v96, 32
	v_readlane_b32 s101, v96, 48
	s_nop 0
	v_add_f32_e32 v97, s100, v97
	v_add_f32_e32 v96, s101, v97
	v_fmamk_f32 v96, v96, 0x3a000000, v229
	v_cmp_gt_f32_e32 vcc, s5, v96
	v_mul_f32_e32 v97, 0x4f800000, v96
	s_nop 0
	v_cndmask_b32_e32 v96, v96, v97, vcc
	v_sqrt_f32_e32 v97, v96
	s_nop 0
	v_add_u32_e32 v98, -1, v97
	v_fma_f32 v99, -v98, v97, v96
	v_cmp_ge_f32_e64 s[6:7], 0, v99
	v_add_u32_e32 v99, 1, v97
	s_nop 0
	v_cndmask_b32_e64 v98, v97, v98, s[6:7]
	v_fma_f32 v97, -v99, v97, v96
	v_cmp_lt_f32_e64 s[6:7], 0, v97
	s_nop 1
	v_cndmask_b32_e64 v97, v98, v99, s[6:7]
	v_mul_f32_e32 v98, 0x37800000, v97
	v_cndmask_b32_e32 v97, v97, v98, vcc
	v_cmp_class_f32_e32 vcc, v96, v230
	s_nop 1
	v_cndmask_b32_e32 v96, v97, v96, vcc
	v_div_scale_f32 v97, s[6:7], v96, v96, 1.0
	v_rcp_f32_e32 v98, v97
	s_nop 0
	v_fma_f32 v99, -v97, v98, 1.0
	v_fmac_f32_e32 v98, v99, v98
	v_div_scale_f32 v99, vcc, 1.0, v96, 1.0
	v_mul_f32_e32 v100, v99, v98
	v_fma_f32 v101, -v97, v100, v99
	v_fmac_f32_e32 v100, v101, v98
	v_fma_f32 v97, -v97, v100, v99
	v_div_fmas_f32 v97, v97, v98, v100
	v_div_fixup_f32 v96, v97, v96, 1.0
	v_pk_mul_f32 v[64:65], v[64:65], v[96:97] op_sel_hi:[1,0]
	v_pk_mul_f32 v[66:67], v[66:67], v[96:97] op_sel_hi:[1,0]
	v_pk_fma_f32 v[64:65], v[0:1], v[64:65], v[8:9]
	v_pk_fma_f32 v[66:67], v[2:3], v[66:67], v[10:11]
	v_pk_mul_f32 v[68:69], v[68:69], v[96:97] op_sel_hi:[1,0]
	v_pk_mul_f32 v[70:71], v[70:71], v[96:97] op_sel_hi:[1,0]
	v_cvt_pk_f16_f32 v99, v66, v67
	v_cvt_pk_f16_f32 v98, v64, v65
	v_lshl_add_u64 v[100:101], v[130:131], 0, s[16:17]
	v_pk_fma_f32 v[70:71], v[6:7], v[70:71], v[14:15]
	v_pk_fma_f32 v[68:69], v[4:5], v[68:69], v[12:13]
	v_pk_mul_f32 v[74:75], v[74:75], v[96:97] op_sel_hi:[1,0]
	v_pk_mul_f32 v[72:73], v[72:73], v[96:97] op_sel_hi:[1,0]
	global_store_dwordx2 v[100:101], v[98:99], off
	v_cvt_pk_f16_f32 v99, v70, v71
	v_cvt_pk_f16_f32 v98, v68, v69
	v_pk_fma_f32 v[72:73], v[16:17], v[72:73], v[24:25]
	v_pk_fma_f32 v[74:75], v[18:19], v[74:75], v[26:27]
	v_pk_mul_f32 v[78:79], v[78:79], v[96:97] op_sel_hi:[1,0]
	v_pk_mul_f32 v[76:77], v[76:77], v[96:97] op_sel_hi:[1,0]
	global_store_dwordx2 v[100:101], v[98:99], off offset:512
	v_cvt_pk_f16_f32 v99, v74, v75
	v_cvt_pk_f16_f32 v98, v72, v73
	v_pk_fma_f32 v[76:77], v[20:21], v[76:77], v[28:29]
	v_pk_fma_f32 v[78:79], v[22:23], v[78:79], v[30:31]
	v_pk_mul_f32 v[80:81], v[80:81], v[96:97] op_sel_hi:[1,0]
	v_pk_mul_f32 v[82:83], v[82:83], v[96:97] op_sel_hi:[1,0]
	global_store_dwordx2 v[100:101], v[98:99], off offset:1024
	v_cvt_pk_f16_f32 v99, v78, v79
	v_cvt_pk_f16_f32 v98, v76, v77
	v_pk_fma_f32 v[82:83], v[34:35], v[82:83], v[42:43]
	v_pk_fma_f32 v[80:81], v[32:33], v[80:81], v[40:41]
	v_pk_mul_f32 v[86:87], v[86:87], v[96:97] op_sel_hi:[1,0]
	v_pk_mul_f32 v[84:85], v[84:85], v[96:97] op_sel_hi:[1,0]
	global_store_dwordx2 v[100:101], v[98:99], off offset:1536
	v_cvt_pk_f16_f32 v99, v82, v83
	v_cvt_pk_f16_f32 v98, v80, v81
	v_pk_fma_f32 v[84:85], v[36:37], v[84:85], v[44:45]
	v_pk_fma_f32 v[86:87], v[38:39], v[86:87], v[46:47]
	v_pk_mul_f32 v[90:91], v[90:91], v[96:97] op_sel_hi:[1,0]
	v_pk_mul_f32 v[88:89], v[88:89], v[96:97] op_sel_hi:[1,0]
	v_pk_mul_f32 v[92:93], v[92:93], v[96:97] op_sel_hi:[1,0]
	v_pk_mul_f32 v[94:95], v[94:95], v[96:97] op_sel_hi:[1,0]
	global_store_dwordx2 v[100:101], v[98:99], off offset:2048
	v_cvt_pk_f16_f32 v99, v86, v87
	v_cvt_pk_f16_f32 v98, v84, v85
	v_pk_fma_f32 v[88:89], v[48:49], v[88:89], v[56:57]
	v_pk_fma_f32 v[90:91], v[50:51], v[90:91], v[58:59]
	v_pk_fma_f32 v[94:95], v[54:55], v[94:95], v[62:63]
	v_pk_fma_f32 v[92:93], v[52:53], v[92:93], v[60:61]
	global_store_dwordx2 v[100:101], v[98:99], off offset:2560
	v_cvt_pk_f16_f32 v99, v90, v91
	v_cvt_pk_f16_f32 v98, v88, v89
	v_cvt_pk_f16_f32 v97, v94, v95
	v_cvt_pk_f16_f32 v96, v92, v93
	global_store_dwordx2 v[100:101], v[98:99], off offset:3072
	global_store_dwordx2 v[100:101], v[96:97], off offset:3584
	v_mov_b32_e32 v96, v68
	v_mov_b32_e32 v97, v64
	v_mov_b32_e32 v98, v69
	v_mov_b32_e32 v99, v65
	v_pk_add_f32 v[96:97], v[96:97], v[98:99]
	v_mov_b32_e32 v98, v70
	v_mov_b32_e32 v99, v66
	v_mov_b32_e32 v100, v71
	v_mov_b32_e32 v101, v67
	v_pk_add_f32 v[98:99], v[98:99], v[100:101]
	v_mov_b32_e32 v100, v72
	v_pk_add_f32 v[96:97], v[96:97], v[98:99]
	v_pk_mov_b32 v[98:99], v[72:73], v[74:75] op_sel:[1,0]
	v_mov_b32_e32 v101, v75
	v_pk_add_f32 v[98:99], v[98:99], v[100:101]
	v_add_f32_e32 v97, 0, v97
	v_pk_add_f32 v[98:99], v[98:99], v[98:99] op_sel_hi:[0,1]
	v_add_f32_e32 v97, v96, v97
	v_add_f32_e32 v101, v76, v77
	v_add_f32_e32 v103, v78, v79
	v_mov_b32_e32 v100, v80
	v_mov_b32_e32 v102, v81
	v_mov_b32_e32 v98, v82
	v_mov_b32_e32 v96, v83
	v_pk_add_f32 v[100:101], v[100:101], v[102:103]
	v_pk_add_f32 v[96:97], v[98:99], v[96:97]
	v_pk_mov_b32 v[98:99], v[84:85], v[86:87] op_sel:[1,0]
	v_pk_add_f32 v[96:97], v[100:101], v[96:97]
	v_mov_b32_e32 v100, v84
	v_mov_b32_e32 v101, v87
	v_pk_add_f32 v[98:99], v[98:99], v[100:101]
	v_pk_add_f32 v[96:97], v[96:97], v[96:97] op_sel_hi:[0,1]
	v_pk_add_f32 v[98:99], v[98:99], v[98:99] op_sel_hi:[0,1]
	v_add_f32_e32 v101, v88, v89
	v_add_f32_e32 v103, v90, v91
	v_mov_b32_e32 v100, v92
	v_mov_b32_e32 v102, v93
	v_mov_b32_e32 v98, v94
	v_mov_b32_e32 v96, v95
	v_pk_add_f32 v[100:101], v[100:101], v[102:103]
	v_pk_add_f32 v[96:97], v[98:99], v[96:97]
	v_mov_b32_e32 v136, v64
	v_pk_add_f32 v[96:97], v[100:101], v[96:97]
	v_mov_b32_e32 v126, v68
	v_add_f32_e32 v96, v96, v97
	s_waitcnt lgkmcnt(0)
	s_nop 1
	v_add_f32_dpp v96, v96, v96 quad_perm:[1,0,3,2] row_mask:0xf bank_mask:0xf
	s_nop 1
	v_add_f32_dpp v96, v96, v96 quad_perm:[2,3,0,1] row_mask:0xf bank_mask:0xf
	s_nop 1
	v_add_f32_dpp v96, v96, v96 row_half_mirror row_mask:0xf bank_mask:0xf
	s_nop 1
	v_add_f32_dpp v96, v96, v96 row_ror:8 row_mask:0xf bank_mask:0xf
	s_nop 0
	v_readlane_b32 s100, v96, 0
	v_readlane_b32 s101, v96, 16
	s_nop 0
	v_mov_b32_e32 v97, s100
	v_add_f32_e32 v97, s101, v97
	v_readlane_b32 s100, v96, 32
	v_readlane_b32 s101, v96, 48
	s_nop 0
	v_add_f32_e32 v97, s100, v97
	v_add_f32_e32 v144, s101, v97
	v_mov_b32_e32 v110, v66
	v_mov_b32_e32 v124, v70
	v_mov_b32_e32 v120, v72
	v_mov_b32_e32 v122, v74
	v_mov_b32_e32 v116, v76
	v_mov_b32_e32 v118, v78
	v_mov_b32_e32 v112, v82
	v_mov_b32_e32 v114, v80
	v_mov_b32_e32 v104, v84
	v_mov_b32_e32 v106, v86
	v_fmamk_f32 v137, v144, 0xba000000, v65
	v_fmamk_f32 v127, v144, 0xba000000, v69
	v_fmamk_f32 v111, v144, 0xba000000, v67
	v_fmac_f32_e32 v136, 0xba000000, v144
	v_fmamk_f32 v125, v144, 0xba000000, v71
	v_fmac_f32_e32 v126, 0xba000000, v144
	v_mov_b32_e32 v98, v137
	v_mov_b32_e32 v99, v127
	v_fmac_f32_e32 v110, 0xba000000, v144
	v_fmac_f32_e32 v124, 0xba000000, v144
	v_mov_b32_e32 v96, v136
	v_mov_b32_e32 v97, v126
	v_pk_mul_f32 v[98:99], v[98:99], v[98:99]
	v_mov_b32_e32 v100, v111
	v_mov_b32_e32 v101, v125
	v_pk_fma_f32 v[96:97], v[96:97], v[96:97], v[98:99]
	v_mov_b32_e32 v98, v110
	v_mov_b32_e32 v99, v124
	v_pk_mul_f32 v[100:101], v[100:101], v[100:101]
	v_fmamk_f32 v121, v144, 0xba000000, v73
	v_pk_fma_f32 v[98:99], v[98:99], v[98:99], v[100:101]
	v_fmac_f32_e32 v120, 0xba000000, v144
	v_pk_add_f32 v[96:97], v[96:97], v[98:99]
	v_fmamk_f32 v123, v144, 0xba000000, v75
	v_fmac_f32_e32 v122, 0xba000000, v144
	v_pk_add_f32 v[96:97], v[96:97], v[96:97] op_sel_hi:[0,1]
	v_pk_mul_f32 v[98:99], v[122:123], v[122:123]
	v_pk_mul_f32 v[100:101], v[120:121], v[120:121]
	v_fmac_f32_e32 v116, 0xba000000, v144
	v_pk_mov_b32 v[102:103], v[100:101], v[98:99] op_sel:[1,0]
	v_mov_b32_e32 v101, v99
	v_fmamk_f32 v117, v144, 0xba000000, v77
	v_fmac_f32_e32 v118, 0xba000000, v144
	v_mul_f32_e32 v96, v116, v116
	v_pk_add_f32 v[98:99], v[102:103], v[100:101]
	v_fmamk_f32 v119, v144, 0xba000000, v79
	v_pk_fma_f32 v[100:101], v[116:117], v[116:117], v[96:97] op_sel_hi:[1,1,0]
	v_mul_f32_e32 v96, v118, v118
	v_pk_add_f32 v[98:99], v[98:99], v[98:99] op_sel_hi:[0,1]
	v_pk_fma_f32 v[102:103], v[118:119], v[118:119], v[96:97] op_sel_hi:[1,1,0]
	v_fmamk_f32 v113, v144, 0xba000000, v83
	v_fmac_f32_e32 v112, 0xba000000, v144
	v_fmamk_f32 v115, v144, 0xba000000, v81
	v_fmac_f32_e32 v114, 0xba000000, v144
	v_mul_f32_e32 v100, v114, v114
	v_mul_f32_e32 v102, v115, v115
	v_mul_f32_e32 v98, v112, v112
	v_mul_f32_e32 v96, v113, v113
	v_pk_add_f32 v[100:101], v[100:101], v[102:103]
	v_pk_add_f32 v[96:97], v[98:99], v[96:97]
	v_fmamk_f32 v105, v144, 0xba000000, v85
	v_pk_add_f32 v[96:97], v[100:101], v[96:97]
	v_fmac_f32_e32 v104, 0xba000000, v144
	v_fmamk_f32 v107, v144, 0xba000000, v87
	v_fmac_f32_e32 v106, 0xba000000, v144
	v_pk_add_f32 v[108:109], v[96:97], v[96:97] op_sel_hi:[0,1]
	v_pk_mul_f32 v[96:97], v[106:107], v[106:107]
	v_pk_mul_f32 v[98:99], v[104:105], v[104:105]
	v_mov_b32_e32 v102, v90
	v_pk_mov_b32 v[100:101], v[98:99], v[96:97] op_sel:[1,0]
	v_mov_b32_e32 v99, v97
	v_pk_add_f32 v[96:97], v[100:101], v[98:99]
	v_mov_b32_e32 v100, v88
	v_fmac_f32_e32 v100, 0xba000000, v144
	v_pk_add_f32 v[138:139], v[96:97], v[96:97] op_sel_hi:[0,1]
	v_fmamk_f32 v101, v144, 0xba000000, v89
	v_fmac_f32_e32 v102, 0xba000000, v144
	v_mul_f32_e32 v96, v100, v100
	v_fmamk_f32 v103, v144, 0xba000000, v91
	v_pk_fma_f32 v[140:141], v[100:101], v[100:101], v[96:97] op_sel_hi:[1,1,0]
	v_mul_f32_e32 v96, v102, v102
	v_pk_fma_f32 v[142:143], v[102:103], v[102:103], v[96:97] op_sel_hi:[1,1,0]
	v_mov_b32_e32 v96, v94
	v_mov_b32_e32 v98, v92
	v_fmamk_f32 v97, v144, 0xba000000, v95
	v_fmac_f32_e32 v96, 0xba000000, v144
	v_fmamk_f32 v99, v144, 0xba000000, v93
	v_fmac_f32_e32 v98, 0xba000000, v144
	v_mul_f32_e32 v140, v98, v98
	v_mul_f32_e32 v142, v99, v99
	v_mul_f32_e32 v138, v96, v96
	v_mul_f32_e32 v108, v97, v97
	v_pk_add_f32 v[140:141], v[140:141], v[142:143]
	v_pk_add_f32 v[108:109], v[138:139], v[108:109]
	s_nop 0
	v_pk_add_f32 v[108:109], v[140:141], v[108:109]
	s_nop 0
	v_add_f32_e32 v108, v108, v109
	s_waitcnt lgkmcnt(0)
	s_nop 1
	v_add_f32_dpp v108, v108, v108 quad_perm:[1,0,3,2] row_mask:0xf bank_mask:0xf
	s_nop 1
	v_add_f32_dpp v108, v108, v108 quad_perm:[2,3,0,1] row_mask:0xf bank_mask:0xf
	s_nop 1
	v_add_f32_dpp v108, v108, v108 row_half_mirror row_mask:0xf bank_mask:0xf
	s_nop 1
	v_add_f32_dpp v108, v108, v108 row_ror:8 row_mask:0xf bank_mask:0xf
	s_nop 0
	v_readlane_b32 s100, v108, 0
	v_readlane_b32 s101, v108, 16
	s_nop 0
	v_mov_b32_e32 v109, s100
	v_add_f32_e32 v109, s101, v109
	v_readlane_b32 s100, v108, 32
	v_readlane_b32 s101, v108, 48
	s_nop 0
	v_add_f32_e32 v109, s100, v109
	v_add_f32_e32 v108, s101, v109
	v_fmamk_f32 v108, v108, 0x3a000000, v229
	v_cmp_gt_f32_e32 vcc, s5, v108
	v_mul_f32_e32 v109, 0x4f800000, v108
	s_nop 0
	v_cndmask_b32_e32 v108, v108, v109, vcc
	v_sqrt_f32_e32 v109, v108
	s_nop 0
	v_add_u32_e32 v138, -1, v109
	v_fma_f32 v139, -v138, v109, v108
	v_cmp_ge_f32_e64 s[6:7], 0, v139
	v_add_u32_e32 v139, 1, v109
	s_nop 0
	v_cndmask_b32_e64 v138, v109, v138, s[6:7]
	v_fma_f32 v109, -v139, v109, v108
	v_cmp_lt_f32_e64 s[6:7], 0, v109
	s_nop 1
	v_cndmask_b32_e64 v109, v138, v139, s[6:7]
	v_mul_f32_e32 v138, 0x37800000, v109
	v_cndmask_b32_e32 v109, v109, v138, vcc
	v_cmp_class_f32_e32 vcc, v108, v230
	s_nop 1
	v_cndmask_b32_e32 v108, v109, v108, vcc
	v_div_scale_f32 v109, s[6:7], v108, v108, 1.0
	v_rcp_f32_e32 v138, v109
	s_nop 0
	v_fma_f32 v139, -v109, v138, 1.0
	v_fmac_f32_e32 v138, v139, v138
	v_div_scale_f32 v139, vcc, 1.0, v108, 1.0
	v_mul_f32_e32 v140, v139, v138
	v_fma_f32 v141, -v109, v140, v139
	v_fmac_f32_e32 v140, v141, v138
	v_fma_f32 v109, -v109, v140, v139
	v_div_fmas_f32 v109, v109, v138, v140
	v_div_fixup_f32 v108, v109, v108, 1.0
	v_add_u32_e32 v109, s14, v176
	ds_read_b128 v[138:141], v109 offset:24576
	ds_read_b128 v[146:149], v109 offset:32768
	v_pk_mul_f32 v[136:137], v[136:137], v[108:109] op_sel_hi:[1,0]
	v_pk_mul_f32 v[110:111], v[110:111], v[108:109] op_sel_hi:[1,0]
	v_pk_mul_f32 v[126:127], v[126:127], v[108:109] op_sel_hi:[1,0]
	v_pk_mul_f32 v[124:125], v[124:125], v[108:109] op_sel_hi:[1,0]
	s_waitcnt lgkmcnt(0)
	v_pk_add_f32 v[146:147], v[146:147], 1.0 op_sel_hi:[1,0]
	v_pk_add_f32 v[142:143], v[148:149], 1.0 op_sel_hi:[1,0]
	v_pk_fma_f32 v[136:137], v[146:147], v[136:137], v[138:139]
	v_pk_fma_f32 v[110:111], v[142:143], v[110:111], v[140:141]
	v_bfe_u32 v138, v136, 16, 1
	v_add3_u32 v136, v136, v138, s69
	v_bfe_u32 v138, v137, 16, 1
	v_lshrrev_b32_e32 v136, 16, v136
	v_add3_u32 v137, v137, v138, s69
	v_and_or_b32 v136, v137, s4, v136
	v_bfe_u32 v137, v110, 16, 1
	v_add3_u32 v110, v110, v137, s69
	v_bfe_u32 v137, v111, 16, 1
	v_lshrrev_b32_e32 v110, 16, v110
	v_add3_u32 v111, v111, v137, s69
	v_and_or_b32 v137, v111, s4, v110
	v_lshl_add_u64 v[110:111], v[132:133], 0, s[16:17]
	global_store_dwordx2 v[110:111], v[136:137], off
	ds_read_b128 v[136:139], v109 offset:25600
	ds_read_b128 v[140:143], v109 offset:33792
	v_pk_mul_f32 v[120:121], v[120:121], v[108:109] op_sel_hi:[1,0]
	v_pk_mul_f32 v[122:123], v[122:123], v[108:109] op_sel_hi:[1,0]
	v_pk_mul_f32 v[116:117], v[116:117], v[108:109] op_sel_hi:[1,0]
	v_pk_mul_f32 v[118:119], v[118:119], v[108:109] op_sel_hi:[1,0]
	s_waitcnt lgkmcnt(0)
	v_pk_add_f32 v[140:141], v[140:141], 1.0 op_sel_hi:[1,0]
	v_pk_add_f32 v[142:143], v[142:143], 1.0 op_sel_hi:[1,0]
	v_pk_fma_f32 v[126:127], v[140:141], v[126:127], v[136:137]
	v_pk_fma_f32 v[124:125], v[142:143], v[124:125], v[138:139]
	v_bfe_u32 v136, v126, 16, 1
	v_add3_u32 v126, v126, v136, s69
	v_bfe_u32 v136, v127, 16, 1
	v_lshrrev_b32_e32 v126, 16, v126
	v_add3_u32 v127, v127, v136, s69
	v_and_or_b32 v126, v127, s4, v126
	v_bfe_u32 v127, v124, 16, 1
	v_add3_u32 v124, v124, v127, s69
	v_bfe_u32 v127, v125, 16, 1
	v_lshrrev_b32_e32 v124, 16, v124
	v_add3_u32 v125, v125, v127, s69
	v_and_or_b32 v127, v125, s4, v124
	global_store_dwordx2 v[110:111], v[126:127], off offset:512
	ds_read_b128 v[124:127], v109 offset:26624
	ds_read_b128 v[136:139], v109 offset:34816
	v_pk_mul_f32 v[114:115], v[114:115], v[108:109] op_sel_hi:[1,0]
	v_pk_mul_f32 v[112:113], v[112:113], v[108:109] op_sel_hi:[1,0]
	v_pk_mul_f32 v[104:105], v[104:105], v[108:109] op_sel_hi:[1,0]
	v_pk_mul_f32 v[106:107], v[106:107], v[108:109] op_sel_hi:[1,0]
	s_waitcnt lgkmcnt(0)
	v_pk_add_f32 v[136:137], v[136:137], 1.0 op_sel_hi:[1,0]
	v_pk_add_f32 v[138:139], v[138:139], 1.0 op_sel_hi:[1,0]
	v_pk_fma_f32 v[120:121], v[136:137], v[120:121], v[124:125]
	v_pk_fma_f32 v[122:123], v[138:139], v[122:123], v[126:127]
	v_bfe_u32 v124, v120, 16, 1
	v_add3_u32 v120, v120, v124, s69
	v_bfe_u32 v124, v121, 16, 1
	v_lshrrev_b32_e32 v120, 16, v120
	v_add3_u32 v121, v121, v124, s69
	v_and_or_b32 v120, v121, s4, v120
	v_bfe_u32 v121, v122, 16, 1
	v_add3_u32 v121, v122, v121, s69
	v_bfe_u32 v122, v123, 16, 1
	v_lshrrev_b32_e32 v121, 16, v121
	v_add3_u32 v122, v123, v122, s69
	v_and_or_b32 v121, v122, s4, v121
	global_store_dwordx2 v[110:111], v[120:121], off offset:1024
	ds_read_b128 v[120:123], v109 offset:27648
	ds_read_b128 v[124:127], v109 offset:35840
	v_pk_mul_f32 v[100:101], v[100:101], v[108:109] op_sel_hi:[1,0]
	v_pk_mul_f32 v[102:103], v[102:103], v[108:109] op_sel_hi:[1,0]
	v_pk_mul_f32 v[98:99], v[98:99], v[108:109] op_sel_hi:[1,0]
	v_pk_mul_f32 v[96:97], v[96:97], v[108:109] op_sel_hi:[1,0]
	s_waitcnt lgkmcnt(0)
	v_pk_add_f32 v[124:125], v[124:125], 1.0 op_sel_hi:[1,0]
	v_pk_add_f32 v[126:127], v[126:127], 1.0 op_sel_hi:[1,0]
	v_pk_fma_f32 v[116:117], v[124:125], v[116:117], v[120:121]
	v_pk_fma_f32 v[118:119], v[126:127], v[118:119], v[122:123]
	v_bfe_u32 v120, v116, 16, 1
	v_add3_u32 v116, v116, v120, s69
	v_bfe_u32 v120, v117, 16, 1
	v_lshrrev_b32_e32 v116, 16, v116
	v_add3_u32 v117, v117, v120, s69
	v_and_or_b32 v116, v117, s4, v116
	v_bfe_u32 v117, v118, 16, 1
	v_add3_u32 v117, v118, v117, s69
	v_bfe_u32 v118, v119, 16, 1
	v_lshrrev_b32_e32 v117, 16, v117
	v_add3_u32 v118, v119, v118, s69
	v_and_or_b32 v117, v118, s4, v117
	global_store_dwordx2 v[110:111], v[116:117], off offset:1536
	ds_read_b128 v[116:119], v109 offset:28672
	ds_read_b128 v[120:123], v109 offset:36864
	s_waitcnt lgkmcnt(0)
	v_pk_add_f32 v[120:121], v[120:121], 1.0 op_sel_hi:[1,0]
	s_nop 0
	v_pk_fma_f32 v[114:115], v[120:121], v[114:115], v[116:117]
	v_pk_add_f32 v[122:123], v[122:123], 1.0 op_sel_hi:[1,0]
	v_bfe_u32 v116, v114, 16, 1
	v_add3_u32 v114, v114, v116, s69
	v_bfe_u32 v116, v115, 16, 1
	v_pk_fma_f32 v[112:113], v[122:123], v[112:113], v[118:119]
	v_lshrrev_b32_e32 v114, 16, v114
	v_add3_u32 v115, v115, v116, s69
	v_and_or_b32 v114, v115, s4, v114
	v_bfe_u32 v115, v112, 16, 1
	v_add3_u32 v112, v112, v115, s69
	v_bfe_u32 v115, v113, 16, 1
	v_lshrrev_b32_e32 v112, 16, v112
	v_add3_u32 v113, v113, v115, s69
	v_and_or_b32 v115, v113, s4, v112
	global_store_dwordx2 v[110:111], v[114:115], off offset:2048
	ds_read_b128 v[112:115], v109 offset:29696
	ds_read_b128 v[116:119], v109 offset:37888
	s_waitcnt lgkmcnt(0)
	v_pk_add_f32 v[116:117], v[116:117], 1.0 op_sel_hi:[1,0]
	s_nop 0
	v_pk_fma_f32 v[104:105], v[116:117], v[104:105], v[112:113]
	v_pk_add_f32 v[118:119], v[118:119], 1.0 op_sel_hi:[1,0]
	v_bfe_u32 v112, v104, 16, 1
	v_add3_u32 v104, v104, v112, s69
	v_bfe_u32 v112, v105, 16, 1
	v_pk_fma_f32 v[106:107], v[118:119], v[106:107], v[114:115]
	v_lshrrev_b32_e32 v104, 16, v104
	v_add3_u32 v105, v105, v112, s69
	v_and_or_b32 v104, v105, s4, v104
	v_bfe_u32 v105, v106, 16, 1
	v_add3_u32 v105, v106, v105, s69
	v_bfe_u32 v106, v107, 16, 1
	v_lshrrev_b32_e32 v105, 16, v105
	v_add3_u32 v106, v107, v106, s69
	v_and_or_b32 v105, v106, s4, v105
	global_store_dwordx2 v[110:111], v[104:105], off offset:2560
	ds_read_b128 v[104:107], v109 offset:30720
	ds_read_b128 v[112:115], v109 offset:38912
	s_waitcnt lgkmcnt(0)
	v_pk_add_f32 v[112:113], v[112:113], 1.0 op_sel_hi:[1,0]
	s_nop 0
	v_pk_fma_f32 v[100:101], v[112:113], v[100:101], v[104:105]
	v_pk_add_f32 v[114:115], v[114:115], 1.0 op_sel_hi:[1,0]
	v_bfe_u32 v104, v100, 16, 1
	v_add3_u32 v100, v100, v104, s69
	v_bfe_u32 v104, v101, 16, 1
	v_pk_fma_f32 v[102:103], v[114:115], v[102:103], v[106:107]
	v_lshrrev_b32_e32 v100, 16, v100
	v_add3_u32 v101, v101, v104, s69
	v_and_or_b32 v100, v101, s4, v100
	v_bfe_u32 v101, v102, 16, 1
	v_add3_u32 v101, v102, v101, s69
	v_bfe_u32 v102, v103, 16, 1
	v_lshrrev_b32_e32 v101, 16, v101
	v_add3_u32 v102, v103, v102, s69
	v_and_or_b32 v101, v102, s4, v101
	global_store_dwordx2 v[110:111], v[100:101], off offset:3072
	ds_read_b128 v[100:103], v109 offset:31744
	ds_read_b128 v[104:107], v109 offset:39936
	s_waitcnt lgkmcnt(0)
	v_pk_add_f32 v[104:105], v[104:105], 1.0 op_sel_hi:[1,0]
	s_nop 0
	v_pk_fma_f32 v[98:99], v[104:105], v[98:99], v[100:101]
	v_pk_add_f32 v[106:107], v[106:107], 1.0 op_sel_hi:[1,0]
	v_bfe_u32 v100, v98, 16, 1
	v_add3_u32 v98, v98, v100, s69
	v_bfe_u32 v100, v99, 16, 1
	v_pk_fma_f32 v[96:97], v[106:107], v[96:97], v[102:103]
	v_lshrrev_b32_e32 v98, 16, v98
	v_add3_u32 v99, v99, v100, s69
	v_and_or_b32 v98, v99, s4, v98
	v_bfe_u32 v99, v96, 16, 1
	v_add3_u32 v96, v96, v99, s69
	v_bfe_u32 v99, v97, 16, 1
	v_lshrrev_b32_e32 v96, 16, v96
	v_add3_u32 v97, v97, v99, s69
	v_and_or_b32 v99, v97, s4, v96
	global_store_dwordx2 v[110:111], v[98:99], off offset:3584
	s_branch .LBB0_918

.LBB0_926:
	v_lshl_add_u64 v[0:1], s[0:1], 0, v[144:145]
	v_add_co_u32_e32 v4, vcc, 0x1dc00000, v0
	s_add_i32 s18, s18, s88
	s_nop 0
	v_addc_co_u32_e32 v5, vcc, 0, v1, vcc
	v_add_co_u32_e32 v8, vcc, 0x1e000000, v0
	global_load_dwordx2 v[6:7], v[4:5], off
	s_nop 0
	v_addc_co_u32_e32 v9, vcc, 0, v1, vcc
	v_add_co_u32_e32 v10, vcc, 0x1e400000, v0
	global_load_dwordx2 v[78:79], v[8:9], off
	s_nop 0
	v_addc_co_u32_e32 v11, vcc, 0, v1, vcc
	v_add_co_u32_e32 v90, vcc, 0x1e800000, v0
	global_load_dwordx2 v[80:81], v[10:11], off
	s_nop 0
	v_addc_co_u32_e32 v91, vcc, 0, v1, vcc
	global_load_dwordx2 v[92:93], v[90:91], off
	v_lshl_add_u64 v[0:1], s[16:17], 0, v[144:145]
	v_add_co_u32_e32 v2, vcc, 0xc800000, v0
	s_add_u32 s0, s0, s62
	s_nop 0
	v_addc_co_u32_e32 v3, vcc, 0, v1, vcc
	global_load_dwordx2 v[94:95], v[2:3], off
	global_load_dwordx2 v[76:77], v[4:5], off offset:512
	global_load_dwordx2 v[74:75], v[8:9], off offset:512
	global_load_dwordx2 v[72:73], v[10:11], off offset:512
	global_load_dwordx2 v[20:21], v[90:91], off offset:512
	global_load_dwordx2 v[18:19], v[2:3], off offset:512
	global_load_dwordx2 v[70:71], v[4:5], off offset:1024
	global_load_dwordx2 v[68:69], v[8:9], off offset:1024
	global_load_dwordx2 v[66:67], v[10:11], off offset:1024
	global_load_dwordx2 v[34:35], v[90:91], off offset:1024
	global_load_dwordx2 v[32:33], v[2:3], off offset:1024
	global_load_dwordx2 v[64:65], v[4:5], off offset:1536
	global_load_dwordx2 v[62:63], v[8:9], off offset:1536
	global_load_dwordx2 v[60:61], v[10:11], off offset:1536
	global_load_dwordx2 v[48:49], v[90:91], off offset:1536
	global_load_dwordx2 v[46:47], v[2:3], off offset:1536
	global_load_dwordx2 v[58:59], v[4:5], off offset:2048
	global_load_dwordx2 v[56:57], v[8:9], off offset:2048
	global_load_dwordx2 v[54:55], v[10:11], off offset:2048
	global_load_dwordx2 v[52:53], v[90:91], off offset:2048
	global_load_dwordx2 v[50:51], v[2:3], off offset:2048
	global_load_dwordx2 v[44:45], v[4:5], off offset:2560
	global_load_dwordx2 v[42:43], v[8:9], off offset:2560
	global_load_dwordx2 v[40:41], v[10:11], off offset:2560
	global_load_dwordx2 v[38:39], v[90:91], off offset:2560
	global_load_dwordx2 v[36:37], v[2:3], off offset:2560
	global_load_dwordx2 v[30:31], v[4:5], off offset:3072
	global_load_dwordx2 v[28:29], v[8:9], off offset:3072
	global_load_dwordx2 v[26:27], v[10:11], off offset:3072
	global_load_dwordx2 v[24:25], v[90:91], off offset:3072
	global_load_dwordx2 v[22:23], v[2:3], off offset:3072
	global_load_dwordx2 v[16:17], v[4:5], off offset:3584
	global_load_dwordx2 v[14:15], v[8:9], off offset:3584
	global_load_dwordx2 v[12:13], v[10:11], off offset:3584
	s_nop 0
	global_load_dwordx2 v[10:11], v[90:91], off offset:3584
	global_load_dwordx2 v[8:9], v[2:3], off offset:3584
	s_addc_u32 s1, s1, s63
	s_add_u32 s16, s16, s62
	s_addc_u32 s17, s17, s63
	s_cmpk_lt_i32 s18, 0x4400
	s_waitcnt vmcnt(39)
	v_lshlrev_b32_e32 v4, 16, v6
	v_and_b32_e32 v5, 0xffff0000, v6
	v_lshlrev_b32_e32 v6, 16, v7
	v_and_b32_e32 v7, 0xffff0000, v7
	s_waitcnt vmcnt(38)
	v_lshlrev_b32_e32 v90, 16, v78
	v_and_b32_e32 v91, 0xffff0000, v78
	v_lshlrev_b32_e32 v78, 16, v79
	v_and_b32_e32 v79, 0xffff0000, v79
	v_pk_add_f32 v[90:91], v[4:5], v[90:91]
	v_pk_add_f32 v[4:5], v[6:7], v[78:79]
	s_waitcnt vmcnt(37)
	v_lshlrev_b32_e32 v6, 16, v80
	v_and_b32_e32 v7, 0xffff0000, v80
	v_lshlrev_b32_e32 v78, 16, v81
	v_and_b32_e32 v79, 0xffff0000, v81
	s_waitcnt vmcnt(36)
	v_lshlrev_b32_e32 v80, 16, v92
	v_and_b32_e32 v81, 0xffff0000, v92
	v_lshlrev_b32_e32 v92, 16, v93
	v_and_b32_e32 v93, 0xffff0000, v93
	v_pk_add_f32 v[6:7], v[6:7], v[80:81]
	v_pk_add_f32 v[78:79], v[78:79], v[92:93]
	s_waitcnt vmcnt(35)
	v_cvt_f32_f16_e32 v80, v95
	v_pk_add_f32 v[4:5], v[4:5], v[78:79]
	v_pk_add_f32 v[78:79], v[90:91], v[6:7]
	ds_read_b128 v[90:93], v88 offset:16384
	v_cvt_f32_f16_e32 v6, v94
	v_cvt_f32_f16_sdwa v7, v94 dst_sel:DWORD dst_unused:UNUSED_PAD src0_sel:WORD_1
	v_cvt_f32_f16_sdwa v81, v95 dst_sel:DWORD dst_unused:UNUSED_PAD src0_sel:WORD_1
	s_waitcnt lgkmcnt(0)
	v_pk_mul_f32 v[78:79], v[78:79], v[90:91]
	v_pk_mul_f32 v[4:5], v[4:5], v[92:93]
	v_pk_fma_f32 v[6:7], v[6:7], s[8:9], v[78:79] op_sel_hi:[1,0,1]
	v_pk_fma_f32 v[4:5], v[80:81], s[8:9], v[4:5] op_sel_hi:[1,0,1]
	s_waitcnt vmcnt(34)
	v_lshlrev_b32_e32 v78, 16, v76
	v_and_b32_e32 v79, 0xffff0000, v76
	v_lshlrev_b32_e32 v76, 16, v77
	v_and_b32_e32 v77, 0xffff0000, v77
	s_waitcnt vmcnt(33)
	v_lshlrev_b32_e32 v80, 16, v74
	v_and_b32_e32 v81, 0xffff0000, v74
	v_lshlrev_b32_e32 v74, 16, v75
	v_and_b32_e32 v75, 0xffff0000, v75
	v_pk_add_f32 v[78:79], v[78:79], v[80:81]
	v_pk_add_f32 v[74:75], v[76:77], v[74:75]
	s_waitcnt vmcnt(32)
	v_lshlrev_b32_e32 v76, 16, v72
	v_and_b32_e32 v77, 0xffff0000, v72
	v_lshlrev_b32_e32 v72, 16, v73
	v_and_b32_e32 v73, 0xffff0000, v73
	s_waitcnt vmcnt(31)
	v_lshlrev_b32_e32 v80, 16, v20
	v_and_b32_e32 v81, 0xffff0000, v20
	v_lshlrev_b32_e32 v20, 16, v21
	v_and_b32_e32 v21, 0xffff0000, v21
	v_pk_add_f32 v[76:77], v[76:77], v[80:81]
	v_pk_add_f32 v[20:21], v[72:73], v[20:21]
	s_nop 0
	v_pk_add_f32 v[72:73], v[74:75], v[20:21]
	v_pk_add_f32 v[74:75], v[78:79], v[76:77]
	s_waitcnt vmcnt(30)
	v_cvt_f32_f16_e32 v76, v18
	v_cvt_f32_f16_sdwa v77, v18 dst_sel:DWORD dst_unused:UNUSED_PAD src0_sel:WORD_1
	v_cvt_f32_f16_e32 v78, v19
	v_cvt_f32_f16_sdwa v79, v19 dst_sel:DWORD dst_unused:UNUSED_PAD src0_sel:WORD_1
	ds_read_b128 v[18:21], v88 offset:17408
	s_waitcnt lgkmcnt(0)
	v_pk_mul_f32 v[74:75], v[74:75], v[18:19]
	v_pk_mul_f32 v[18:19], v[72:73], v[20:21]
	v_pk_fma_f32 v[20:21], v[76:77], s[8:9], v[74:75] op_sel_hi:[1,0,1]
	s_waitcnt vmcnt(29)
	v_lshlrev_b32_e32 v72, 16, v70
	v_and_b32_e32 v73, 0xffff0000, v70
	v_lshlrev_b32_e32 v70, 16, v71
	v_and_b32_e32 v71, 0xffff0000, v71
	s_waitcnt vmcnt(28)
	v_lshlrev_b32_e32 v74, 16, v68
	v_and_b32_e32 v75, 0xffff0000, v68
	v_lshlrev_b32_e32 v68, 16, v69
	v_and_b32_e32 v69, 0xffff0000, v69
	v_pk_add_f32 v[72:73], v[72:73], v[74:75]
	v_pk_add_f32 v[68:69], v[70:71], v[68:69]
	s_waitcnt vmcnt(27)
	v_lshlrev_b32_e32 v70, 16, v66
	v_and_b32_e32 v71, 0xffff0000, v66
	v_lshlrev_b32_e32 v66, 16, v67
	v_and_b32_e32 v67, 0xffff0000, v67
	s_waitcnt vmcnt(26)
	v_lshlrev_b32_e32 v74, 16, v34
	v_and_b32_e32 v75, 0xffff0000, v34
	v_lshlrev_b32_e32 v34, 16, v35
	v_and_b32_e32 v35, 0xffff0000, v35
	v_pk_add_f32 v[70:71], v[70:71], v[74:75]
	v_pk_add_f32 v[34:35], v[66:67], v[34:35]
	v_pk_fma_f32 v[18:19], v[78:79], s[8:9], v[18:19] op_sel_hi:[1,0,1]
	v_pk_add_f32 v[66:67], v[68:69], v[34:35]
	v_pk_add_f32 v[68:69], v[72:73], v[70:71]
	s_waitcnt vmcnt(25)
	v_cvt_f32_f16_e32 v70, v32
	v_cvt_f32_f16_sdwa v71, v32 dst_sel:DWORD dst_unused:UNUSED_PAD src0_sel:WORD_1
	v_cvt_f32_f16_e32 v72, v33
	v_cvt_f32_f16_sdwa v73, v33 dst_sel:DWORD dst_unused:UNUSED_PAD src0_sel:WORD_1
	ds_read_b128 v[32:35], v88 offset:18432
	s_waitcnt lgkmcnt(0)
	v_pk_mul_f32 v[32:33], v[68:69], v[32:33]
	v_pk_mul_f32 v[34:35], v[66:67], v[34:35]
	s_waitcnt vmcnt(24)
	v_lshlrev_b32_e32 v66, 16, v64
	v_and_b32_e32 v67, 0xffff0000, v64
	v_lshlrev_b32_e32 v64, 16, v65
	v_and_b32_e32 v65, 0xffff0000, v65
	s_waitcnt vmcnt(23)
	v_lshlrev_b32_e32 v68, 16, v62
	v_and_b32_e32 v69, 0xffff0000, v62
	v_lshlrev_b32_e32 v62, 16, v63
	v_and_b32_e32 v63, 0xffff0000, v63
	v_pk_add_f32 v[66:67], v[66:67], v[68:69]
	v_pk_add_f32 v[62:63], v[64:65], v[62:63]
	s_waitcnt vmcnt(22)
	v_lshlrev_b32_e32 v64, 16, v60
	v_and_b32_e32 v65, 0xffff0000, v60
	v_lshlrev_b32_e32 v60, 16, v61
	v_and_b32_e32 v61, 0xffff0000, v61
	s_waitcnt vmcnt(21)
	v_lshlrev_b32_e32 v68, 16, v48
	v_and_b32_e32 v69, 0xffff0000, v48
	v_lshlrev_b32_e32 v48, 16, v49
	v_and_b32_e32 v49, 0xffff0000, v49
	v_pk_add_f32 v[64:65], v[64:65], v[68:69]
	v_pk_add_f32 v[48:49], v[60:61], v[48:49]
	v_pk_fma_f32 v[34:35], v[72:73], s[8:9], v[34:35] op_sel_hi:[1,0,1]
	v_pk_add_f32 v[60:61], v[62:63], v[48:49]
	v_pk_add_f32 v[62:63], v[66:67], v[64:65]
	s_waitcnt vmcnt(20)
	v_cvt_f32_f16_e32 v64, v46
	v_cvt_f32_f16_sdwa v65, v46 dst_sel:DWORD dst_unused:UNUSED_PAD src0_sel:WORD_1
	v_cvt_f32_f16_e32 v66, v47
	v_cvt_f32_f16_sdwa v67, v47 dst_sel:DWORD dst_unused:UNUSED_PAD src0_sel:WORD_1
	ds_read_b128 v[46:49], v88 offset:19456
	v_pk_fma_f32 v[32:33], v[70:71], s[8:9], v[32:33] op_sel_hi:[1,0,1]
	s_waitcnt lgkmcnt(0)
	v_pk_mul_f32 v[46:47], v[62:63], v[46:47]
	v_pk_mul_f32 v[48:49], v[60:61], v[48:49]
	s_waitcnt vmcnt(19)
	v_lshlrev_b32_e32 v60, 16, v58
	v_and_b32_e32 v61, 0xffff0000, v58
	v_lshlrev_b32_e32 v58, 16, v59
	v_and_b32_e32 v59, 0xffff0000, v59
	s_waitcnt vmcnt(18)
	v_lshlrev_b32_e32 v62, 16, v56
	v_and_b32_e32 v63, 0xffff0000, v56
	v_lshlrev_b32_e32 v56, 16, v57
	v_and_b32_e32 v57, 0xffff0000, v57
	v_pk_add_f32 v[60:61], v[60:61], v[62:63]
	v_pk_add_f32 v[56:57], v[58:59], v[56:57]
	s_waitcnt vmcnt(17)
	v_lshlrev_b32_e32 v58, 16, v54
	v_and_b32_e32 v59, 0xffff0000, v54
	v_lshlrev_b32_e32 v54, 16, v55
	v_and_b32_e32 v55, 0xffff0000, v55
	s_waitcnt vmcnt(16)
	v_lshlrev_b32_e32 v62, 16, v52
	v_and_b32_e32 v63, 0xffff0000, v52
	v_lshlrev_b32_e32 v52, 16, v53
	v_and_b32_e32 v53, 0xffff0000, v53
	v_pk_add_f32 v[58:59], v[58:59], v[62:63]
	v_pk_add_f32 v[52:53], v[54:55], v[52:53]
	v_pk_fma_f32 v[48:49], v[66:67], s[8:9], v[48:49] op_sel_hi:[1,0,1]
	v_pk_add_f32 v[54:55], v[56:57], v[52:53]
	v_pk_add_f32 v[56:57], v[60:61], v[58:59]
	s_waitcnt vmcnt(15)
	v_cvt_f32_f16_e32 v58, v50
	v_cvt_f32_f16_sdwa v59, v50 dst_sel:DWORD dst_unused:UNUSED_PAD src0_sel:WORD_1
	v_cvt_f32_f16_e32 v60, v51
	v_cvt_f32_f16_sdwa v61, v51 dst_sel:DWORD dst_unused:UNUSED_PAD src0_sel:WORD_1
	ds_read_b128 v[50:53], v88 offset:20480
	v_pk_fma_f32 v[46:47], v[64:65], s[8:9], v[46:47] op_sel_hi:[1,0,1]
	s_waitcnt lgkmcnt(0)
	v_pk_mul_f32 v[50:51], v[56:57], v[50:51]
	v_pk_mul_f32 v[52:53], v[54:55], v[52:53]
	s_waitcnt vmcnt(14)
	v_lshlrev_b32_e32 v54, 16, v44
	v_and_b32_e32 v55, 0xffff0000, v44
	v_lshlrev_b32_e32 v44, 16, v45
	v_and_b32_e32 v45, 0xffff0000, v45
	s_waitcnt vmcnt(13)
	v_lshlrev_b32_e32 v56, 16, v42
	v_and_b32_e32 v57, 0xffff0000, v42
	v_lshlrev_b32_e32 v42, 16, v43
	v_and_b32_e32 v43, 0xffff0000, v43
	v_pk_add_f32 v[54:55], v[54:55], v[56:57]
	v_pk_add_f32 v[42:43], v[44:45], v[42:43]
	s_waitcnt vmcnt(12)
	v_lshlrev_b32_e32 v44, 16, v40
	v_and_b32_e32 v45, 0xffff0000, v40
	v_lshlrev_b32_e32 v40, 16, v41
	v_and_b32_e32 v41, 0xffff0000, v41
	s_waitcnt vmcnt(11)
	v_lshlrev_b32_e32 v56, 16, v38
	v_and_b32_e32 v57, 0xffff0000, v38
	v_lshlrev_b32_e32 v38, 16, v39
	v_and_b32_e32 v39, 0xffff0000, v39
	v_pk_add_f32 v[44:45], v[44:45], v[56:57]
	v_pk_add_f32 v[38:39], v[40:41], v[38:39]
	v_pk_fma_f32 v[52:53], v[60:61], s[8:9], v[52:53] op_sel_hi:[1,0,1]
	v_pk_add_f32 v[40:41], v[42:43], v[38:39]
	v_pk_add_f32 v[42:43], v[54:55], v[44:45]
	s_waitcnt vmcnt(10)
	v_cvt_f32_f16_e32 v44, v36
	v_cvt_f32_f16_sdwa v45, v36 dst_sel:DWORD dst_unused:UNUSED_PAD src0_sel:WORD_1
	v_cvt_f32_f16_e32 v54, v37
	v_cvt_f32_f16_sdwa v55, v37 dst_sel:DWORD dst_unused:UNUSED_PAD src0_sel:WORD_1
	ds_read_b128 v[36:39], v88 offset:21504
	v_pk_fma_f32 v[50:51], v[58:59], s[8:9], v[50:51] op_sel_hi:[1,0,1]
	s_waitcnt lgkmcnt(0)
	v_pk_mul_f32 v[36:37], v[42:43], v[36:37]
	v_pk_mul_f32 v[38:39], v[40:41], v[38:39]
	s_waitcnt vmcnt(9)
	v_lshlrev_b32_e32 v40, 16, v30
	v_and_b32_e32 v41, 0xffff0000, v30
	v_lshlrev_b32_e32 v30, 16, v31
	v_and_b32_e32 v31, 0xffff0000, v31
	s_waitcnt vmcnt(8)
	v_lshlrev_b32_e32 v42, 16, v28
	v_and_b32_e32 v43, 0xffff0000, v28
	v_lshlrev_b32_e32 v28, 16, v29
	v_and_b32_e32 v29, 0xffff0000, v29
	v_pk_add_f32 v[40:41], v[40:41], v[42:43]
	v_pk_add_f32 v[28:29], v[30:31], v[28:29]
	s_waitcnt vmcnt(7)
	v_lshlrev_b32_e32 v30, 16, v26
	v_and_b32_e32 v31, 0xffff0000, v26
	v_lshlrev_b32_e32 v26, 16, v27
	v_and_b32_e32 v27, 0xffff0000, v27
	s_waitcnt vmcnt(6)
	v_lshlrev_b32_e32 v42, 16, v24
	v_and_b32_e32 v43, 0xffff0000, v24
	v_lshlrev_b32_e32 v24, 16, v25
	v_and_b32_e32 v25, 0xffff0000, v25
	v_pk_add_f32 v[30:31], v[30:31], v[42:43]
	v_pk_add_f32 v[24:25], v[26:27], v[24:25]
	v_pk_fma_f32 v[38:39], v[54:55], s[8:9], v[38:39] op_sel_hi:[1,0,1]
	v_pk_add_f32 v[26:27], v[28:29], v[24:25]
	v_pk_add_f32 v[28:29], v[40:41], v[30:31]
	s_waitcnt vmcnt(5)
	v_cvt_f32_f16_e32 v30, v22
	v_cvt_f32_f16_sdwa v31, v22 dst_sel:DWORD dst_unused:UNUSED_PAD src0_sel:WORD_1
	v_cvt_f32_f16_e32 v40, v23
	v_cvt_f32_f16_sdwa v41, v23 dst_sel:DWORD dst_unused:UNUSED_PAD src0_sel:WORD_1
	ds_read_b128 v[22:25], v88 offset:22528
	v_pk_fma_f32 v[36:37], v[44:45], s[8:9], v[36:37] op_sel_hi:[1,0,1]
	s_waitcnt lgkmcnt(0)
	v_pk_mul_f32 v[28:29], v[28:29], v[22:23]
	v_pk_mul_f32 v[22:23], v[26:27], v[24:25]
	v_pk_fma_f32 v[24:25], v[30:31], s[8:9], v[28:29] op_sel_hi:[1,0,1]
	s_waitcnt vmcnt(4)
	v_lshlrev_b32_e32 v26, 16, v16
	v_and_b32_e32 v27, 0xffff0000, v16
	v_lshlrev_b32_e32 v16, 16, v17
	v_and_b32_e32 v17, 0xffff0000, v17
	s_waitcnt vmcnt(3)
	v_lshlrev_b32_e32 v28, 16, v14
	v_and_b32_e32 v29, 0xffff0000, v14
	v_lshlrev_b32_e32 v14, 16, v15
	v_and_b32_e32 v15, 0xffff0000, v15
	v_pk_add_f32 v[26:27], v[26:27], v[28:29]
	v_pk_add_f32 v[14:15], v[16:17], v[14:15]
	s_waitcnt vmcnt(2)
	v_lshlrev_b32_e32 v16, 16, v12
	v_and_b32_e32 v17, 0xffff0000, v12
	v_lshlrev_b32_e32 v12, 16, v13
	v_and_b32_e32 v13, 0xffff0000, v13
	s_waitcnt vmcnt(1)
	v_lshlrev_b32_e32 v28, 16, v10
	v_and_b32_e32 v29, 0xffff0000, v10
	v_lshlrev_b32_e32 v10, 16, v11
	v_and_b32_e32 v11, 0xffff0000, v11
	v_pk_add_f32 v[16:17], v[16:17], v[28:29]
	v_pk_add_f32 v[10:11], v[12:13], v[10:11]
	v_pk_fma_f32 v[22:23], v[40:41], s[8:9], v[22:23] op_sel_hi:[1,0,1]
	v_pk_add_f32 v[12:13], v[14:15], v[10:11]
	v_pk_add_f32 v[14:15], v[26:27], v[16:17]
	s_waitcnt vmcnt(0)
	v_cvt_f32_f16_e32 v16, v8
	v_cvt_f32_f16_sdwa v17, v8 dst_sel:DWORD dst_unused:UNUSED_PAD src0_sel:WORD_1
	v_cvt_f32_f16_e32 v26, v9
	v_cvt_f32_f16_sdwa v27, v9 dst_sel:DWORD dst_unused:UNUSED_PAD src0_sel:WORD_1
	ds_read_b128 v[8:11], v88 offset:23552
	s_waitcnt lgkmcnt(0)
	v_pk_mul_f32 v[8:9], v[8:9], v[14:15]
	v_pk_mul_f32 v[10:11], v[10:11], v[12:13]
	v_pk_fma_f32 v[54:55], v[16:17], s[8:9], v[8:9] op_sel_hi:[1,0,1]
	v_pk_fma_f32 v[44:45], v[26:27], s[8:9], v[10:11] op_sel_hi:[1,0,1]
	v_mov_b32_e32 v8, v6
	v_mov_b32_e32 v9, v20
	v_mov_b32_e32 v10, v7
	v_mov_b32_e32 v11, v21
	v_pk_add_f32 v[8:9], v[8:9], v[10:11]
	v_mov_b32_e32 v10, v4
	v_mov_b32_e32 v11, v18
	v_mov_b32_e32 v12, v5
	v_mov_b32_e32 v13, v19
	v_pk_add_f32 v[10:11], v[10:11], v[12:13]
	v_mov_b32_e32 v12, v32
	v_pk_add_f32 v[8:9], v[8:9], v[10:11]
	v_pk_mov_b32 v[10:11], v[32:33], v[34:35] op_sel:[1,0]
	v_mov_b32_e32 v13, v35
	v_pk_add_f32 v[10:11], v[10:11], v[12:13]
	v_add_f32_e32 v8, 0, v8
	v_pk_add_f32 v[10:11], v[10:11], v[10:11] op_sel:[0,1] op_sel_hi:[1,0]
	v_add_f32_e32 v8, v8, v9
	v_add_f32_e32 v12, v46, v47
	v_add_f32_e32 v14, v48, v49
	v_mov_b32_e32 v9, v50
	v_mov_b32_e32 v11, v51
	v_mov_b32_e32 v13, v52
	v_mov_b32_e32 v15, v53
	v_pk_add_f32 v[8:9], v[8:9], v[10:11]
	v_pk_add_f32 v[10:11], v[12:13], v[14:15]
	v_mov_b32_e32 v12, v36
	v_pk_add_f32 v[8:9], v[8:9], v[10:11]
	v_pk_mov_b32 v[10:11], v[36:37], v[38:39] op_sel:[1,0]
	v_mov_b32_e32 v13, v39
	v_pk_add_f32 v[10:11], v[10:11], v[12:13]
	v_pk_add_f32 v[8:9], v[8:9], v[8:9] op_sel:[0,1] op_sel_hi:[1,0]
	v_pk_add_f32 v[10:11], v[10:11], v[10:11] op_sel:[0,1] op_sel_hi:[1,0]
	v_add_f32_e32 v12, v24, v25
	v_add_f32_e32 v14, v22, v23
	v_mov_b32_e32 v9, v54
	v_mov_b32_e32 v11, v55
	v_mov_b32_e32 v13, v44
	v_mov_b32_e32 v15, v45
	v_pk_add_f32 v[8:9], v[8:9], v[10:11]
	v_pk_add_f32 v[10:11], v[12:13], v[14:15]
	s_nop 0
	v_pk_add_f32 v[8:9], v[8:9], v[10:11]
	s_nop 0
	v_add_f32_e32 v8, v8, v9
	s_waitcnt lgkmcnt(0)
	s_nop 1
	v_add_f32_dpp v8, v8, v8 quad_perm:[1,0,3,2] row_mask:0xf bank_mask:0xf
	s_nop 1
	v_add_f32_dpp v8, v8, v8 quad_perm:[2,3,0,1] row_mask:0xf bank_mask:0xf
	s_nop 1
	v_add_f32_dpp v8, v8, v8 row_half_mirror row_mask:0xf bank_mask:0xf
	s_nop 1
	v_add_f32_dpp v8, v8, v8 row_ror:8 row_mask:0xf bank_mask:0xf
	s_nop 0
	v_readlane_b32 s100, v8, 0
	v_readlane_b32 s101, v8, 16
	s_nop 0
	v_mov_b32_e32 v9, s100
	v_add_f32_e32 v9, s101, v9
	v_readlane_b32 s100, v8, 32
	v_readlane_b32 s101, v8, 48
	s_nop 0
	v_add_f32_e32 v9, s100, v9
	v_add_f32_e32 v16, s101, v9
	v_fmamk_f32 v7, v16, 0xba000000, v7
	v_fmamk_f32 v21, v16, 0xba000000, v21
	v_fmamk_f32 v5, v16, 0xba000000, v5
	v_fmac_f32_e32 v6, 0xba000000, v16
	v_fmamk_f32 v19, v16, 0xba000000, v19
	v_fmac_f32_e32 v20, 0xba000000, v16
	v_mov_b32_e32 v10, v7
	v_mov_b32_e32 v11, v21
	v_fmac_f32_e32 v4, 0xba000000, v16
	v_fmac_f32_e32 v18, 0xba000000, v16
	v_mov_b32_e32 v8, v6
	v_mov_b32_e32 v9, v20
	v_pk_mul_f32 v[10:11], v[10:11], v[10:11]
	v_mov_b32_e32 v12, v5
	v_mov_b32_e32 v13, v19
	v_pk_fma_f32 v[8:9], v[8:9], v[8:9], v[10:11]
	v_mov_b32_e32 v10, v4
	v_mov_b32_e32 v11, v18
	v_pk_mul_f32 v[12:13], v[12:13], v[12:13]
	v_fmamk_f32 v33, v16, 0xba000000, v33
	v_pk_fma_f32 v[10:11], v[10:11], v[10:11], v[12:13]
	v_fmac_f32_e32 v32, 0xba000000, v16
	v_pk_add_f32 v[8:9], v[8:9], v[10:11]
	v_fmamk_f32 v35, v16, 0xba000000, v35
	v_fmac_f32_e32 v34, 0xba000000, v16
	v_pk_add_f32 v[8:9], v[8:9], v[8:9] op_sel_hi:[0,1]
	v_pk_mul_f32 v[10:11], v[34:35], v[34:35]
	v_pk_mul_f32 v[12:13], v[32:33], v[32:33]
	v_fmac_f32_e32 v46, 0xba000000, v16
	v_pk_mov_b32 v[14:15], v[12:13], v[10:11] op_sel:[1,0]
	v_mov_b32_e32 v13, v11
	v_fmamk_f32 v47, v16, 0xba000000, v47
	v_fmac_f32_e32 v48, 0xba000000, v16
	v_mul_f32_e32 v8, v46, v46
	v_pk_add_f32 v[10:11], v[14:15], v[12:13]
	v_fmamk_f32 v49, v16, 0xba000000, v49
	v_pk_fma_f32 v[12:13], v[46:47], v[46:47], v[8:9] op_sel_hi:[1,1,0]
	v_mul_f32_e32 v8, v48, v48
	v_pk_add_f32 v[10:11], v[10:11], v[10:11] op_sel_hi:[0,1]
	v_pk_fma_f32 v[14:15], v[48:49], v[48:49], v[8:9] op_sel_hi:[1,1,0]
	v_fmamk_f32 v53, v16, 0xba000000, v53
	v_fmac_f32_e32 v52, 0xba000000, v16
	v_fmamk_f32 v51, v16, 0xba000000, v51
	v_fmac_f32_e32 v50, 0xba000000, v16
	v_mul_f32_e32 v12, v50, v50
	v_mul_f32_e32 v14, v51, v51
	v_mul_f32_e32 v10, v52, v52
	v_mul_f32_e32 v8, v53, v53
	v_pk_add_f32 v[12:13], v[12:13], v[14:15]
	v_pk_add_f32 v[8:9], v[10:11], v[8:9]
	v_fmamk_f32 v37, v16, 0xba000000, v37
	v_pk_add_f32 v[8:9], v[12:13], v[8:9]
	v_fmac_f32_e32 v36, 0xba000000, v16
	v_fmamk_f32 v39, v16, 0xba000000, v39
	v_fmac_f32_e32 v38, 0xba000000, v16
	v_pk_add_f32 v[8:9], v[8:9], v[8:9] op_sel_hi:[0,1]
	v_pk_mul_f32 v[10:11], v[38:39], v[38:39]
	v_pk_mul_f32 v[12:13], v[36:37], v[36:37]
	v_fmac_f32_e32 v24, 0xba000000, v16
	v_pk_mov_b32 v[14:15], v[12:13], v[10:11] op_sel:[1,0]
	v_mov_b32_e32 v13, v11
	v_fmamk_f32 v25, v16, 0xba000000, v25
	v_fmac_f32_e32 v22, 0xba000000, v16
	v_mul_f32_e32 v8, v24, v24
	v_pk_add_f32 v[10:11], v[14:15], v[12:13]
	v_fmamk_f32 v23, v16, 0xba000000, v23
	v_pk_fma_f32 v[12:13], v[24:25], v[24:25], v[8:9] op_sel_hi:[1,1,0]
	v_mul_f32_e32 v8, v22, v22
	v_pk_add_f32 v[10:11], v[10:11], v[10:11] op_sel_hi:[0,1]
	v_pk_fma_f32 v[14:15], v[22:23], v[22:23], v[8:9] op_sel_hi:[1,1,0]
	v_fmamk_f32 v45, v16, 0xba000000, v45
	v_fmac_f32_e32 v44, 0xba000000, v16
	v_fmamk_f32 v55, v16, 0xba000000, v55
	v_fmac_f32_e32 v54, 0xba000000, v16
	v_mul_f32_e32 v12, v54, v54
	v_mul_f32_e32 v14, v55, v55
	v_mul_f32_e32 v10, v44, v44
	v_mul_f32_e32 v8, v45, v45
	v_pk_add_f32 v[12:13], v[12:13], v[14:15]
	v_pk_add_f32 v[8:9], v[10:11], v[8:9]
	s_nop 0
	v_pk_add_f32 v[8:9], v[12:13], v[8:9]
	s_nop 0
	v_add_f32_e32 v8, v8, v9
	s_waitcnt lgkmcnt(0)
	s_nop 1
	v_add_f32_dpp v8, v8, v8 quad_perm:[1,0,3,2] row_mask:0xf bank_mask:0xf
	s_nop 1
	v_add_f32_dpp v8, v8, v8 quad_perm:[2,3,0,1] row_mask:0xf bank_mask:0xf
	s_nop 1
	v_add_f32_dpp v8, v8, v8 row_half_mirror row_mask:0xf bank_mask:0xf
	s_nop 1
	v_add_f32_dpp v8, v8, v8 row_ror:8 row_mask:0xf bank_mask:0xf
	s_nop 0
	v_readlane_b32 s100, v8, 0
	v_readlane_b32 s101, v8, 16
	s_nop 0
	v_mov_b32_e32 v9, s100
	v_add_f32_e32 v9, s101, v9
	v_readlane_b32 s100, v8, 32
	v_readlane_b32 s101, v8, 48
	s_nop 0
	v_add_f32_e32 v9, s100, v9
	v_add_f32_e32 v8, s101, v9
	v_fmamk_f32 v8, v8, 0x3a000000, v229
	v_cmp_gt_f32_e32 vcc, s5, v8
	v_mul_f32_e32 v9, 0x4f800000, v8
	s_nop 0
	v_cndmask_b32_e32 v8, v8, v9, vcc
	v_sqrt_f32_e32 v9, v8
	s_nop 0
	v_add_u32_e32 v10, -1, v9
	v_fma_f32 v11, -v10, v9, v8
	v_cmp_ge_f32_e64 s[14:15], 0, v11
	v_add_u32_e32 v11, 1, v9
	s_nop 0
	v_cndmask_b32_e64 v10, v9, v10, s[14:15]
	v_fma_f32 v9, -v11, v9, v8
	v_cmp_lt_f32_e64 s[14:15], 0, v9
	s_nop 1
	v_cndmask_b32_e64 v9, v10, v11, s[14:15]
	v_mul_f32_e32 v10, 0x37800000, v9
	v_cndmask_b32_e32 v9, v9, v10, vcc
	v_cmp_class_f32_e32 vcc, v8, v230
	s_nop 1
	v_cndmask_b32_e32 v8, v9, v8, vcc
	v_div_scale_f32 v9, s[14:15], v8, v8, 1.0
	v_rcp_f32_e32 v10, v9
	s_nop 0
	v_fma_f32 v11, -v9, v10, 1.0
	v_fmac_f32_e32 v10, v11, v10
	v_div_scale_f32 v11, vcc, 1.0, v8, 1.0
	v_mul_f32_e32 v12, v11, v10
	v_fma_f32 v13, -v9, v12, v11
	v_fmac_f32_e32 v12, v13, v10
	v_fma_f32 v9, -v9, v12, v11
	v_div_fmas_f32 v9, v9, v10, v12
	v_div_fixup_f32 v56, v9, v8, 1.0
	ds_read_b128 v[8:11], v88
	ds_read_b128 v[12:15], v88 offset:8192
	v_pk_mul_f32 v[4:5], v[4:5], v[56:57] op_sel_hi:[1,0]
	v_pk_mul_f32 v[6:7], v[6:7], v[56:57] op_sel_hi:[1,0]
	s_waitcnt lgkmcnt(0)
	v_pk_fma_f32 v[60:61], v[10:11], v[4:5], v[14:15]
	v_pk_fma_f32 v[58:59], v[8:9], v[6:7], v[12:13]
	v_cvt_pk_f16_f32 v5, v60, v61
	v_cvt_pk_f16_f32 v4, v58, v59
	global_store_dwordx2 v[2:3], v[4:5], off
	ds_read_b128 v[4:7], v88 offset:1024
	ds_read_b128 v[8:11], v88 offset:9216
	v_pk_mul_f32 v[12:13], v[18:19], v[56:57] op_sel_hi:[1,0]
	v_pk_mul_f32 v[14:15], v[20:21], v[56:57] op_sel_hi:[1,0]
	s_waitcnt lgkmcnt(0)
	v_pk_fma_f32 v[40:41], v[6:7], v[12:13], v[10:11]
	v_pk_fma_f32 v[42:43], v[4:5], v[14:15], v[8:9]
	v_cvt_pk_f16_f32 v5, v40, v41
	v_cvt_pk_f16_f32 v4, v42, v43
	global_store_dwordx2 v[2:3], v[4:5], off offset:512
	ds_read_b128 v[4:7], v88 offset:2048
	ds_read_b128 v[8:11], v88 offset:10240
	v_pk_mul_f32 v[12:13], v[34:35], v[56:57] op_sel_hi:[1,0]
	v_pk_mul_f32 v[14:15], v[32:33], v[56:57] op_sel_hi:[1,0]
	s_waitcnt lgkmcnt(0)
	v_pk_fma_f32 v[30:31], v[6:7], v[12:13], v[10:11]
	v_pk_fma_f32 v[28:29], v[4:5], v[14:15], v[8:9]
	v_cvt_pk_f16_f32 v5, v30, v31
	v_cvt_pk_f16_f32 v4, v28, v29
	global_store_dwordx2 v[2:3], v[4:5], off offset:1024
	ds_read_b128 v[4:7], v88 offset:3072
	ds_read_b128 v[8:11], v88 offset:11264
	v_pk_mul_f32 v[12:13], v[48:49], v[56:57] op_sel_hi:[1,0]
	v_pk_mul_f32 v[14:15], v[46:47], v[56:57] op_sel_hi:[1,0]
	s_waitcnt lgkmcnt(0)
	v_pk_fma_f32 v[26:27], v[6:7], v[12:13], v[10:11]
	v_pk_fma_f32 v[20:21], v[4:5], v[14:15], v[8:9]
	v_cvt_pk_f16_f32 v5, v26, v27
	v_cvt_pk_f16_f32 v4, v20, v21
	global_store_dwordx2 v[2:3], v[4:5], off offset:1536
	ds_read_b128 v[4:7], v88 offset:4096
	ds_read_b128 v[8:11], v88 offset:12288
	v_pk_mul_f32 v[12:13], v[52:53], v[56:57] op_sel_hi:[1,0]
	v_pk_mul_f32 v[14:15], v[50:51], v[56:57] op_sel_hi:[1,0]
	s_waitcnt lgkmcnt(0)
	v_pk_fma_f32 v[16:17], v[6:7], v[12:13], v[10:11]
	v_pk_fma_f32 v[18:19], v[4:5], v[14:15], v[8:9]
	v_cvt_pk_f16_f32 v5, v16, v17
	v_cvt_pk_f16_f32 v4, v18, v19
	global_store_dwordx2 v[2:3], v[4:5], off offset:2048
	ds_read_b128 v[4:7], v88 offset:5120
	ds_read_b128 v[8:11], v88 offset:13312
	v_pk_mul_f32 v[14:15], v[38:39], v[56:57] op_sel_hi:[1,0]
	v_pk_mul_f32 v[12:13], v[36:37], v[56:57] op_sel_hi:[1,0]
	s_waitcnt lgkmcnt(0)
	v_pk_fma_f32 v[14:15], v[6:7], v[14:15], v[10:11]
	v_pk_fma_f32 v[12:13], v[4:5], v[12:13], v[8:9]
	v_cvt_pk_f16_f32 v5, v14, v15
	v_cvt_pk_f16_f32 v4, v12, v13
	global_store_dwordx2 v[2:3], v[4:5], off offset:2560
	ds_read_b128 v[4:7], v88 offset:6144
	ds_read_b128 v[32:35], v88 offset:14336
	v_pk_mul_f32 v[10:11], v[24:25], v[56:57] op_sel_hi:[1,0]
	v_pk_mul_f32 v[8:9], v[22:23], v[56:57] op_sel_hi:[1,0]
	s_waitcnt lgkmcnt(0)
	v_pk_fma_f32 v[10:11], v[4:5], v[10:11], v[32:33]
	v_pk_fma_f32 v[8:9], v[6:7], v[8:9], v[34:35]
	v_cvt_pk_f16_f32 v4, v10, v11
	v_cvt_pk_f16_f32 v5, v8, v9
	global_store_dwordx2 v[2:3], v[4:5], off offset:3072
	ds_read_b128 v[22:25], v88 offset:7168
	ds_read_b128 v[32:35], v88 offset:15360
	v_pk_mul_f32 v[6:7], v[54:55], v[56:57] op_sel_hi:[1,0]
	v_pk_mul_f32 v[4:5], v[44:45], v[56:57] op_sel_hi:[1,0]
	s_waitcnt lgkmcnt(0)
	v_pk_fma_f32 v[6:7], v[22:23], v[6:7], v[32:33]
	v_pk_fma_f32 v[4:5], v[24:25], v[4:5], v[34:35]
	v_cvt_pk_f16_f32 v22, v6, v7
	v_cvt_pk_f16_f32 v23, v4, v5
	global_store_dwordx2 v[2:3], v[22:23], off offset:3584
	v_mov_b32_e32 v2, v42
	v_mov_b32_e32 v3, v58
	v_mov_b32_e32 v22, v43
	v_mov_b32_e32 v23, v59
	v_pk_add_f32 v[2:3], v[2:3], v[22:23]
	v_mov_b32_e32 v22, v40
	v_mov_b32_e32 v23, v60
	v_mov_b32_e32 v24, v41
	v_mov_b32_e32 v25, v61
	v_pk_add_f32 v[22:23], v[22:23], v[24:25]
	v_mov_b32_e32 v24, v28
	v_pk_add_f32 v[2:3], v[2:3], v[22:23]
	v_pk_mov_b32 v[22:23], v[28:29], v[30:31] op_sel:[1,0]
	v_mov_b32_e32 v25, v31
	v_pk_add_f32 v[22:23], v[22:23], v[24:25]
	v_add_f32_e32 v3, 0, v3
	v_pk_add_f32 v[22:23], v[22:23], v[22:23] op_sel_hi:[0,1]
	v_add_f32_e32 v3, v2, v3
	v_add_f32_e32 v25, v20, v21
	v_add_f32_e32 v33, v26, v27
	v_mov_b32_e32 v24, v18
	v_mov_b32_e32 v32, v19
	v_mov_b32_e32 v22, v16
	v_mov_b32_e32 v2, v17
	v_pk_add_f32 v[24:25], v[24:25], v[32:33]
	v_pk_add_f32 v[2:3], v[22:23], v[2:3]
	v_pk_mov_b32 v[22:23], v[12:13], v[14:15] op_sel:[1,0]
	v_pk_add_f32 v[2:3], v[24:25], v[2:3]
	v_mov_b32_e32 v24, v12
	v_mov_b32_e32 v25, v15
	v_pk_add_f32 v[22:23], v[22:23], v[24:25]
	v_pk_add_f32 v[2:3], v[2:3], v[2:3] op_sel_hi:[0,1]
	v_pk_add_f32 v[22:23], v[22:23], v[22:23] op_sel_hi:[0,1]
	v_add_f32_e32 v25, v10, v11
	v_add_f32_e32 v33, v8, v9
	v_mov_b32_e32 v24, v6
	v_mov_b32_e32 v32, v7
	v_mov_b32_e32 v22, v4
	v_mov_b32_e32 v2, v5
	v_pk_add_f32 v[24:25], v[24:25], v[32:33]
	v_pk_add_f32 v[2:3], v[22:23], v[2:3]
	s_nop 0
	v_pk_add_f32 v[2:3], v[24:25], v[2:3]
	s_nop 0
	v_add_f32_e32 v2, v2, v3
	s_waitcnt lgkmcnt(0)
	s_nop 1
	v_add_f32_dpp v2, v2, v2 quad_perm:[1,0,3,2] row_mask:0xf bank_mask:0xf
	s_nop 1
	v_add_f32_dpp v2, v2, v2 quad_perm:[2,3,0,1] row_mask:0xf bank_mask:0xf
	s_nop 1
	v_add_f32_dpp v2, v2, v2 row_half_mirror row_mask:0xf bank_mask:0xf
	s_nop 1
	v_add_f32_dpp v2, v2, v2 row_ror:8 row_mask:0xf bank_mask:0xf
	s_nop 0
	v_readlane_b32 s100, v2, 0
	v_readlane_b32 s101, v2, 16
	s_nop 0
	v_mov_b32_e32 v3, s100
	v_add_f32_e32 v3, s101, v3
	v_readlane_b32 s100, v2, 32
	v_readlane_b32 s101, v2, 48
	s_nop 0
	v_add_f32_e32 v3, s100, v3
	v_add_f32_e32 v34, s101, v3
	v_fmamk_f32 v59, v34, 0xba000000, v59
	v_fmamk_f32 v43, v34, 0xba000000, v43
	v_fmamk_f32 v61, v34, 0xba000000, v61
	v_fmac_f32_e32 v58, 0xba000000, v34
	v_fmamk_f32 v41, v34, 0xba000000, v41
	v_fmac_f32_e32 v42, 0xba000000, v34
	v_mov_b32_e32 v22, v59
	v_mov_b32_e32 v23, v43
	v_fmac_f32_e32 v60, 0xba000000, v34
	v_fmac_f32_e32 v40, 0xba000000, v34
	v_mov_b32_e32 v2, v58
	v_mov_b32_e32 v3, v42
	v_pk_mul_f32 v[22:23], v[22:23], v[22:23]
	v_mov_b32_e32 v24, v61
	v_mov_b32_e32 v25, v41
	v_pk_fma_f32 v[2:3], v[2:3], v[2:3], v[22:23]
	v_mov_b32_e32 v22, v60
	v_mov_b32_e32 v23, v40
	v_pk_mul_f32 v[24:25], v[24:25], v[24:25]
	v_fmamk_f32 v29, v34, 0xba000000, v29
	v_pk_fma_f32 v[22:23], v[22:23], v[22:23], v[24:25]
	v_fmac_f32_e32 v28, 0xba000000, v34
	v_pk_add_f32 v[2:3], v[2:3], v[22:23]
	v_fmamk_f32 v31, v34, 0xba000000, v31
	v_fmac_f32_e32 v30, 0xba000000, v34
	v_pk_add_f32 v[2:3], v[2:3], v[2:3] op_sel_hi:[0,1]
	v_pk_mul_f32 v[22:23], v[30:31], v[30:31]
	v_pk_mul_f32 v[24:25], v[28:29], v[28:29]
	v_fmac_f32_e32 v20, 0xba000000, v34
	v_pk_mov_b32 v[32:33], v[24:25], v[22:23] op_sel:[1,0]
	v_mov_b32_e32 v25, v23
	v_fmamk_f32 v21, v34, 0xba000000, v21
	v_fmac_f32_e32 v26, 0xba000000, v34
	v_mul_f32_e32 v2, v20, v20
	v_pk_add_f32 v[22:23], v[32:33], v[24:25]
	v_fmamk_f32 v27, v34, 0xba000000, v27
	v_pk_fma_f32 v[24:25], v[20:21], v[20:21], v[2:3] op_sel_hi:[1,1,0]
	v_mul_f32_e32 v2, v26, v26
	v_pk_add_f32 v[22:23], v[22:23], v[22:23] op_sel_hi:[0,1]
	v_pk_fma_f32 v[32:33], v[26:27], v[26:27], v[2:3] op_sel_hi:[1,1,0]
	v_fmamk_f32 v17, v34, 0xba000000, v17
	v_fmac_f32_e32 v16, 0xba000000, v34
	v_fmamk_f32 v19, v34, 0xba000000, v19
	v_fmac_f32_e32 v18, 0xba000000, v34
	v_mul_f32_e32 v24, v18, v18
	v_mul_f32_e32 v32, v19, v19
	v_mul_f32_e32 v22, v16, v16
	v_mul_f32_e32 v2, v17, v17
	v_pk_add_f32 v[24:25], v[24:25], v[32:33]
	v_pk_add_f32 v[2:3], v[22:23], v[2:3]
	v_fmamk_f32 v13, v34, 0xba000000, v13
	v_pk_add_f32 v[2:3], v[24:25], v[2:3]
	v_fmac_f32_e32 v12, 0xba000000, v34
	v_fmamk_f32 v15, v34, 0xba000000, v15
	v_fmac_f32_e32 v14, 0xba000000, v34
	v_pk_add_f32 v[2:3], v[2:3], v[2:3] op_sel_hi:[0,1]
	v_pk_mul_f32 v[22:23], v[14:15], v[14:15]
	v_pk_mul_f32 v[24:25], v[12:13], v[12:13]
	v_fmac_f32_e32 v10, 0xba000000, v34
	v_pk_mov_b32 v[32:33], v[24:25], v[22:23] op_sel:[1,0]
	v_mov_b32_e32 v25, v23
	v_fmamk_f32 v11, v34, 0xba000000, v11
	v_fmac_f32_e32 v8, 0xba000000, v34
	v_mul_f32_e32 v2, v10, v10
	v_pk_add_f32 v[22:23], v[32:33], v[24:25]
	v_fmamk_f32 v9, v34, 0xba000000, v9
	v_pk_fma_f32 v[24:25], v[10:11], v[10:11], v[2:3] op_sel_hi:[1,1,0]
	v_mul_f32_e32 v2, v8, v8
	v_pk_add_f32 v[22:23], v[22:23], v[22:23] op_sel_hi:[0,1]
	v_pk_fma_f32 v[32:33], v[8:9], v[8:9], v[2:3] op_sel_hi:[1,1,0]
	v_fmamk_f32 v5, v34, 0xba000000, v5
	v_fmac_f32_e32 v4, 0xba000000, v34
	v_fmamk_f32 v7, v34, 0xba000000, v7
	v_fmac_f32_e32 v6, 0xba000000, v34
	v_mul_f32_e32 v24, v6, v6
	v_mul_f32_e32 v32, v7, v7
	v_mul_f32_e32 v22, v4, v4
	v_mul_f32_e32 v2, v5, v5
	v_pk_add_f32 v[24:25], v[24:25], v[32:33]
	v_pk_add_f32 v[2:3], v[22:23], v[2:3]
	s_nop 0
	v_pk_add_f32 v[2:3], v[24:25], v[2:3]
	s_nop 0
	v_add_f32_e32 v2, v2, v3
	s_waitcnt lgkmcnt(0)
	s_nop 1
	v_add_f32_dpp v2, v2, v2 quad_perm:[1,0,3,2] row_mask:0xf bank_mask:0xf
	s_nop 1
	v_add_f32_dpp v2, v2, v2 quad_perm:[2,3,0,1] row_mask:0xf bank_mask:0xf
	s_nop 1
	v_add_f32_dpp v2, v2, v2 row_half_mirror row_mask:0xf bank_mask:0xf
	s_nop 1
	v_add_f32_dpp v2, v2, v2 row_ror:8 row_mask:0xf bank_mask:0xf
	s_nop 0
	v_readlane_b32 s100, v2, 0
	v_readlane_b32 s101, v2, 16
	s_nop 0
	v_mov_b32_e32 v3, s100
	v_add_f32_e32 v3, s101, v3
	v_readlane_b32 s100, v2, 32
	v_readlane_b32 s101, v2, 48
	s_nop 0
	v_add_f32_e32 v3, s100, v3
	v_add_f32_e32 v2, s101, v3
	v_fmamk_f32 v2, v2, 0x3a000000, v229
	v_cmp_gt_f32_e32 vcc, s5, v2
	v_mul_f32_e32 v3, 0x4f800000, v2
	s_nop 0
	v_cndmask_b32_e32 v2, v2, v3, vcc
	v_sqrt_f32_e32 v3, v2
	s_nop 0
	v_add_u32_e32 v22, -1, v3
	v_fma_f32 v23, -v22, v3, v2
	v_cmp_ge_f32_e64 s[14:15], 0, v23
	v_add_u32_e32 v23, 1, v3
	s_nop 0
	v_cndmask_b32_e64 v22, v3, v22, s[14:15]
	v_fma_f32 v3, -v23, v3, v2
	v_cmp_lt_f32_e64 s[14:15], 0, v3
	s_nop 1
	v_cndmask_b32_e64 v3, v22, v23, s[14:15]
	v_mul_f32_e32 v22, 0x37800000, v3
	v_cndmask_b32_e32 v3, v3, v22, vcc
	v_cmp_class_f32_e32 vcc, v2, v230
	s_nop 1
	v_cndmask_b32_e32 v2, v3, v2, vcc
	v_div_scale_f32 v3, s[14:15], v2, v2, 1.0
	v_rcp_f32_e32 v22, v3
	s_nop 0
	v_fma_f32 v23, -v3, v22, 1.0
	v_fmac_f32_e32 v22, v23, v22
	v_div_scale_f32 v23, vcc, 1.0, v2, 1.0
	v_mul_f32_e32 v24, v23, v22
	v_fma_f32 v25, -v3, v24, v23
	v_fmac_f32_e32 v24, v25, v22
	v_fma_f32 v3, -v3, v24, v23
	v_div_fmas_f32 v3, v3, v22, v24
	ds_read_b128 v[22:25], v88 offset:24576
	ds_read_b128 v[32:35], v88 offset:32768
	v_div_fixup_f32 v36, v3, v2, 1.0
	v_pk_mul_f32 v[2:3], v[58:59], v[36:37] op_sel_hi:[1,0]
	v_pk_mul_f32 v[38:39], v[60:61], v[36:37] op_sel_hi:[1,0]
	v_pk_mul_f32 v[28:29], v[28:29], v[36:37] op_sel_hi:[1,0]
	s_waitcnt lgkmcnt(0)
	v_pk_add_f32 v[32:33], v[32:33], 1.0 op_sel_hi:[1,0]
	v_pk_add_f32 v[34:35], v[34:35], 1.0 op_sel_hi:[1,0]
	v_pk_fma_f32 v[2:3], v[32:33], v[2:3], v[22:23]
	v_pk_fma_f32 v[24:25], v[34:35], v[38:39], v[24:25]
	v_bfe_u32 v22, v2, 16, 1
	v_add3_u32 v2, v2, v22, s69
	v_bfe_u32 v22, v3, 16, 1
	v_lshrrev_b32_e32 v2, 16, v2
	v_add3_u32 v3, v3, v22, s69
	v_and_or_b32 v2, v3, s4, v2
	v_bfe_u32 v3, v24, 16, 1
	v_add3_u32 v3, v24, v3, s69
	v_bfe_u32 v22, v25, 16, 1
	v_lshrrev_b32_e32 v3, 16, v3
	v_add3_u32 v22, v25, v22, s69
	v_add_co_u32_e32 v32, vcc, s6, v0
	v_and_or_b32 v3, v22, s4, v3
	s_nop 0
	v_addc_co_u32_e32 v33, vcc, 0, v1, vcc
	global_store_dwordx2 v[32:33], v[2:3], off
	ds_read_b128 v[0:3], v88 offset:25600
	ds_read_b128 v[22:25], v88 offset:33792
	v_pk_mul_f32 v[34:35], v[42:43], v[36:37] op_sel_hi:[1,0]
	v_pk_mul_f32 v[38:39], v[40:41], v[36:37] op_sel_hi:[1,0]
	v_pk_mul_f32 v[30:31], v[30:31], v[36:37] op_sel_hi:[1,0]
	v_pk_mul_f32 v[20:21], v[20:21], v[36:37] op_sel_hi:[1,0]
	s_waitcnt lgkmcnt(0)
	v_pk_add_f32 v[22:23], v[22:23], 1.0 op_sel_hi:[1,0]
	v_pk_add_f32 v[24:25], v[24:25], 1.0 op_sel_hi:[1,0]
	v_pk_fma_f32 v[0:1], v[22:23], v[34:35], v[0:1]
	v_pk_fma_f32 v[2:3], v[24:25], v[38:39], v[2:3]
	v_bfe_u32 v22, v0, 16, 1
	v_add3_u32 v0, v0, v22, s69
	v_bfe_u32 v22, v1, 16, 1
	v_lshrrev_b32_e32 v0, 16, v0
	v_add3_u32 v1, v1, v22, s69
	v_and_or_b32 v0, v1, s4, v0
	v_bfe_u32 v1, v2, 16, 1
	v_add3_u32 v1, v2, v1, s69
	v_bfe_u32 v2, v3, 16, 1
	v_lshrrev_b32_e32 v1, 16, v1
	v_add3_u32 v2, v3, v2, s69
	v_and_or_b32 v1, v2, s4, v1
	global_store_dwordx2 v[32:33], v[0:1], off offset:512
	ds_read_b128 v[0:3], v88 offset:26624
	ds_read_b128 v[22:25], v88 offset:34816
	v_pk_mul_f32 v[26:27], v[26:27], v[36:37] op_sel_hi:[1,0]
	v_pk_mul_f32 v[18:19], v[18:19], v[36:37] op_sel_hi:[1,0]
	v_pk_mul_f32 v[16:17], v[16:17], v[36:37] op_sel_hi:[1,0]
	v_pk_mul_f32 v[12:13], v[12:13], v[36:37] op_sel_hi:[1,0]
	s_waitcnt lgkmcnt(0)
	v_pk_add_f32 v[22:23], v[22:23], 1.0 op_sel_hi:[1,0]
	v_pk_add_f32 v[24:25], v[24:25], 1.0 op_sel_hi:[1,0]
	v_pk_fma_f32 v[0:1], v[22:23], v[28:29], v[0:1]
	v_pk_fma_f32 v[2:3], v[24:25], v[30:31], v[2:3]
	v_bfe_u32 v22, v0, 16, 1
	v_add3_u32 v0, v0, v22, s69
	v_bfe_u32 v22, v1, 16, 1
	v_lshrrev_b32_e32 v0, 16, v0
	v_add3_u32 v1, v1, v22, s69
	v_and_or_b32 v0, v1, s4, v0
	v_bfe_u32 v1, v2, 16, 1
	v_add3_u32 v1, v2, v1, s69
	v_bfe_u32 v2, v3, 16, 1
	v_lshrrev_b32_e32 v1, 16, v1
	v_add3_u32 v2, v3, v2, s69
	v_and_or_b32 v1, v2, s4, v1
	global_store_dwordx2 v[32:33], v[0:1], off offset:1024
	ds_read_b128 v[0:3], v88 offset:27648
	ds_read_b128 v[22:25], v88 offset:35840
	v_pk_mul_f32 v[14:15], v[14:15], v[36:37] op_sel_hi:[1,0]
	v_pk_mul_f32 v[10:11], v[10:11], v[36:37] op_sel_hi:[1,0]
	v_pk_mul_f32 v[8:9], v[8:9], v[36:37] op_sel_hi:[1,0]
	v_pk_mul_f32 v[6:7], v[6:7], v[36:37] op_sel_hi:[1,0]
	s_waitcnt lgkmcnt(0)
	v_pk_add_f32 v[22:23], v[22:23], 1.0 op_sel_hi:[1,0]
	v_pk_add_f32 v[24:25], v[24:25], 1.0 op_sel_hi:[1,0]
	v_pk_fma_f32 v[0:1], v[22:23], v[20:21], v[0:1]
	v_pk_fma_f32 v[2:3], v[24:25], v[26:27], v[2:3]
	v_bfe_u32 v20, v0, 16, 1
	v_add3_u32 v0, v0, v20, s69
	v_bfe_u32 v20, v1, 16, 1
	v_lshrrev_b32_e32 v0, 16, v0
	v_add3_u32 v1, v1, v20, s69
	v_and_or_b32 v0, v1, s4, v0
	v_bfe_u32 v1, v2, 16, 1
	v_add3_u32 v1, v2, v1, s69
	v_bfe_u32 v2, v3, 16, 1
	v_lshrrev_b32_e32 v1, 16, v1
	v_add3_u32 v2, v3, v2, s69
	v_and_or_b32 v1, v2, s4, v1
	global_store_dwordx2 v[32:33], v[0:1], off offset:1536
	ds_read_b128 v[0:3], v88 offset:28672
	ds_read_b128 v[20:23], v88 offset:36864
	v_pk_mul_f32 v[4:5], v[4:5], v[36:37] op_sel_hi:[1,0]
	s_waitcnt lgkmcnt(0)
	v_pk_add_f32 v[20:21], v[20:21], 1.0 op_sel_hi:[1,0]
	v_pk_add_f32 v[22:23], v[22:23], 1.0 op_sel_hi:[1,0]
	v_pk_fma_f32 v[0:1], v[20:21], v[18:19], v[0:1]
	v_pk_fma_f32 v[2:3], v[22:23], v[16:17], v[2:3]
	v_bfe_u32 v16, v0, 16, 1
	v_add3_u32 v0, v0, v16, s69
	v_bfe_u32 v16, v1, 16, 1
	v_lshrrev_b32_e32 v0, 16, v0
	v_add3_u32 v1, v1, v16, s69
	v_and_or_b32 v0, v1, s4, v0
	v_bfe_u32 v1, v2, 16, 1
	v_add3_u32 v1, v2, v1, s69
	v_bfe_u32 v2, v3, 16, 1
	v_lshrrev_b32_e32 v1, 16, v1
	v_add3_u32 v2, v3, v2, s69
	v_and_or_b32 v1, v2, s4, v1
	global_store_dwordx2 v[32:33], v[0:1], off offset:2048
	ds_read_b128 v[0:3], v88 offset:29696
	ds_read_b128 v[16:19], v88 offset:37888
	s_waitcnt lgkmcnt(0)
	v_pk_add_f32 v[16:17], v[16:17], 1.0 op_sel_hi:[1,0]
	s_nop 0
	v_pk_fma_f32 v[0:1], v[16:17], v[12:13], v[0:1]
	v_pk_add_f32 v[18:19], v[18:19], 1.0 op_sel_hi:[1,0]
	v_bfe_u32 v12, v0, 16, 1
	v_add3_u32 v0, v0, v12, s69
	v_bfe_u32 v12, v1, 16, 1
	v_pk_fma_f32 v[2:3], v[18:19], v[14:15], v[2:3]
	v_lshrrev_b32_e32 v0, 16, v0
	v_add3_u32 v1, v1, v12, s69
	v_and_or_b32 v0, v1, s4, v0
	v_bfe_u32 v1, v2, 16, 1
	v_add3_u32 v1, v2, v1, s69
	v_bfe_u32 v2, v3, 16, 1
	v_lshrrev_b32_e32 v1, 16, v1
	v_add3_u32 v2, v3, v2, s69
	v_and_or_b32 v1, v2, s4, v1
	global_store_dwordx2 v[32:33], v[0:1], off offset:2560
	ds_read_b128 v[0:3], v88 offset:30720
	ds_read_b128 v[12:15], v88 offset:38912
	s_waitcnt lgkmcnt(0)
	v_pk_add_f32 v[12:13], v[12:13], 1.0 op_sel_hi:[1,0]
	v_pk_add_f32 v[14:15], v[14:15], 1.0 op_sel_hi:[1,0]
	v_pk_fma_f32 v[0:1], v[12:13], v[10:11], v[0:1]
	v_pk_fma_f32 v[2:3], v[14:15], v[8:9], v[2:3]
	v_bfe_u32 v8, v0, 16, 1
	v_add3_u32 v0, v0, v8, s69
	v_bfe_u32 v8, v1, 16, 1
	v_lshrrev_b32_e32 v0, 16, v0
	v_add3_u32 v1, v1, v8, s69
	v_and_or_b32 v0, v1, s4, v0
	v_bfe_u32 v1, v2, 16, 1
	v_add3_u32 v1, v2, v1, s69
	v_bfe_u32 v2, v3, 16, 1
	v_lshrrev_b32_e32 v1, 16, v1
	v_add3_u32 v2, v3, v2, s69
	v_and_or_b32 v1, v2, s4, v1
	global_store_dwordx2 v[32:33], v[0:1], off offset:3072
	ds_read_b128 v[0:3], v88 offset:31744
	ds_read_b128 v[8:11], v88 offset:39936
	s_waitcnt lgkmcnt(0)
	v_pk_add_f32 v[8:9], v[8:9], 1.0 op_sel_hi:[1,0]
	v_pk_add_f32 v[10:11], v[10:11], 1.0 op_sel_hi:[1,0]
	v_pk_fma_f32 v[0:1], v[8:9], v[6:7], v[0:1]
	v_pk_fma_f32 v[2:3], v[10:11], v[4:5], v[2:3]
	v_bfe_u32 v4, v0, 16, 1
	v_add3_u32 v0, v0, v4, s69
	v_bfe_u32 v4, v1, 16, 1
	v_lshrrev_b32_e32 v0, 16, v0
	v_add3_u32 v1, v1, v4, s69
	v_and_or_b32 v0, v1, s4, v0
	v_bfe_u32 v1, v2, 16, 1
	v_add3_u32 v1, v2, v1, s69
	v_bfe_u32 v2, v3, 16, 1
	v_lshrrev_b32_e32 v1, 16, v1
	v_add3_u32 v2, v3, v2, s69
	v_and_or_b32 v1, v2, s4, v1
	global_store_dwordx2 v[32:33], v[0:1], off offset:3584
	s_cbranch_scc1 .LBB0_926

.LBB0_1228:
	s_waitcnt vmcnt(15)
	v_cvt_f32_f16_sdwa v177, v170 dst_sel:DWORD dst_unused:UNUSED_PAD src0_sel:WORD_1
	v_cvt_f32_f16_e32 v176, v170
	s_waitcnt vmcnt(14)
	v_lshlrev_b32_e32 v174, 16, v172
	v_and_b32_e32 v175, 0xffff0000, v172
	v_lshlrev_b32_e32 v172, 16, v173
	v_and_b32_e32 v173, 0xffff0000, v173
	v_cvt_f32_f16_sdwa v179, v171 dst_sel:DWORD dst_unused:UNUSED_PAD src0_sel:WORD_1
	v_cvt_f32_f16_e32 v178, v171
	s_waitcnt lgkmcnt(7)
	v_pk_mul_f32 v[170:171], v[124:125], v[174:175]
	v_pk_mul_f32 v[124:125], v[126:127], v[172:173]
	s_waitcnt vmcnt(10)
	v_cvt_f32_f16_sdwa v173, v168 dst_sel:DWORD dst_unused:UNUSED_PAD src0_sel:WORD_1
	v_cvt_f32_f16_sdwa v175, v169 dst_sel:DWORD dst_unused:UNUSED_PAD src0_sel:WORD_1
	v_cvt_f32_f16_e32 v174, v169
	v_cvt_f32_f16_e32 v172, v168
	s_mov_b32 s4, 0x3fb504f3
	v_pk_fma_f32 v[126:127], v[176:177], s[4:5], v[170:171] op_sel_hi:[1,0,1]
	v_lshlrev_b32_e32 v170, 16, v166
	v_and_b32_e32 v171, 0xffff0000, v166
	v_lshlrev_b32_e32 v166, 16, v167
	v_and_b32_e32 v167, 0xffff0000, v167
	s_waitcnt lgkmcnt(6)
	v_pk_mul_f32 v[120:121], v[120:121], v[170:171]
	v_pk_mul_f32 v[122:123], v[122:123], v[166:167]
	v_pk_fma_f32 v[168:169], v[172:173], s[4:5], v[120:121] op_sel_hi:[1,0,1]
	v_pk_fma_f32 v[166:167], v[174:175], s[4:5], v[122:123] op_sel_hi:[1,0,1]
	v_lshlrev_b32_e32 v120, 16, v162
	v_and_b32_e32 v121, 0xffff0000, v162
	v_lshlrev_b32_e32 v122, 16, v163
	v_and_b32_e32 v123, 0xffff0000, v163
	s_waitcnt vmcnt(9)
	v_cvt_f32_f16_sdwa v163, v164 dst_sel:DWORD dst_unused:UNUSED_PAD src0_sel:WORD_1
	v_cvt_f32_f16_sdwa v171, v165 dst_sel:DWORD dst_unused:UNUSED_PAD src0_sel:WORD_1
	v_cvt_f32_f16_e32 v170, v165
	v_cvt_f32_f16_e32 v162, v164
	s_waitcnt lgkmcnt(5)
	v_pk_mul_f32 v[116:117], v[116:117], v[120:121]
	v_pk_mul_f32 v[118:119], v[118:119], v[122:123]
	v_pk_fma_f32 v[124:125], v[178:179], s[4:5], v[124:125] op_sel_hi:[1,0,1]
	v_pk_fma_f32 v[120:121], v[170:171], s[4:5], v[118:119] op_sel_hi:[1,0,1]
	v_pk_fma_f32 v[122:123], v[162:163], s[4:5], v[116:117] op_sel_hi:[1,0,1]
	v_lshlrev_b32_e32 v116, 16, v160
	v_and_b32_e32 v117, 0xffff0000, v160
	v_lshlrev_b32_e32 v118, 16, v161
	v_and_b32_e32 v119, 0xffff0000, v161
	s_waitcnt vmcnt(8)
	v_cvt_f32_f16_sdwa v161, v158 dst_sel:DWORD dst_unused:UNUSED_PAD src0_sel:WORD_1
	v_cvt_f32_f16_e32 v160, v158
	v_cvt_f32_f16_sdwa v163, v159 dst_sel:DWORD dst_unused:UNUSED_PAD src0_sel:WORD_1
	v_cvt_f32_f16_e32 v162, v159
	s_waitcnt lgkmcnt(4)
	v_pk_mul_f32 v[112:113], v[112:113], v[116:117]
	s_waitcnt vmcnt(7)
	v_cvt_f32_f16_sdwa v117, v154 dst_sel:DWORD dst_unused:UNUSED_PAD src0_sel:WORD_1
	v_cvt_f32_f16_e32 v116, v154
	v_pk_mul_f32 v[114:115], v[114:115], v[118:119]
	v_cvt_f32_f16_sdwa v119, v155 dst_sel:DWORD dst_unused:UNUSED_PAD src0_sel:WORD_1
	v_cvt_f32_f16_e32 v118, v155
	v_pk_fma_f32 v[160:161], v[160:161], s[4:5], v[112:113] op_sel_hi:[1,0,1]
	s_waitcnt vmcnt(6)
	v_lshlrev_b32_e32 v112, 16, v156
	v_and_b32_e32 v113, 0xffff0000, v156
	v_pk_fma_f32 v[158:159], v[162:163], s[4:5], v[114:115] op_sel_hi:[1,0,1]
	v_lshlrev_b32_e32 v114, 16, v157
	v_and_b32_e32 v115, 0xffff0000, v157
	s_waitcnt lgkmcnt(3)
	v_pk_mul_f32 v[108:109], v[108:109], v[112:113]
	v_pk_mul_f32 v[110:111], v[110:111], v[114:115]
	v_pk_fma_f32 v[114:115], v[116:117], s[4:5], v[108:109] op_sel_hi:[1,0,1]
	s_waitcnt vmcnt(2)
	v_cvt_f32_f16_sdwa v117, v152 dst_sel:DWORD dst_unused:UNUSED_PAD src0_sel:WORD_1
	v_cvt_f32_f16_e32 v116, v152
	v_pk_fma_f32 v[112:113], v[118:119], s[4:5], v[110:111] op_sel_hi:[1,0,1]
	v_lshlrev_b32_e32 v108, 16, v150
	v_and_b32_e32 v109, 0xffff0000, v150
	v_cvt_f32_f16_sdwa v119, v153 dst_sel:DWORD dst_unused:UNUSED_PAD src0_sel:WORD_1
	v_cvt_f32_f16_e32 v118, v153
	s_waitcnt lgkmcnt(2)
	v_pk_mul_f32 v[104:105], v[104:105], v[108:109]
	s_waitcnt vmcnt(1)
	v_cvt_f32_f16_sdwa v109, v148 dst_sel:DWORD dst_unused:UNUSED_PAD src0_sel:WORD_1
	v_cvt_f32_f16_e32 v108, v148
	v_lshlrev_b32_e32 v110, 16, v151
	v_and_b32_e32 v111, 0xffff0000, v151
	v_pk_mul_f32 v[106:107], v[106:107], v[110:111]
	v_pk_fma_f32 v[152:153], v[116:117], s[4:5], v[104:105] op_sel_hi:[1,0,1]
	v_lshlrev_b32_e32 v104, 16, v146
	v_and_b32_e32 v105, 0xffff0000, v146
	v_pk_fma_f32 v[150:151], v[118:119], s[4:5], v[106:107] op_sel_hi:[1,0,1]
	v_lshlrev_b32_e32 v106, 16, v147
	v_and_b32_e32 v107, 0xffff0000, v147
	v_cvt_f32_f16_sdwa v111, v149 dst_sel:DWORD dst_unused:UNUSED_PAD src0_sel:WORD_1
	v_cvt_f32_f16_e32 v110, v149
	s_waitcnt lgkmcnt(1)
	v_pk_mul_f32 v[100:101], v[100:101], v[104:105]
	v_pk_mul_f32 v[102:103], v[102:103], v[106:107]
	v_pk_fma_f32 v[106:107], v[108:109], s[4:5], v[100:101] op_sel_hi:[1,0,1]
	s_waitcnt vmcnt(0)
	v_cvt_f32_f16_sdwa v109, v140 dst_sel:DWORD dst_unused:UNUSED_PAD src0_sel:WORD_1
	v_cvt_f32_f16_e32 v108, v140
	v_lshlrev_b32_e32 v100, 16, v142
	v_and_b32_e32 v101, 0xffff0000, v142
	v_pk_fma_f32 v[104:105], v[110:111], s[4:5], v[102:103] op_sel_hi:[1,0,1]
	v_lshlrev_b32_e32 v102, 16, v143
	v_and_b32_e32 v103, 0xffff0000, v143
	s_waitcnt lgkmcnt(0)
	v_pk_mul_f32 v[100:101], v[96:97], v[100:101]
	v_pk_mul_f32 v[96:97], v[98:99], v[102:103]
	v_pk_fma_f32 v[98:99], v[108:109], s[4:5], v[100:101] op_sel_hi:[1,0,1]
	v_mov_b32_e32 v100, v126
	v_mov_b32_e32 v101, v168
	v_mov_b32_e32 v102, v127
	v_mov_b32_e32 v103, v169
	v_pk_add_f32 v[100:101], v[100:101], v[102:103]
	v_mov_b32_e32 v102, v124
	v_mov_b32_e32 v103, v166
	v_mov_b32_e32 v108, v125
	v_mov_b32_e32 v109, v167
	v_cvt_f32_f16_sdwa v111, v141 dst_sel:DWORD dst_unused:UNUSED_PAD src0_sel:WORD_1
	v_cvt_f32_f16_e32 v110, v141
	v_pk_add_f32 v[102:103], v[102:103], v[108:109]
	v_mov_b32_e32 v108, v122
	v_pk_add_f32 v[100:101], v[100:101], v[102:103]
	v_pk_mov_b32 v[102:103], v[122:123], v[120:121] op_sel:[1,0]
	v_mov_b32_e32 v109, v121
	v_pk_add_f32 v[102:103], v[102:103], v[108:109]
	v_add_f32_e32 v100, 0, v100
	v_pk_add_f32 v[102:103], v[102:103], v[102:103] op_sel:[0,1] op_sel_hi:[1,0]
	v_pk_fma_f32 v[96:97], v[110:111], s[4:5], v[96:97] op_sel_hi:[1,0,1]
	v_add_f32_e32 v100, v100, v101
	v_add_f32_e32 v108, v160, v161
	v_add_f32_e32 v110, v158, v159
	v_mov_b32_e32 v101, v114
	v_mov_b32_e32 v103, v115
	v_mov_b32_e32 v109, v112
	v_mov_b32_e32 v111, v113
	v_pk_add_f32 v[100:101], v[100:101], v[102:103]
	v_pk_add_f32 v[102:103], v[108:109], v[110:111]
	v_mov_b32_e32 v108, v152
	v_pk_add_f32 v[100:101], v[100:101], v[102:103]
	v_pk_mov_b32 v[102:103], v[152:153], v[150:151] op_sel:[1,0]
	v_mov_b32_e32 v109, v151
	v_pk_add_f32 v[102:103], v[102:103], v[108:109]
	v_pk_add_f32 v[100:101], v[100:101], v[100:101] op_sel:[0,1] op_sel_hi:[1,0]
	v_pk_add_f32 v[102:103], v[102:103], v[102:103] op_sel:[0,1] op_sel_hi:[1,0]
	v_add_f32_e32 v108, v106, v107
	v_add_f32_e32 v110, v104, v105
	v_mov_b32_e32 v101, v98
	v_mov_b32_e32 v103, v99
	v_mov_b32_e32 v109, v96
	v_mov_b32_e32 v111, v97
	v_pk_add_f32 v[100:101], v[100:101], v[102:103]
	v_pk_add_f32 v[102:103], v[108:109], v[110:111]
	s_mov_b32 s4, 0xf800000
	v_pk_add_f32 v[100:101], v[100:101], v[102:103]
	s_nop 0
	v_add_f32_e32 v100, v100, v101
	s_waitcnt lgkmcnt(0)
	s_nop 1
	v_add_f32_dpp v100, v100, v100 quad_perm:[1,0,3,2] row_mask:0xf bank_mask:0xf
	s_nop 1
	v_add_f32_dpp v100, v100, v100 quad_perm:[2,3,0,1] row_mask:0xf bank_mask:0xf
	s_nop 1
	v_add_f32_dpp v100, v100, v100 row_half_mirror row_mask:0xf bank_mask:0xf
	s_nop 1
	v_add_f32_dpp v100, v100, v100 row_ror:8 row_mask:0xf bank_mask:0xf
	s_nop 0
	v_readlane_b32 s100, v100, 0
	v_readlane_b32 s101, v100, 16
	s_nop 0
	v_mov_b32_e32 v101, s100
	v_add_f32_e32 v101, s101, v101
	v_readlane_b32 s100, v100, 32
	v_readlane_b32 s101, v100, 48
	s_nop 0
	v_add_f32_e32 v101, s100, v101
	v_add_f32_e32 v140, s101, v101
	v_fmamk_f32 v127, v140, 0xba000000, v127
	v_fmamk_f32 v125, v140, 0xba000000, v125
	v_fmac_f32_e32 v126, 0xba000000, v140
	v_fmamk_f32 v103, v140, 0xba000000, v169
	v_fmac_f32_e32 v168, 0xba000000, v140
	v_mov_b32_e32 v102, v127
	v_fmac_f32_e32 v124, 0xba000000, v140
	v_fmamk_f32 v101, v140, 0xba000000, v167
	v_fmac_f32_e32 v166, 0xba000000, v140
	v_mov_b32_e32 v108, v126
	v_mov_b32_e32 v109, v168
	v_pk_mul_f32 v[110:111], v[102:103], v[102:103]
	v_mov_b32_e32 v100, v125
	v_pk_fma_f32 v[108:109], v[108:109], v[108:109], v[110:111]
	v_mov_b32_e32 v110, v124
	v_mov_b32_e32 v111, v166
	v_pk_mul_f32 v[116:117], v[100:101], v[100:101]
	v_fmamk_f32 v121, v140, 0xba000000, v121
	v_pk_fma_f32 v[110:111], v[110:111], v[110:111], v[116:117]
	v_fmac_f32_e32 v120, 0xba000000, v140
	v_fmamk_f32 v123, v140, 0xba000000, v123
	v_fmac_f32_e32 v122, 0xba000000, v140
	v_pk_add_f32 v[108:109], v[108:109], v[110:111]
	v_pk_mul_f32 v[110:111], v[120:121], v[120:121]
	v_pk_mul_f32 v[116:117], v[122:123], v[122:123]
	v_fmac_f32_e32 v160, 0xba000000, v140
	v_pk_mov_b32 v[118:119], v[116:117], v[110:111] op_sel:[1,0]
	v_mov_b32_e32 v117, v111
	v_fmac_f32_e32 v158, 0xba000000, v140
	v_fmamk_f32 v161, v140, 0xba000000, v161
	v_mul_f32_e32 v100, v160, v160
	v_pk_add_f32 v[110:111], v[118:119], v[116:117]
	v_fmamk_f32 v159, v140, 0xba000000, v159
	v_pk_fma_f32 v[116:117], v[160:161], v[160:161], v[100:101] op_sel_hi:[1,1,0]
	v_mul_f32_e32 v100, v158, v158
	v_pk_add_f32 v[108:109], v[108:109], v[108:109] op_sel_hi:[0,1]
	v_pk_add_f32 v[110:111], v[110:111], v[110:111] op_sel_hi:[0,1]
	v_pk_fma_f32 v[118:119], v[158:159], v[158:159], v[100:101] op_sel_hi:[1,1,0]
	v_fmamk_f32 v113, v140, 0xba000000, v113
	v_fmac_f32_e32 v112, 0xba000000, v140
	v_fmamk_f32 v115, v140, 0xba000000, v115
	v_fmac_f32_e32 v114, 0xba000000, v140
	v_mul_f32_e32 v116, v114, v114
	v_mul_f32_e32 v118, v115, v115
	v_mul_f32_e32 v110, v112, v112
	v_mul_f32_e32 v108, v113, v113
	v_pk_add_f32 v[116:117], v[116:117], v[118:119]
	v_pk_add_f32 v[108:109], v[110:111], v[108:109]
	v_fmamk_f32 v151, v140, 0xba000000, v151
	v_fmac_f32_e32 v150, 0xba000000, v140
	v_fmamk_f32 v153, v140, 0xba000000, v153
	v_fmac_f32_e32 v152, 0xba000000, v140
	v_pk_add_f32 v[108:109], v[116:117], v[108:109]
	v_pk_mul_f32 v[110:111], v[150:151], v[150:151]
	v_pk_mul_f32 v[116:117], v[152:153], v[152:153]
	v_fmac_f32_e32 v106, 0xba000000, v140
	v_pk_mov_b32 v[118:119], v[116:117], v[110:111] op_sel:[1,0]
	v_mov_b32_e32 v117, v111
	v_fmac_f32_e32 v104, 0xba000000, v140
	v_fmamk_f32 v107, v140, 0xba000000, v107
	v_mul_f32_e32 v100, v106, v106
	v_pk_add_f32 v[110:111], v[118:119], v[116:117]
	v_fmamk_f32 v105, v140, 0xba000000, v105
	v_pk_fma_f32 v[116:117], v[106:107], v[106:107], v[100:101] op_sel_hi:[1,1,0]
	v_mul_f32_e32 v100, v104, v104
	v_pk_add_f32 v[108:109], v[108:109], v[108:109] op_sel_hi:[0,1]
	v_pk_add_f32 v[110:111], v[110:111], v[110:111] op_sel_hi:[0,1]
	v_pk_fma_f32 v[118:119], v[104:105], v[104:105], v[100:101] op_sel_hi:[1,1,0]
	v_fmamk_f32 v97, v140, 0xba000000, v97
	v_fmac_f32_e32 v96, 0xba000000, v140
	v_fmamk_f32 v99, v140, 0xba000000, v99
	v_fmac_f32_e32 v98, 0xba000000, v140
	v_mul_f32_e32 v116, v98, v98
	v_mul_f32_e32 v118, v99, v99
	v_mul_f32_e32 v110, v96, v96
	v_mul_f32_e32 v108, v97, v97
	v_pk_add_f32 v[116:117], v[116:117], v[118:119]
	v_pk_add_f32 v[108:109], v[110:111], v[108:109]
	s_nop 0
	v_pk_add_f32 v[108:109], v[116:117], v[108:109]
	s_nop 0
	v_add_f32_e32 v100, v108, v109
	s_waitcnt lgkmcnt(0)
	s_nop 1
	v_add_f32_dpp v100, v100, v100 quad_perm:[1,0,3,2] row_mask:0xf bank_mask:0xf
	s_nop 1
	v_add_f32_dpp v100, v100, v100 quad_perm:[2,3,0,1] row_mask:0xf bank_mask:0xf
	s_nop 1
	v_add_f32_dpp v100, v100, v100 row_half_mirror row_mask:0xf bank_mask:0xf
	s_nop 1
	v_add_f32_dpp v100, v100, v100 row_ror:8 row_mask:0xf bank_mask:0xf
	s_nop 0
	v_readlane_b32 s100, v100, 0
	v_readlane_b32 s101, v100, 16
	s_nop 0
	v_mov_b32_e32 v102, s100
	v_add_f32_e32 v102, s101, v102
	v_readlane_b32 s100, v100, 32
	v_readlane_b32 s101, v100, 48
	s_nop 0
	v_add_f32_e32 v102, s100, v102
	v_add_f32_e32 v100, s101, v102
	v_fmamk_f32 v100, v100, 0x3a000000, v229
	v_mul_f32_e32 v102, 0x4f800000, v100
	v_cmp_gt_f32_e32 vcc, s4, v100
	s_nop 1
	v_cndmask_b32_e32 v100, v100, v102, vcc
	v_sqrt_f32_e32 v102, v100
	s_nop 0
	v_add_u32_e32 v108, -1, v102
	v_fma_f32 v109, -v108, v102, v100
	v_cmp_ge_f32_e64 s[8:9], 0, v109
	v_add_u32_e32 v109, 1, v102
	s_nop 0
	v_cndmask_b32_e64 v108, v102, v108, s[8:9]
	v_fma_f32 v102, -v109, v102, v100
	v_cmp_lt_f32_e64 s[8:9], 0, v102
	s_nop 1
	v_cndmask_b32_e64 v102, v108, v109, s[8:9]
	v_mul_f32_e32 v108, 0x37800000, v102
	v_cndmask_b32_e32 v102, v102, v108, vcc
	v_cmp_class_f32_e32 vcc, v100, v230
	s_nop 1
	v_cndmask_b32_e32 v100, v102, v100, vcc
	v_div_scale_f32 v102, s[8:9], v100, v100, 1.0
	v_rcp_f32_e32 v108, v102
	s_mov_b64 s[8:9], -1
	v_fma_f32 v109, -v102, v108, 1.0
	v_fmac_f32_e32 v108, v109, v108
	v_div_scale_f32 v109, vcc, 1.0, v100, 1.0
	v_mul_f32_e32 v110, v109, v108
	v_fma_f32 v111, -v102, v110, v109
	v_fmac_f32_e32 v110, v111, v108
	v_fma_f32 v102, -v102, v110, v109
	v_div_fmas_f32 v102, v102, v108, v110
	v_div_fixup_f32 v140, v102, v100, 1.0
	v_pk_mul_f32 v[108:109], v[126:127], v[140:141] op_sel_hi:[1,0]
	v_pk_mul_f32 v[110:111], v[124:125], v[140:141] op_sel_hi:[1,0]
	v_pk_fma_f32 v[124:125], v[0:1], v[108:109], v[8:9]
	v_pk_fma_f32 v[126:127], v[2:3], v[110:111], v[10:11]
	s_and_b64 vcc, exec, s[0:1]
	s_cbranch_vccz .LBB0_1230
	s_mov_b64 s[8:9], 0
	global_store_dwordx4 v[138:139], v[124:127], off offset:-4096

.LBB0_1260:
	v_readlane_b32 s4, v254, 45
	v_readlane_b32 s5, v254, 46
	s_and_b64 vcc, exec, s[4:5]
	s_cbranch_vccz .LBB0_1262
	v_mov_b32_e32 v140, v116
	v_mov_b32_e32 v141, v124
	v_mov_b32_e32 v142, v117
	v_mov_b32_e32 v143, v125
	v_pk_add_f32 v[140:141], v[140:141], v[142:143]
	v_mov_b32_e32 v142, v118
	v_mov_b32_e32 v143, v126
	v_mov_b32_e32 v146, v119
	v_mov_b32_e32 v147, v127
	v_pk_add_f32 v[142:143], v[142:143], v[146:147]
	v_mov_b32_e32 v146, v120
	v_pk_add_f32 v[140:141], v[140:141], v[142:143]
	v_mov_b32_e32 v142, v121
	v_mov_b32_e32 v143, v122
	v_mov_b32_e32 v147, v123
	v_pk_add_f32 v[142:143], v[142:143], v[146:147]
	v_add_f32_e32 v141, 0, v141
	v_pk_add_f32 v[142:143], v[142:143], v[142:143] op_sel_hi:[0,1]
	v_add_f32_e32 v141, v140, v141
	v_add_f32_e32 v147, v108, v109
	v_add_f32_e32 v149, v110, v111
	v_mov_b32_e32 v146, v112
	v_mov_b32_e32 v148, v113
	v_mov_b32_e32 v142, v114
	v_mov_b32_e32 v140, v115
	v_pk_add_f32 v[146:147], v[146:147], v[148:149]
	v_pk_add_f32 v[140:141], v[142:143], v[140:141]
	v_mov_b32_e32 v142, v101
	v_pk_add_f32 v[140:141], v[146:147], v[140:141]
	v_mov_b32_e32 v143, v102
	v_mov_b32_e32 v146, v100
	v_mov_b32_e32 v147, v103
	v_pk_add_f32 v[142:143], v[142:143], v[146:147]
	v_pk_add_f32 v[140:141], v[140:141], v[140:141] op_sel_hi:[0,1]
	v_pk_add_f32 v[142:143], v[142:143], v[142:143] op_sel_hi:[0,1]
	v_add_f32_e32 v147, v104, v105
	v_add_f32_e32 v149, v106, v107
	v_mov_b32_e32 v146, v96
	v_mov_b32_e32 v148, v97
	v_mov_b32_e32 v142, v98
	v_mov_b32_e32 v140, v99
	v_pk_add_f32 v[146:147], v[146:147], v[148:149]
	v_pk_add_f32 v[140:141], v[142:143], v[140:141]
	s_mov_b32 s4, 0xf800000
	v_pk_add_f32 v[140:141], v[146:147], v[140:141]
	s_nop 0
	v_add_f32_e32 v140, v140, v141
	s_waitcnt lgkmcnt(0)
	s_nop 1
	v_add_f32_dpp v140, v140, v140 quad_perm:[1,0,3,2] row_mask:0xf bank_mask:0xf
	s_nop 1
	v_add_f32_dpp v140, v140, v140 quad_perm:[2,3,0,1] row_mask:0xf bank_mask:0xf
	s_nop 1
	v_add_f32_dpp v140, v140, v140 row_half_mirror row_mask:0xf bank_mask:0xf
	s_nop 1
	v_add_f32_dpp v140, v140, v140 row_ror:8 row_mask:0xf bank_mask:0xf
	s_nop 0
	v_readlane_b32 s100, v140, 0
	v_readlane_b32 s101, v140, 16
	s_nop 0
	v_mov_b32_e32 v141, s100
	v_add_f32_e32 v141, s101, v141
	v_readlane_b32 s100, v140, 32
	v_readlane_b32 s101, v140, 48
	s_nop 0
	v_add_f32_e32 v141, s100, v141
	v_add_f32_e32 v150, s101, v141
	v_fmamk_f32 v125, v150, 0xba000000, v125
	v_fmamk_f32 v117, v150, 0xba000000, v117
	v_fmamk_f32 v127, v150, 0xba000000, v127
	v_fmac_f32_e32 v124, 0xba000000, v150
	v_fmamk_f32 v119, v150, 0xba000000, v119
	v_fmac_f32_e32 v116, 0xba000000, v150
	v_mov_b32_e32 v142, v125
	v_mov_b32_e32 v143, v117
	v_fmac_f32_e32 v126, 0xba000000, v150
	v_fmac_f32_e32 v118, 0xba000000, v150
	v_mov_b32_e32 v140, v124
	v_mov_b32_e32 v141, v116
	v_pk_mul_f32 v[142:143], v[142:143], v[142:143]
	v_mov_b32_e32 v146, v127
	v_mov_b32_e32 v147, v119
	v_pk_fma_f32 v[140:141], v[140:141], v[140:141], v[142:143]
	v_mov_b32_e32 v142, v126
	v_mov_b32_e32 v143, v118
	v_pk_mul_f32 v[146:147], v[146:147], v[146:147]
	v_fmamk_f32 v121, v150, 0xba000000, v121
	v_pk_fma_f32 v[142:143], v[142:143], v[142:143], v[146:147]
	v_fmac_f32_e32 v120, 0xba000000, v150
	v_pk_add_f32 v[140:141], v[140:141], v[142:143]
	v_fmamk_f32 v123, v150, 0xba000000, v123
	v_fmac_f32_e32 v122, 0xba000000, v150
	v_pk_add_f32 v[140:141], v[140:141], v[140:141] op_sel_hi:[0,1]
	v_pk_mul_f32 v[142:143], v[122:123], v[122:123]
	v_pk_mul_f32 v[146:147], v[120:121], v[120:121]
	v_fmac_f32_e32 v108, 0xba000000, v150
	v_pk_mov_b32 v[148:149], v[146:147], v[142:143] op_sel:[1,0]
	v_mov_b32_e32 v147, v143
	v_fmamk_f32 v109, v150, 0xba000000, v109
	v_fmac_f32_e32 v110, 0xba000000, v150
	v_mul_f32_e32 v140, v108, v108
	v_pk_add_f32 v[142:143], v[148:149], v[146:147]
	v_fmamk_f32 v111, v150, 0xba000000, v111
	v_pk_fma_f32 v[146:147], v[108:109], v[108:109], v[140:141] op_sel_hi:[1,1,0]
	v_mul_f32_e32 v140, v110, v110
	v_pk_add_f32 v[142:143], v[142:143], v[142:143] op_sel_hi:[0,1]
	v_pk_fma_f32 v[148:149], v[110:111], v[110:111], v[140:141] op_sel_hi:[1,1,0]
	v_fmamk_f32 v115, v150, 0xba000000, v115
	v_fmac_f32_e32 v114, 0xba000000, v150
	v_fmamk_f32 v113, v150, 0xba000000, v113
	v_fmac_f32_e32 v112, 0xba000000, v150
	v_mul_f32_e32 v146, v112, v112
	v_mul_f32_e32 v148, v113, v113
	v_mul_f32_e32 v142, v114, v114
	v_mul_f32_e32 v140, v115, v115
	v_pk_add_f32 v[146:147], v[146:147], v[148:149]
	v_pk_add_f32 v[140:141], v[142:143], v[140:141]
	v_fmamk_f32 v101, v150, 0xba000000, v101
	v_pk_add_f32 v[140:141], v[146:147], v[140:141]
	v_fmac_f32_e32 v100, 0xba000000, v150
	v_fmamk_f32 v103, v150, 0xba000000, v103
	v_fmac_f32_e32 v102, 0xba000000, v150
	v_pk_add_f32 v[140:141], v[140:141], v[140:141] op_sel_hi:[0,1]
	v_pk_mul_f32 v[142:143], v[102:103], v[102:103]
	v_pk_mul_f32 v[146:147], v[100:101], v[100:101]
	v_fmac_f32_e32 v104, 0xba000000, v150
	v_pk_mov_b32 v[148:149], v[146:147], v[142:143] op_sel:[1,0]
	v_mov_b32_e32 v147, v143
	v_fmamk_f32 v105, v150, 0xba000000, v105
	v_fmac_f32_e32 v106, 0xba000000, v150
	v_mul_f32_e32 v140, v104, v104
	v_pk_add_f32 v[142:143], v[148:149], v[146:147]
	v_fmamk_f32 v107, v150, 0xba000000, v107
	v_pk_fma_f32 v[146:147], v[104:105], v[104:105], v[140:141] op_sel_hi:[1,1,0]
	v_mul_f32_e32 v140, v106, v106
	v_pk_add_f32 v[142:143], v[142:143], v[142:143] op_sel_hi:[0,1]
	v_pk_fma_f32 v[148:149], v[106:107], v[106:107], v[140:141] op_sel_hi:[1,1,0]
	v_fmamk_f32 v99, v150, 0xba000000, v99
	v_fmac_f32_e32 v98, 0xba000000, v150
	v_fmamk_f32 v97, v150, 0xba000000, v97
	v_fmac_f32_e32 v96, 0xba000000, v150
	v_mul_f32_e32 v146, v96, v96
	v_mul_f32_e32 v148, v97, v97
	v_mul_f32_e32 v142, v98, v98
	v_mul_f32_e32 v140, v99, v99
	v_pk_add_f32 v[146:147], v[146:147], v[148:149]
	v_pk_add_f32 v[140:141], v[142:143], v[140:141]
	s_nop 0
	v_pk_add_f32 v[140:141], v[146:147], v[140:141]
	s_nop 0
	v_add_f32_e32 v140, v140, v141
	s_waitcnt lgkmcnt(0)
	s_nop 1
	v_add_f32_dpp v140, v140, v140 quad_perm:[1,0,3,2] row_mask:0xf bank_mask:0xf
	s_nop 1
	v_add_f32_dpp v140, v140, v140 quad_perm:[2,3,0,1] row_mask:0xf bank_mask:0xf
	s_nop 1
	v_add_f32_dpp v140, v140, v140 row_half_mirror row_mask:0xf bank_mask:0xf
	s_nop 1
	v_add_f32_dpp v140, v140, v140 row_ror:8 row_mask:0xf bank_mask:0xf
	s_nop 0
	v_readlane_b32 s100, v140, 0
	v_readlane_b32 s101, v140, 16
	s_nop 0
	v_mov_b32_e32 v141, s100
	v_add_f32_e32 v141, s101, v141
	v_readlane_b32 s100, v140, 32
	v_readlane_b32 s101, v140, 48
	s_nop 0
	v_add_f32_e32 v141, s100, v141
	v_add_f32_e32 v140, s101, v141
	v_fmamk_f32 v140, v140, 0x3a000000, v229
	v_cmp_gt_f32_e32 vcc, s4, v140
	v_mul_f32_e32 v141, 0x4f800000, v140
	s_mov_b32 s4, 0xffff0000
	v_cndmask_b32_e32 v140, v140, v141, vcc
	v_sqrt_f32_e32 v141, v140
	s_nop 0
	v_add_u32_e32 v142, -1, v141
	v_fma_f32 v143, -v142, v141, v140
	v_cmp_ge_f32_e64 s[8:9], 0, v143
	v_add_u32_e32 v143, 1, v141
	s_nop 0
	v_cndmask_b32_e64 v142, v141, v142, s[8:9]
	v_fma_f32 v141, -v143, v141, v140
	v_cmp_lt_f32_e64 s[8:9], 0, v141
	s_nop 1
	v_cndmask_b32_e64 v141, v142, v143, s[8:9]
	v_mul_f32_e32 v142, 0x37800000, v141
	v_cndmask_b32_e32 v141, v141, v142, vcc
	v_cmp_class_f32_e32 vcc, v140, v230
	s_nop 1
	v_cndmask_b32_e32 v140, v141, v140, vcc
	v_div_scale_f32 v141, s[8:9], v140, v140, 1.0
	v_rcp_f32_e32 v142, v141
	s_nop 0
	v_fma_f32 v143, -v141, v142, 1.0
	v_fmac_f32_e32 v142, v143, v142
	v_div_scale_f32 v143, vcc, 1.0, v140, 1.0
	v_mul_f32_e32 v146, v143, v142
	v_fma_f32 v147, -v141, v146, v143
	v_fmac_f32_e32 v146, v147, v142
	v_fma_f32 v141, -v141, v146, v143
	v_div_fmas_f32 v141, v141, v142, v146
	ds_read_b128 v[146:149], v191 offset:24576
	ds_read_b128 v[150:153], v191 offset:32768
	v_div_fixup_f32 v140, v141, v140, 1.0
	v_pk_mul_f32 v[124:125], v[124:125], v[140:141] op_sel_hi:[1,0]
	v_pk_mul_f32 v[126:127], v[126:127], v[140:141] op_sel_hi:[1,0]
	s_waitcnt lgkmcnt(0)
	v_pk_add_f32 v[150:151], v[150:151], 1.0 op_sel_hi:[1,0]
	s_nop 0
	v_pk_fma_f32 v[124:125], v[150:151], v[124:125], v[146:147]
	v_pk_add_f32 v[142:143], v[152:153], 1.0 op_sel_hi:[1,0]
	v_bfe_u32 v141, v124, 16, 1
	v_add3_u32 v124, v124, v141, s69
	v_bfe_u32 v141, v125, 16, 1
	v_pk_fma_f32 v[126:127], v[142:143], v[126:127], v[148:149]
	v_lshrrev_b32_e32 v124, 16, v124
	v_add3_u32 v125, v125, v141, s69
	v_and_or_b32 v124, v125, s4, v124
	v_bfe_u32 v125, v126, 16, 1
	v_add3_u32 v125, v126, v125, s69
	v_bfe_u32 v126, v127, 16, 1
	v_lshrrev_b32_e32 v125, 16, v125
	v_add3_u32 v126, v127, v126, s69
	v_and_or_b32 v125, v126, s4, v125
	global_store_dwordx2 v[136:137], v[124:125], off
	ds_read_b128 v[124:127], v191 offset:25600
	ds_read_b128 v[146:149], v191 offset:33792
	v_pk_mul_f32 v[116:117], v[116:117], v[140:141] op_sel_hi:[1,0]
	v_pk_mul_f32 v[118:119], v[118:119], v[140:141] op_sel_hi:[1,0]
	v_pk_mul_f32 v[120:121], v[120:121], v[140:141] op_sel_hi:[1,0]
	v_pk_mul_f32 v[122:123], v[122:123], v[140:141] op_sel_hi:[1,0]
	s_waitcnt lgkmcnt(0)
	v_pk_add_f32 v[146:147], v[146:147], 1.0 op_sel_hi:[1,0]
	v_pk_add_f32 v[142:143], v[148:149], 1.0 op_sel_hi:[1,0]
	v_pk_fma_f32 v[116:117], v[146:147], v[116:117], v[124:125]
	v_pk_fma_f32 v[118:119], v[142:143], v[118:119], v[126:127]
	v_bfe_u32 v124, v116, 16, 1
	v_add3_u32 v116, v116, v124, s69
	v_bfe_u32 v124, v117, 16, 1
	v_lshrrev_b32_e32 v116, 16, v116
	v_add3_u32 v117, v117, v124, s69
	v_and_or_b32 v116, v117, s4, v116
	v_bfe_u32 v117, v118, 16, 1
	v_add3_u32 v117, v118, v117, s69
	v_bfe_u32 v118, v119, 16, 1
	v_lshrrev_b32_e32 v117, 16, v117
	v_add3_u32 v118, v119, v118, s69
	v_and_or_b32 v117, v118, s4, v117
	global_store_dwordx2 v[136:137], v[116:117], off offset:512
	ds_read_b128 v[116:119], v191 offset:26624
	ds_read_b128 v[124:127], v191 offset:34816
	v_pk_mul_f32 v[108:109], v[108:109], v[140:141] op_sel_hi:[1,0]
	v_pk_mul_f32 v[110:111], v[110:111], v[140:141] op_sel_hi:[1,0]
	v_pk_mul_f32 v[112:113], v[112:113], v[140:141] op_sel_hi:[1,0]
	v_pk_mul_f32 v[114:115], v[114:115], v[140:141] op_sel_hi:[1,0]
	s_waitcnt lgkmcnt(0)
	v_pk_add_f32 v[124:125], v[124:125], 1.0 op_sel_hi:[1,0]
	v_pk_add_f32 v[126:127], v[126:127], 1.0 op_sel_hi:[1,0]
	v_pk_fma_f32 v[116:117], v[124:125], v[120:121], v[116:117]
	v_pk_fma_f32 v[118:119], v[126:127], v[122:123], v[118:119]
	v_bfe_u32 v120, v116, 16, 1
	v_add3_u32 v116, v116, v120, s69
	v_bfe_u32 v120, v117, 16, 1
	v_lshrrev_b32_e32 v116, 16, v116
	v_add3_u32 v117, v117, v120, s69
	v_and_or_b32 v116, v117, s4, v116
	v_bfe_u32 v117, v118, 16, 1
	v_add3_u32 v117, v118, v117, s69
	v_bfe_u32 v118, v119, 16, 1
	v_lshrrev_b32_e32 v117, 16, v117
	v_add3_u32 v118, v119, v118, s69
	v_and_or_b32 v117, v118, s4, v117
	global_store_dwordx2 v[136:137], v[116:117], off offset:1024
	ds_read_b128 v[116:119], v191 offset:27648
	ds_read_b128 v[120:123], v191 offset:35840
	v_pk_mul_f32 v[100:101], v[100:101], v[140:141] op_sel_hi:[1,0]
	v_pk_mul_f32 v[102:103], v[102:103], v[140:141] op_sel_hi:[1,0]
	v_pk_mul_f32 v[104:105], v[104:105], v[140:141] op_sel_hi:[1,0]
	v_pk_mul_f32 v[106:107], v[106:107], v[140:141] op_sel_hi:[1,0]
	s_waitcnt lgkmcnt(0)
	v_pk_add_f32 v[120:121], v[120:121], 1.0 op_sel_hi:[1,0]
	v_pk_add_f32 v[122:123], v[122:123], 1.0 op_sel_hi:[1,0]
	v_pk_fma_f32 v[108:109], v[120:121], v[108:109], v[116:117]
	v_pk_fma_f32 v[110:111], v[122:123], v[110:111], v[118:119]
	v_bfe_u32 v116, v108, 16, 1
	v_add3_u32 v108, v108, v116, s69
	v_bfe_u32 v116, v109, 16, 1
	v_lshrrev_b32_e32 v108, 16, v108
	v_add3_u32 v109, v109, v116, s69
	v_and_or_b32 v108, v109, s4, v108
	v_bfe_u32 v109, v110, 16, 1
	v_add3_u32 v109, v110, v109, s69
	v_bfe_u32 v110, v111, 16, 1
	v_lshrrev_b32_e32 v109, 16, v109
	v_add3_u32 v110, v111, v110, s69
	v_and_or_b32 v109, v110, s4, v109
	global_store_dwordx2 v[136:137], v[108:109], off offset:1536
	ds_read_b128 v[108:111], v191 offset:28672
	ds_read_b128 v[116:119], v191 offset:36864
	v_pk_mul_f32 v[96:97], v[96:97], v[140:141] op_sel_hi:[1,0]
	v_pk_mul_f32 v[98:99], v[98:99], v[140:141] op_sel_hi:[1,0]
	s_waitcnt lgkmcnt(0)
	v_pk_add_f32 v[116:117], v[116:117], 1.0 op_sel_hi:[1,0]
	s_nop 0
	v_pk_fma_f32 v[108:109], v[116:117], v[112:113], v[108:109]
	v_pk_add_f32 v[118:119], v[118:119], 1.0 op_sel_hi:[1,0]
	v_bfe_u32 v112, v108, 16, 1
	v_add3_u32 v108, v108, v112, s69
	v_bfe_u32 v112, v109, 16, 1
	v_pk_fma_f32 v[110:111], v[118:119], v[114:115], v[110:111]
	v_lshrrev_b32_e32 v108, 16, v108
	v_add3_u32 v109, v109, v112, s69
	v_and_or_b32 v108, v109, s4, v108
	v_bfe_u32 v109, v110, 16, 1
	v_add3_u32 v109, v110, v109, s69
	v_bfe_u32 v110, v111, 16, 1
	v_lshrrev_b32_e32 v109, 16, v109
	v_add3_u32 v110, v111, v110, s69
	v_and_or_b32 v109, v110, s4, v109
	global_store_dwordx2 v[136:137], v[108:109], off offset:2048
	ds_read_b128 v[108:111], v191 offset:29696
	ds_read_b128 v[112:115], v191 offset:37888
	s_waitcnt lgkmcnt(0)
	v_pk_add_f32 v[112:113], v[112:113], 1.0 op_sel_hi:[1,0]
	s_nop 0
	v_pk_fma_f32 v[100:101], v[112:113], v[100:101], v[108:109]
	v_pk_add_f32 v[114:115], v[114:115], 1.0 op_sel_hi:[1,0]
	v_bfe_u32 v108, v100, 16, 1
	v_add3_u32 v100, v100, v108, s69
	v_bfe_u32 v108, v101, 16, 1
	v_pk_fma_f32 v[102:103], v[114:115], v[102:103], v[110:111]
	v_lshrrev_b32_e32 v100, 16, v100
	v_add3_u32 v101, v101, v108, s69
	v_and_or_b32 v100, v101, s4, v100
	v_bfe_u32 v101, v102, 16, 1
	v_add3_u32 v101, v102, v101, s69
	v_bfe_u32 v102, v103, 16, 1
	v_lshrrev_b32_e32 v101, 16, v101
	v_add3_u32 v102, v103, v102, s69
	v_and_or_b32 v101, v102, s4, v101
	global_store_dwordx2 v[136:137], v[100:101], off offset:2560
	ds_read_b128 v[100:103], v191 offset:30720
	ds_read_b128 v[108:111], v191 offset:38912
	s_waitcnt lgkmcnt(0)
	v_pk_add_f32 v[108:109], v[108:109], 1.0 op_sel_hi:[1,0]
	s_nop 0
	v_pk_fma_f32 v[100:101], v[108:109], v[104:105], v[100:101]
	v_pk_add_f32 v[110:111], v[110:111], 1.0 op_sel_hi:[1,0]
	v_bfe_u32 v104, v100, 16, 1
	v_add3_u32 v100, v100, v104, s69
	v_bfe_u32 v104, v101, 16, 1
	v_pk_fma_f32 v[102:103], v[110:111], v[106:107], v[102:103]
	v_lshrrev_b32_e32 v100, 16, v100
	v_add3_u32 v101, v101, v104, s69
	v_and_or_b32 v100, v101, s4, v100
	v_bfe_u32 v101, v102, 16, 1
	v_add3_u32 v101, v102, v101, s69
	v_bfe_u32 v102, v103, 16, 1
	v_lshrrev_b32_e32 v101, 16, v101
	v_add3_u32 v102, v103, v102, s69
	v_and_or_b32 v101, v102, s4, v101
	global_store_dwordx2 v[136:137], v[100:101], off offset:3072
	ds_read_b128 v[100:103], v191 offset:31744
	ds_read_b128 v[104:107], v191 offset:39936
	s_waitcnt lgkmcnt(0)
	v_pk_add_f32 v[104:105], v[104:105], 1.0 op_sel_hi:[1,0]
	s_nop 0
	v_pk_fma_f32 v[96:97], v[104:105], v[96:97], v[100:101]
	v_pk_add_f32 v[106:107], v[106:107], 1.0 op_sel_hi:[1,0]
	v_bfe_u32 v100, v96, 16, 1
	v_add3_u32 v96, v96, v100, s69
	v_bfe_u32 v100, v97, 16, 1
	v_pk_fma_f32 v[98:99], v[106:107], v[98:99], v[102:103]
	v_lshrrev_b32_e32 v96, 16, v96
	v_add3_u32 v97, v97, v100, s69
	v_and_or_b32 v96, v97, s4, v96
	v_bfe_u32 v97, v98, 16, 1
	v_add3_u32 v97, v98, v97, s69
	v_bfe_u32 v98, v99, 16, 1
	v_lshrrev_b32_e32 v97, 16, v97
	v_add3_u32 v98, v99, v98, s69
	v_and_or_b32 v97, v98, s4, v97
	global_store_dwordx2 v[136:137], v[96:97], off offset:3584
.LBB0_1262:
	s_andn2_b64 vcc, exec, s[18:19]
	s_cbranch_vccnz .LBB0_1225
	v_mov_b32_e32 v96, v64
	v_mov_b32_e32 v97, v68
	v_mov_b32_e32 v98, v65
	v_mov_b32_e32 v99, v69
	v_pk_add_f32 v[96:97], v[96:97], v[98:99]
	v_mov_b32_e32 v98, v66
	v_mov_b32_e32 v99, v70
	v_mov_b32_e32 v100, v67
	v_mov_b32_e32 v101, v71
	v_pk_add_f32 v[98:99], v[98:99], v[100:101]
	v_mov_b32_e32 v100, v72
	v_pk_add_f32 v[96:97], v[96:97], v[98:99]
	v_mov_b32_e32 v98, v73
	v_mov_b32_e32 v99, v74
	v_mov_b32_e32 v101, v75
	v_pk_add_f32 v[98:99], v[98:99], v[100:101]
	v_add_f32_e32 v97, 0, v97
	v_pk_add_f32 v[98:99], v[98:99], v[98:99] op_sel_hi:[0,1]
	v_add_f32_e32 v97, v96, v97
	v_add_f32_e32 v101, v76, v77
	v_add_f32_e32 v103, v78, v79
	v_mov_b32_e32 v100, v80
	v_mov_b32_e32 v102, v81
	v_mov_b32_e32 v98, v82
	v_mov_b32_e32 v96, v83
	v_pk_add_f32 v[100:101], v[100:101], v[102:103]
	v_pk_add_f32 v[96:97], v[98:99], v[96:97]
	v_mov_b32_e32 v98, v85
	v_pk_add_f32 v[96:97], v[100:101], v[96:97]
	v_mov_b32_e32 v99, v86
	v_mov_b32_e32 v100, v84
	v_mov_b32_e32 v101, v87
	v_pk_add_f32 v[98:99], v[98:99], v[100:101]
	v_pk_add_f32 v[96:97], v[96:97], v[96:97] op_sel_hi:[0,1]
	v_pk_add_f32 v[98:99], v[98:99], v[98:99] op_sel_hi:[0,1]
	v_add_f32_e32 v101, v88, v89
	v_add_f32_e32 v103, v90, v91
	v_mov_b32_e32 v100, v92
	v_mov_b32_e32 v102, v93
	v_mov_b32_e32 v98, v94
	v_mov_b32_e32 v96, v95
	v_pk_add_f32 v[100:101], v[100:101], v[102:103]
	v_pk_add_f32 v[96:97], v[98:99], v[96:97]
	s_mov_b32 s4, 0xf800000
	v_pk_add_f32 v[96:97], v[100:101], v[96:97]
	s_ashr_i32 s17, s16, 31
	v_add_f32_e32 v96, v96, v97
	ds_bpermute_b32 v97, v129, v96
	s_mov_b64 s[20:21], -1
	s_waitcnt lgkmcnt(0)
	v_add_f32_e32 v96, v96, v97
	ds_bpermute_b32 v97, v182, v96
	s_waitcnt lgkmcnt(0)
	v_add_f32_e32 v96, v96, v97
	ds_bpermute_b32 v97, v183, v96
	s_waitcnt lgkmcnt(0)
	v_add_f32_e32 v96, v96, v97
	ds_bpermute_b32 v97, v184, v96
	s_waitcnt lgkmcnt(0)
	v_add_f32_e32 v96, v96, v97
	ds_bpermute_b32 v97, v185, v96
	s_waitcnt lgkmcnt(0)
	v_add_f32_e32 v96, v96, v97
	ds_bpermute_b32 v97, v186, v96
	s_waitcnt lgkmcnt(0)
	v_add_f32_e32 v104, v96, v97
	v_fmamk_f32 v69, v104, 0xba000000, v69
	v_fmamk_f32 v65, v104, 0xba000000, v65
	v_fmamk_f32 v71, v104, 0xba000000, v71
	v_fmac_f32_e32 v68, 0xba000000, v104
	v_fmamk_f32 v67, v104, 0xba000000, v67
	v_fmac_f32_e32 v64, 0xba000000, v104
	v_mov_b32_e32 v98, v69
	v_mov_b32_e32 v99, v65
	v_fmamk_f32 v70, v104, 0xba000000, v70
	v_fmamk_f32 v66, v104, 0xba000000, v66
	v_mov_b32_e32 v96, v68
	v_mov_b32_e32 v97, v64
	v_pk_mul_f32 v[98:99], v[98:99], v[98:99]
	v_mov_b32_e32 v100, v71
	v_mov_b32_e32 v101, v67
	v_pk_fma_f32 v[96:97], v[96:97], v[96:97], v[98:99]
	v_mov_b32_e32 v98, v70
	v_mov_b32_e32 v99, v66
	v_pk_mul_f32 v[100:101], v[100:101], v[100:101]
	v_fmamk_f32 v75, v104, 0xba000000, v75
	v_pk_fma_f32 v[98:99], v[98:99], v[98:99], v[100:101]
	v_fmamk_f32 v74, v104, 0xba000000, v74
	v_pk_add_f32 v[96:97], v[96:97], v[98:99]
	v_fmamk_f32 v73, v104, 0xba000000, v73
	v_fmac_f32_e32 v72, 0xba000000, v104
	v_pk_add_f32 v[96:97], v[96:97], v[96:97] op_sel_hi:[0,1]
	v_pk_mul_f32 v[98:99], v[74:75], v[74:75]
	v_pk_mul_f32 v[100:101], v[72:73], v[72:73]
	v_fmac_f32_e32 v76, 0xba000000, v104
	v_pk_mov_b32 v[102:103], v[100:101], v[98:99] op_sel:[1,0]
	v_mov_b32_e32 v101, v99
	v_fmamk_f32 v78, v104, 0xba000000, v78
	v_fmamk_f32 v77, v104, 0xba000000, v77
	v_mul_f32_e32 v96, v76, v76
	v_pk_add_f32 v[98:99], v[102:103], v[100:101]
	v_fmamk_f32 v79, v104, 0xba000000, v79
	v_pk_fma_f32 v[100:101], v[76:77], v[76:77], v[96:97] op_sel_hi:[1,1,0]
	v_mul_f32_e32 v96, v78, v78
	v_pk_add_f32 v[98:99], v[98:99], v[98:99] op_sel_hi:[0,1]
	v_pk_fma_f32 v[102:103], v[78:79], v[78:79], v[96:97] op_sel_hi:[1,1,0]
	v_fmamk_f32 v83, v104, 0xba000000, v83
	v_fmamk_f32 v82, v104, 0xba000000, v82
	v_fmamk_f32 v81, v104, 0xba000000, v81
	v_fmac_f32_e32 v80, 0xba000000, v104
	v_mul_f32_e32 v100, v80, v80
	v_mul_f32_e32 v102, v81, v81
	v_mul_f32_e32 v98, v82, v82
	v_mul_f32_e32 v96, v83, v83
	v_pk_add_f32 v[100:101], v[100:101], v[102:103]
	v_pk_add_f32 v[96:97], v[98:99], v[96:97]
	v_fmamk_f32 v87, v104, 0xba000000, v87
	v_pk_add_f32 v[96:97], v[100:101], v[96:97]
	v_fmamk_f32 v86, v104, 0xba000000, v86
	v_fmamk_f32 v85, v104, 0xba000000, v85
	v_fmac_f32_e32 v84, 0xba000000, v104
	v_pk_add_f32 v[96:97], v[96:97], v[96:97] op_sel_hi:[0,1]
	v_pk_mul_f32 v[98:99], v[86:87], v[86:87]
	v_pk_mul_f32 v[100:101], v[84:85], v[84:85]
	v_fmac_f32_e32 v88, 0xba000000, v104
	v_pk_mov_b32 v[102:103], v[100:101], v[98:99] op_sel:[1,0]
	v_mov_b32_e32 v101, v99
	v_fmamk_f32 v90, v104, 0xba000000, v90
	v_fmamk_f32 v89, v104, 0xba000000, v89
	v_mul_f32_e32 v96, v88, v88
	v_pk_add_f32 v[98:99], v[102:103], v[100:101]
	v_fmamk_f32 v91, v104, 0xba000000, v91
	v_pk_fma_f32 v[100:101], v[88:89], v[88:89], v[96:97] op_sel_hi:[1,1,0]
	v_mul_f32_e32 v96, v90, v90
	v_pk_add_f32 v[98:99], v[98:99], v[98:99] op_sel_hi:[0,1]
	v_pk_fma_f32 v[102:103], v[90:91], v[90:91], v[96:97] op_sel_hi:[1,1,0]
	v_fmamk_f32 v95, v104, 0xba000000, v95
	v_fmamk_f32 v94, v104, 0xba000000, v94
	v_fmamk_f32 v93, v104, 0xba000000, v93
	v_fmac_f32_e32 v92, 0xba000000, v104
	v_mul_f32_e32 v100, v92, v92
	v_mul_f32_e32 v102, v93, v93
	v_mul_f32_e32 v98, v94, v94
	v_mul_f32_e32 v96, v95, v95
	v_pk_add_f32 v[100:101], v[100:101], v[102:103]
	v_pk_add_f32 v[96:97], v[98:99], v[96:97]
	s_nop 0
	v_pk_add_f32 v[96:97], v[100:101], v[96:97]
	s_nop 0
	v_add_f32_e32 v96, v96, v97
	s_waitcnt lgkmcnt(0)
	s_nop 1
	v_add_f32_dpp v96, v96, v96 quad_perm:[1,0,3,2] row_mask:0xf bank_mask:0xf
	s_nop 1
	v_add_f32_dpp v96, v96, v96 quad_perm:[2,3,0,1] row_mask:0xf bank_mask:0xf
	s_nop 1
	v_add_f32_dpp v96, v96, v96 row_half_mirror row_mask:0xf bank_mask:0xf
	s_nop 1
	v_add_f32_dpp v96, v96, v96 row_ror:8 row_mask:0xf bank_mask:0xf
	s_nop 0
	v_readlane_b32 s100, v96, 0
	v_readlane_b32 s101, v96, 16
	s_nop 0
	v_mov_b32_e32 v97, s100
	v_add_f32_e32 v97, s101, v97
	v_readlane_b32 s100, v96, 32
	v_readlane_b32 s101, v96, 48
	s_nop 0
	v_add_f32_e32 v97, s100, v97
	v_add_f32_e32 v96, s101, v97
	v_fmamk_f32 v96, v96, 0x3a000000, v229
	v_mul_f32_e32 v97, 0x4f800000, v96
	v_cmp_gt_f32_e32 vcc, s4, v96
	s_nop 1
	v_cndmask_b32_e32 v96, v96, v97, vcc
	v_sqrt_f32_e32 v97, v96
	s_nop 0
	v_add_u32_e32 v98, -1, v97
	v_fma_f32 v99, -v98, v97, v96
	v_cmp_ge_f32_e64 s[8:9], 0, v99
	v_add_u32_e32 v99, 1, v97
	s_nop 0
	v_cndmask_b32_e64 v98, v97, v98, s[8:9]
	v_fma_f32 v97, -v99, v97, v96
	v_cmp_lt_f32_e64 s[8:9], 0, v97
	s_nop 1
	v_cndmask_b32_e64 v97, v98, v99, s[8:9]
	v_mul_f32_e32 v98, 0x37800000, v97
	v_cndmask_b32_e32 v97, v97, v98, vcc
	v_cmp_class_f32_e32 vcc, v96, v230
	s_nop 1
	v_cndmask_b32_e32 v96, v97, v96, vcc
	v_div_scale_f32 v97, s[8:9], v96, v96, 1.0
	v_rcp_f32_e32 v98, v97
	s_lshl_b64 s[8:9], s[16:17], 13
	s_add_u32 s18, s14, s8
	s_addc_u32 s19, s15, s9
	v_fma_f32 v99, -v97, v98, 1.0
	v_fmac_f32_e32 v98, v99, v98
	v_div_scale_f32 v99, vcc, 1.0, v96, 1.0
	v_mul_f32_e32 v100, v99, v98
	v_fma_f32 v101, -v97, v100, v99
	v_fmac_f32_e32 v100, v101, v98
	v_fma_f32 v97, -v97, v100, v99
	v_div_fmas_f32 v97, v97, v98, v100
	v_div_fixup_f32 v96, v97, v96, 1.0
	s_lshl_b64 s[8:9], s[16:17], 12
	s_add_u32 s8, s12, s8
	v_pk_mul_f32 v[68:69], v[68:69], v[96:97] op_sel_hi:[1,0]
	v_pk_mul_f32 v[70:71], v[70:71], v[96:97] op_sel_hi:[1,0]
	s_addc_u32 s9, s13, s9
	v_pk_fma_f32 v[70:71], v[2:3], v[70:71], v[10:11]
	v_pk_fma_f32 v[68:69], v[0:1], v[68:69], v[8:9]
	s_and_b64 vcc, exec, s[0:1]
	v_lshlrev_b32_e32 v99, 2, v128
	s_cbranch_vccz .LBB0_1265
	global_store_dwordx4 v99, v[68:71], s[18:19]
	s_mov_b64 s[20:21], 0

.LBB0_1295:
	v_readlane_b32 s4, v255, 15
	v_readlane_b32 s5, v255, 16
	s_and_b64 vcc, exec, s[4:5]
	s_cbranch_vccnz .LBB0_1225
	v_mov_b32_e32 v96, v64
	v_mov_b32_e32 v97, v68
	v_mov_b32_e32 v98, v65
	v_mov_b32_e32 v99, v69
	v_pk_add_f32 v[96:97], v[96:97], v[98:99]
	v_mov_b32_e32 v98, v66
	v_mov_b32_e32 v99, v70
	v_mov_b32_e32 v100, v67
	v_mov_b32_e32 v101, v71
	v_pk_add_f32 v[98:99], v[98:99], v[100:101]
	v_mov_b32_e32 v100, v72
	v_pk_add_f32 v[96:97], v[96:97], v[98:99]
	v_mov_b32_e32 v98, v73
	v_mov_b32_e32 v99, v74
	v_mov_b32_e32 v101, v75
	v_pk_add_f32 v[98:99], v[98:99], v[100:101]
	v_add_f32_e32 v97, 0, v97
	v_pk_add_f32 v[98:99], v[98:99], v[98:99] op_sel_hi:[0,1]
	v_add_f32_e32 v97, v96, v97
	v_add_f32_e32 v101, v76, v77
	v_add_f32_e32 v103, v78, v79
	v_mov_b32_e32 v100, v80
	v_mov_b32_e32 v102, v81
	v_mov_b32_e32 v98, v82
	v_mov_b32_e32 v96, v83
	v_pk_add_f32 v[100:101], v[100:101], v[102:103]
	v_pk_add_f32 v[96:97], v[98:99], v[96:97]
	v_mov_b32_e32 v98, v85
	v_pk_add_f32 v[96:97], v[100:101], v[96:97]
	v_mov_b32_e32 v99, v86
	v_mov_b32_e32 v100, v84
	v_mov_b32_e32 v101, v87
	v_pk_add_f32 v[98:99], v[98:99], v[100:101]
	v_pk_add_f32 v[96:97], v[96:97], v[96:97] op_sel_hi:[0,1]
	v_pk_add_f32 v[98:99], v[98:99], v[98:99] op_sel_hi:[0,1]
	v_add_f32_e32 v101, v88, v89
	v_add_f32_e32 v103, v90, v91
	v_mov_b32_e32 v100, v92
	v_mov_b32_e32 v102, v93
	v_mov_b32_e32 v98, v94
	v_mov_b32_e32 v96, v95
	v_pk_add_f32 v[100:101], v[100:101], v[102:103]
	v_pk_add_f32 v[96:97], v[98:99], v[96:97]
	v_mov_b32_e32 v140, v68
	v_pk_add_f32 v[96:97], v[100:101], v[96:97]
	v_mov_b32_e32 v152, v64
	v_add_f32_e32 v96, v96, v97
	ds_bpermute_b32 v97, v129, v96
	v_mov_b32_e32 v126, v70
	v_mov_b32_e32 v150, v66
	v_mov_b32_e32 v154, v72
	v_mov_b32_e32 v156, v74
	s_waitcnt lgkmcnt(0)
	v_add_f32_e32 v96, v96, v97
	ds_bpermute_b32 v97, v182, v96
	v_mov_b32_e32 v114, v76
	v_mov_b32_e32 v116, v78
	v_mov_b32_e32 v108, v82
	v_mov_b32_e32 v112, v80
	s_waitcnt lgkmcnt(0)
	v_add_f32_e32 v96, v96, v97
	ds_bpermute_b32 v97, v183, v96
	v_mov_b32_e32 v104, v84
	v_mov_b32_e32 v106, v86
	s_mov_b32 s4, 0xf800000
	s_lshr_b32 s6, s16, 12
	s_waitcnt lgkmcnt(0)
	v_add_f32_e32 v96, v96, v97
	ds_bpermute_b32 v97, v184, v96
	s_mulk_i32 s6, 0x6000
	s_waitcnt lgkmcnt(0)
	v_add_f32_e32 v96, v96, v97
	ds_bpermute_b32 v97, v185, v96
	s_waitcnt lgkmcnt(0)
	v_add_f32_e32 v96, v96, v97
	ds_bpermute_b32 v97, v186, v96
	s_waitcnt lgkmcnt(0)
	v_add_f32_e32 v124, v96, v97
	v_fmamk_f32 v141, v124, 0xba000000, v69
	v_fmamk_f32 v153, v124, 0xba000000, v65
	v_fmamk_f32 v127, v124, 0xba000000, v71
	v_fmac_f32_e32 v140, 0xba000000, v124
	v_fmamk_f32 v151, v124, 0xba000000, v67
	v_fmac_f32_e32 v152, 0xba000000, v124
	v_mov_b32_e32 v98, v141
	v_mov_b32_e32 v99, v153
	v_fmac_f32_e32 v126, 0xba000000, v124
	v_fmac_f32_e32 v150, 0xba000000, v124
	v_mov_b32_e32 v96, v140
	v_mov_b32_e32 v97, v152
	v_pk_mul_f32 v[98:99], v[98:99], v[98:99]
	v_mov_b32_e32 v100, v127
	v_mov_b32_e32 v101, v151
	v_pk_fma_f32 v[96:97], v[96:97], v[96:97], v[98:99]
	v_mov_b32_e32 v98, v126
	v_mov_b32_e32 v99, v150
	v_pk_mul_f32 v[100:101], v[100:101], v[100:101]
	v_fmamk_f32 v155, v124, 0xba000000, v73
	v_pk_fma_f32 v[98:99], v[98:99], v[98:99], v[100:101]
	v_fmac_f32_e32 v154, 0xba000000, v124
	v_pk_add_f32 v[96:97], v[96:97], v[98:99]
	v_fmamk_f32 v157, v124, 0xba000000, v75
	v_fmac_f32_e32 v156, 0xba000000, v124
	v_pk_add_f32 v[96:97], v[96:97], v[96:97] op_sel_hi:[0,1]
	v_pk_mul_f32 v[98:99], v[156:157], v[156:157]
	v_pk_mul_f32 v[100:101], v[154:155], v[154:155]
	v_fmac_f32_e32 v114, 0xba000000, v124
	v_pk_mov_b32 v[102:103], v[100:101], v[98:99] op_sel:[1,0]
	v_mov_b32_e32 v101, v99
	v_fmamk_f32 v115, v124, 0xba000000, v77
	v_fmac_f32_e32 v116, 0xba000000, v124
	v_mul_f32_e32 v96, v114, v114
	v_pk_add_f32 v[98:99], v[102:103], v[100:101]
	v_fmamk_f32 v117, v124, 0xba000000, v79
	v_pk_fma_f32 v[100:101], v[114:115], v[114:115], v[96:97] op_sel_hi:[1,1,0]
	v_mul_f32_e32 v96, v116, v116
	v_pk_add_f32 v[98:99], v[98:99], v[98:99] op_sel_hi:[0,1]
	v_pk_fma_f32 v[102:103], v[116:117], v[116:117], v[96:97] op_sel_hi:[1,1,0]
	v_fmamk_f32 v109, v124, 0xba000000, v83
	v_fmac_f32_e32 v108, 0xba000000, v124
	v_fmamk_f32 v113, v124, 0xba000000, v81
	v_fmac_f32_e32 v112, 0xba000000, v124
	v_mul_f32_e32 v100, v112, v112
	v_mul_f32_e32 v102, v113, v113
	v_mul_f32_e32 v98, v108, v108
	v_mul_f32_e32 v96, v109, v109
	v_pk_add_f32 v[100:101], v[100:101], v[102:103]
	v_pk_add_f32 v[96:97], v[98:99], v[96:97]
	v_fmamk_f32 v105, v124, 0xba000000, v85
	v_pk_add_f32 v[96:97], v[100:101], v[96:97]
	v_fmac_f32_e32 v104, 0xba000000, v124
	v_fmamk_f32 v107, v124, 0xba000000, v87
	v_fmac_f32_e32 v106, 0xba000000, v124
	v_pk_add_f32 v[110:111], v[96:97], v[96:97] op_sel_hi:[0,1]
	v_pk_mul_f32 v[96:97], v[106:107], v[106:107]
	v_pk_mul_f32 v[98:99], v[104:105], v[104:105]
	v_mov_b32_e32 v102, v90
	v_pk_mov_b32 v[100:101], v[98:99], v[96:97] op_sel:[1,0]
	v_mov_b32_e32 v99, v97
	v_pk_add_f32 v[96:97], v[100:101], v[98:99]
	v_mov_b32_e32 v100, v88
	v_fmac_f32_e32 v100, 0xba000000, v124
	v_pk_add_f32 v[118:119], v[96:97], v[96:97] op_sel_hi:[0,1]
	v_fmamk_f32 v101, v124, 0xba000000, v89
	v_fmac_f32_e32 v102, 0xba000000, v124
	v_mul_f32_e32 v96, v100, v100
	v_fmamk_f32 v103, v124, 0xba000000, v91
	v_pk_fma_f32 v[120:121], v[100:101], v[100:101], v[96:97] op_sel_hi:[1,1,0]
	v_mul_f32_e32 v96, v102, v102
	v_pk_fma_f32 v[122:123], v[102:103], v[102:103], v[96:97] op_sel_hi:[1,1,0]
	v_mov_b32_e32 v96, v94
	v_mov_b32_e32 v98, v92
	v_fmamk_f32 v97, v124, 0xba000000, v95
	v_fmac_f32_e32 v96, 0xba000000, v124
	v_fmamk_f32 v99, v124, 0xba000000, v93
	v_fmac_f32_e32 v98, 0xba000000, v124
	v_mul_f32_e32 v120, v98, v98
	v_mul_f32_e32 v122, v99, v99
	v_mul_f32_e32 v118, v96, v96
	v_mul_f32_e32 v110, v97, v97
	v_pk_add_f32 v[120:121], v[120:121], v[122:123]
	v_pk_add_f32 v[110:111], v[118:119], v[110:111]
	s_nop 0
	v_pk_add_f32 v[110:111], v[120:121], v[110:111]
	s_nop 0
	v_add_f32_e32 v110, v110, v111
	s_waitcnt lgkmcnt(0)
	s_nop 1
	v_add_f32_dpp v110, v110, v110 quad_perm:[1,0,3,2] row_mask:0xf bank_mask:0xf
	s_nop 1
	v_add_f32_dpp v110, v110, v110 quad_perm:[2,3,0,1] row_mask:0xf bank_mask:0xf
	s_nop 1
	v_add_f32_dpp v110, v110, v110 row_half_mirror row_mask:0xf bank_mask:0xf
	s_nop 1
	v_add_f32_dpp v110, v110, v110 row_ror:8 row_mask:0xf bank_mask:0xf
	s_nop 0
	v_readlane_b32 s100, v110, 0
	v_readlane_b32 s101, v110, 16
	s_nop 0
	v_mov_b32_e32 v111, s100
	v_add_f32_e32 v111, s101, v111
	v_readlane_b32 s100, v110, 32
	v_readlane_b32 s101, v110, 48
	s_nop 0
	v_add_f32_e32 v111, s100, v111
	v_add_f32_e32 v110, s101, v111
	v_fmamk_f32 v110, v110, 0x3a000000, v229
	v_mul_f32_e32 v111, 0x4f800000, v110
	v_cmp_gt_f32_e32 vcc, s4, v110
	s_mov_b32 s4, 0xffff0000
	s_nop 0
	v_cndmask_b32_e32 v110, v110, v111, vcc
	v_sqrt_f32_e32 v111, v110
	s_nop 0
	v_add_u32_e32 v118, -1, v111
	v_fma_f32 v119, -v118, v111, v110
	v_cmp_ge_f32_e64 s[8:9], 0, v119
	v_add_u32_e32 v119, 1, v111
	s_nop 0
	v_cndmask_b32_e64 v118, v111, v118, s[8:9]
	v_fma_f32 v111, -v119, v111, v110
	v_cmp_lt_f32_e64 s[8:9], 0, v111
	s_nop 1
	v_cndmask_b32_e64 v111, v118, v119, s[8:9]
	v_mul_f32_e32 v118, 0x37800000, v111
	v_cndmask_b32_e32 v111, v111, v118, vcc
	v_cmp_class_f32_e32 vcc, v110, v230
	s_nop 1
	v_cndmask_b32_e32 v110, v111, v110, vcc
	v_div_scale_f32 v111, s[8:9], v110, v110, 1.0
	v_rcp_f32_e32 v118, v111
	s_lshl_b64 s[8:9], s[16:17], 11
	v_fma_f32 v119, -v111, v118, 1.0
	v_fmac_f32_e32 v118, v119, v118
	v_div_scale_f32 v119, vcc, 1.0, v110, 1.0
	v_mul_f32_e32 v120, v119, v118
	v_fma_f32 v121, -v111, v120, v119
	v_fmac_f32_e32 v120, v121, v118
	v_fma_f32 v111, -v111, v120, v119
	v_div_fmas_f32 v111, v111, v118, v120
	v_div_fixup_f32 v110, v111, v110, 1.0
	v_add_u32_e32 v111, s6, v187
	ds_read_b128 v[118:121], v111 offset:32768
	ds_read_b128 v[122:125], v111 offset:24576
	v_pk_mul_f32 v[158:159], v[140:141], v[110:111] op_sel_hi:[1,0]
	v_pk_mul_f32 v[126:127], v[126:127], v[110:111] op_sel_hi:[1,0]
	ds_read_b128 v[140:143], v111 offset:33792
	ds_read_b128 v[146:149], v111 offset:25600
	s_waitcnt lgkmcnt(3)
	v_pk_add_f32 v[118:119], v[118:119], 1.0 op_sel_hi:[1,0]
	v_pk_add_f32 v[120:121], v[120:121], 1.0 op_sel_hi:[1,0]
	s_waitcnt lgkmcnt(2)
	v_pk_fma_f32 v[118:119], v[118:119], v[158:159], v[122:123]
	v_pk_fma_f32 v[120:121], v[120:121], v[126:127], v[124:125]
	v_bfe_u32 v122, v118, 16, 1
	v_add3_u32 v118, v118, v122, s69
	v_bfe_u32 v122, v119, 16, 1
	v_lshrrev_b32_e32 v118, 16, v118
	v_add3_u32 v119, v119, v122, s69
	v_and_or_b32 v122, v119, s4, v118
	v_bfe_u32 v118, v120, 16, 1
	v_add3_u32 v118, v120, v118, s69
	v_bfe_u32 v119, v121, 16, 1
	v_lshrrev_b32_e32 v118, 16, v118
	v_add3_u32 v119, v121, v119, s69
	v_and_or_b32 v123, v119, s4, v118
	v_lshl_add_u64 v[118:119], s[8:9], 1, v[134:135]
	v_pk_mul_f32 v[120:121], v[152:153], v[110:111] op_sel_hi:[1,0]
	s_waitcnt lgkmcnt(1)
	v_pk_add_f32 v[126:127], v[140:141], 1.0 op_sel_hi:[1,0]
	global_store_dwordx2 v[118:119], v[122:123], off
	v_pk_mul_f32 v[122:123], v[150:151], v[110:111] op_sel_hi:[1,0]
	v_pk_add_f32 v[124:125], v[142:143], 1.0 op_sel_hi:[1,0]
	s_waitcnt lgkmcnt(0)
	v_pk_fma_f32 v[120:121], v[126:127], v[120:121], v[146:147]
	v_pk_fma_f32 v[122:123], v[124:125], v[122:123], v[148:149]
	v_bfe_u32 v124, v120, 16, 1
	v_add3_u32 v120, v120, v124, s69
	v_bfe_u32 v124, v121, 16, 1
	v_lshrrev_b32_e32 v120, 16, v120
	v_add3_u32 v121, v121, v124, s69
	v_and_or_b32 v120, v121, s4, v120
	v_bfe_u32 v121, v122, 16, 1
	v_add3_u32 v121, v122, v121, s69
	v_bfe_u32 v122, v123, 16, 1
	v_lshrrev_b32_e32 v121, 16, v121
	v_add3_u32 v122, v123, v122, s69
	v_and_or_b32 v121, v122, s4, v121
	global_store_dwordx2 v[118:119], v[120:121], off offset:512
	ds_read_b128 v[120:123], v111 offset:34816
	ds_read_b128 v[124:127], v111 offset:26624
	v_pk_mul_f32 v[146:147], v[154:155], v[110:111] op_sel_hi:[1,0]
	v_pk_mul_f32 v[148:149], v[156:157], v[110:111] op_sel_hi:[1,0]
	ds_read_b128 v[140:143], v111 offset:35840
	s_waitcnt lgkmcnt(2)
	v_pk_add_f32 v[152:153], v[120:121], 1.0 op_sel_hi:[1,0]
	v_pk_add_f32 v[150:151], v[122:123], 1.0 op_sel_hi:[1,0]
	s_waitcnt lgkmcnt(1)
	v_pk_fma_f32 v[124:125], v[152:153], v[146:147], v[124:125]
	ds_read_b128 v[120:123], v111 offset:27648
	v_bfe_u32 v146, v124, 16, 1
	v_add3_u32 v124, v124, v146, s69
	v_bfe_u32 v146, v125, 16, 1
	v_pk_fma_f32 v[126:127], v[150:151], v[148:149], v[126:127]
	v_lshrrev_b32_e32 v124, 16, v124
	v_add3_u32 v125, v125, v146, s69
	v_and_or_b32 v124, v125, s4, v124
	v_bfe_u32 v125, v126, 16, 1
	v_add3_u32 v125, v126, v125, s69
	v_bfe_u32 v126, v127, 16, 1
	v_lshrrev_b32_e32 v125, 16, v125
	v_add3_u32 v126, v127, v126, s69
	v_and_or_b32 v125, v126, s4, v125
	v_pk_mul_f32 v[114:115], v[114:115], v[110:111] op_sel_hi:[1,0]
	s_waitcnt lgkmcnt(1)
	v_pk_add_f32 v[126:127], v[140:141], 1.0 op_sel_hi:[1,0]
	global_store_dwordx2 v[118:119], v[124:125], off offset:1024
	s_waitcnt lgkmcnt(0)
	v_pk_fma_f32 v[114:115], v[126:127], v[114:115], v[120:121]
	v_pk_mul_f32 v[116:117], v[116:117], v[110:111] op_sel_hi:[1,0]
	v_bfe_u32 v120, v114, 16, 1
	v_pk_add_f32 v[124:125], v[142:143], 1.0 op_sel_hi:[1,0]
	v_add3_u32 v114, v114, v120, s69
	v_bfe_u32 v120, v115, 16, 1
	v_pk_fma_f32 v[116:117], v[124:125], v[116:117], v[122:123]
	v_lshrrev_b32_e32 v114, 16, v114
	v_add3_u32 v115, v115, v120, s69
	v_and_or_b32 v114, v115, s4, v114
	v_bfe_u32 v115, v116, 16, 1
	v_add3_u32 v115, v116, v115, s69
	v_bfe_u32 v116, v117, 16, 1
	v_lshrrev_b32_e32 v115, 16, v115
	v_add3_u32 v116, v117, v116, s69
	v_and_or_b32 v115, v116, s4, v115
	global_store_dwordx2 v[118:119], v[114:115], off offset:1536
	ds_read_b128 v[114:117], v111 offset:36864
	ds_read_b128 v[120:123], v111 offset:28672
	v_pk_mul_f32 v[140:141], v[112:113], v[110:111] op_sel_hi:[1,0]
	v_pk_mul_f32 v[108:109], v[108:109], v[110:111] op_sel_hi:[1,0]
	ds_read_b128 v[124:127], v111 offset:37888
	s_waitcnt lgkmcnt(2)
	v_pk_add_f32 v[116:117], v[116:117], 1.0 op_sel_hi:[1,0]
	v_pk_add_f32 v[142:143], v[114:115], 1.0 op_sel_hi:[1,0]
	s_waitcnt lgkmcnt(1)
	v_pk_fma_f32 v[108:109], v[116:117], v[108:109], v[122:123]
	v_pk_fma_f32 v[116:117], v[142:143], v[140:141], v[120:121]
	ds_read_b128 v[112:115], v111 offset:29696
	v_bfe_u32 v120, v116, 16, 1
	v_add3_u32 v116, v116, v120, s69
	v_bfe_u32 v120, v117, 16, 1
	v_lshrrev_b32_e32 v116, 16, v116
	v_add3_u32 v117, v117, v120, s69
	v_and_or_b32 v116, v117, s4, v116
	v_bfe_u32 v117, v108, 16, 1
	v_add3_u32 v108, v108, v117, s69
	v_bfe_u32 v117, v109, 16, 1
	v_lshrrev_b32_e32 v108, 16, v108
	v_add3_u32 v109, v109, v117, s69
	v_and_or_b32 v117, v109, s4, v108
	global_store_dwordx2 v[118:119], v[116:117], off offset:2048
	v_pk_mul_f32 v[104:105], v[104:105], v[110:111] op_sel_hi:[1,0]
	s_waitcnt lgkmcnt(1)
	v_pk_add_f32 v[116:117], v[124:125], 1.0 op_sel_hi:[1,0]
	v_pk_mul_f32 v[106:107], v[106:107], v[110:111] op_sel_hi:[1,0]
	v_pk_add_f32 v[108:109], v[126:127], 1.0 op_sel_hi:[1,0]
	s_waitcnt lgkmcnt(0)
	v_pk_fma_f32 v[104:105], v[116:117], v[104:105], v[112:113]
	v_pk_fma_f32 v[106:107], v[108:109], v[106:107], v[114:115]
	v_bfe_u32 v108, v104, 16, 1
	v_add3_u32 v104, v104, v108, s69
	v_bfe_u32 v108, v105, 16, 1
	v_lshrrev_b32_e32 v104, 16, v104
	v_add3_u32 v105, v105, v108, s69
	v_and_or_b32 v104, v105, s4, v104
	v_bfe_u32 v105, v106, 16, 1
	v_add3_u32 v105, v106, v105, s69
	v_bfe_u32 v106, v107, 16, 1
	v_lshrrev_b32_e32 v105, 16, v105
	v_add3_u32 v106, v107, v106, s69
	v_and_or_b32 v105, v106, s4, v105
	global_store_dwordx2 v[118:119], v[104:105], off offset:2560
	ds_read_b128 v[104:107], v111 offset:38912
	ds_read_b128 v[112:115], v111 offset:30720
	v_pk_mul_f32 v[108:109], v[100:101], v[110:111] op_sel_hi:[1,0]
	v_pk_mul_f32 v[116:117], v[102:103], v[110:111] op_sel_hi:[1,0]
	ds_read_b128 v[100:103], v111 offset:39936
	s_waitcnt lgkmcnt(2)
	v_pk_add_f32 v[122:123], v[104:105], 1.0 op_sel_hi:[1,0]
	v_pk_add_f32 v[120:121], v[106:107], 1.0 op_sel_hi:[1,0]
	s_waitcnt lgkmcnt(1)
	v_pk_fma_f32 v[108:109], v[122:123], v[108:109], v[112:113]
	ds_read_b128 v[104:107], v111 offset:31744
	v_bfe_u32 v111, v108, 16, 1
	v_pk_fma_f32 v[114:115], v[120:121], v[116:117], v[114:115]
	v_add3_u32 v108, v108, v111, s69
	v_bfe_u32 v111, v109, 16, 1
	v_add3_u32 v109, v109, v111, s69
	v_bfe_u32 v111, v115, 16, 1
	v_add3_u32 v111, v115, v111, s69
	v_pk_mul_f32 v[98:99], v[98:99], v[110:111] op_sel_hi:[1,0]
	s_waitcnt lgkmcnt(1)
	v_pk_add_f32 v[100:101], v[100:101], 1.0 op_sel_hi:[1,0]
	v_pk_mul_f32 v[96:97], v[96:97], v[110:111] op_sel_hi:[1,0]
	s_waitcnt lgkmcnt(0)
	v_pk_fma_f32 v[98:99], v[100:101], v[98:99], v[104:105]
	v_pk_add_f32 v[102:103], v[102:103], 1.0 op_sel_hi:[1,0]
	v_bfe_u32 v100, v98, 16, 1
	v_add3_u32 v98, v98, v100, s69
	v_bfe_u32 v100, v99, 16, 1
	v_lshrrev_b32_e32 v108, 16, v108
	v_pk_fma_f32 v[96:97], v[102:103], v[96:97], v[106:107]
	v_lshrrev_b32_e32 v98, 16, v98
	v_add3_u32 v99, v99, v100, s69
	v_and_or_b32 v108, v109, s4, v108
	v_bfe_u32 v109, v114, 16, 1
	v_and_or_b32 v98, v99, s4, v98
	v_bfe_u32 v99, v96, 16, 1
	v_add3_u32 v109, v114, v109, s69
	v_add3_u32 v96, v96, v99, s69
	v_bfe_u32 v99, v97, 16, 1
	v_lshrrev_b32_e32 v109, 16, v109
	v_lshrrev_b32_e32 v96, 16, v96
	v_add3_u32 v97, v97, v99, s69
	v_and_or_b32 v109, v111, s4, v109
	v_and_or_b32 v99, v97, s4, v96
	global_store_dwordx2 v[118:119], v[108:109], off offset:3072
	global_store_dwordx2 v[118:119], v[98:99], off offset:3584
	s_branch .LBB0_1225

.LBB0_1300:
	v_lshl_add_u64 v[0:1], s[0:1], 0, v[144:145]
	v_add_co_u32_e32 v4, vcc, 0x1dc00000, v0
	s_add_i32 s8, s8, s88
	s_nop 0
	v_addc_co_u32_e32 v5, vcc, 0, v1, vcc
	v_add_co_u32_e32 v8, vcc, 0x1e000000, v0
	global_load_dwordx2 v[6:7], v[4:5], off
	s_nop 0
	v_addc_co_u32_e32 v9, vcc, 0, v1, vcc
	v_add_co_u32_e32 v10, vcc, 0x1e400000, v0
	global_load_dwordx2 v[78:79], v[8:9], off
	s_nop 0
	v_addc_co_u32_e32 v11, vcc, 0, v1, vcc
	v_add_co_u32_e32 v90, vcc, 0x1e800000, v0
	global_load_dwordx2 v[80:81], v[10:11], off
	s_nop 0
	v_addc_co_u32_e32 v91, vcc, 0, v1, vcc
	global_load_dwordx2 v[92:93], v[90:91], off
	v_lshl_add_u64 v[0:1], s[6:7], 0, v[144:145]
	v_add_co_u32_e32 v2, vcc, 0xc800000, v0
	s_add_u32 s0, s0, s62
	s_nop 0
	v_addc_co_u32_e32 v3, vcc, 0, v1, vcc
	global_load_dwordx2 v[94:95], v[2:3], off
	global_load_dwordx2 v[76:77], v[4:5], off offset:512
	global_load_dwordx2 v[74:75], v[8:9], off offset:512
	global_load_dwordx2 v[72:73], v[10:11], off offset:512
	global_load_dwordx2 v[20:21], v[90:91], off offset:512
	global_load_dwordx2 v[18:19], v[2:3], off offset:512
	global_load_dwordx2 v[70:71], v[4:5], off offset:1024
	global_load_dwordx2 v[68:69], v[8:9], off offset:1024
	global_load_dwordx2 v[66:67], v[10:11], off offset:1024
	global_load_dwordx2 v[34:35], v[90:91], off offset:1024
	global_load_dwordx2 v[32:33], v[2:3], off offset:1024
	global_load_dwordx2 v[64:65], v[4:5], off offset:1536
	global_load_dwordx2 v[62:63], v[8:9], off offset:1536
	global_load_dwordx2 v[60:61], v[10:11], off offset:1536
	global_load_dwordx2 v[48:49], v[90:91], off offset:1536
	global_load_dwordx2 v[46:47], v[2:3], off offset:1536
	global_load_dwordx2 v[58:59], v[4:5], off offset:2048
	global_load_dwordx2 v[56:57], v[8:9], off offset:2048
	global_load_dwordx2 v[54:55], v[10:11], off offset:2048
	global_load_dwordx2 v[52:53], v[90:91], off offset:2048
	global_load_dwordx2 v[50:51], v[2:3], off offset:2048
	global_load_dwordx2 v[44:45], v[4:5], off offset:2560
	global_load_dwordx2 v[42:43], v[8:9], off offset:2560
	global_load_dwordx2 v[40:41], v[10:11], off offset:2560
	global_load_dwordx2 v[38:39], v[90:91], off offset:2560
	global_load_dwordx2 v[36:37], v[2:3], off offset:2560
	global_load_dwordx2 v[30:31], v[4:5], off offset:3072
	global_load_dwordx2 v[28:29], v[8:9], off offset:3072
	global_load_dwordx2 v[26:27], v[10:11], off offset:3072
	global_load_dwordx2 v[24:25], v[90:91], off offset:3072
	global_load_dwordx2 v[22:23], v[2:3], off offset:3072
	global_load_dwordx2 v[16:17], v[4:5], off offset:3584
	global_load_dwordx2 v[14:15], v[8:9], off offset:3584
	global_load_dwordx2 v[12:13], v[10:11], off offset:3584
	s_nop 0
	global_load_dwordx2 v[10:11], v[90:91], off offset:3584
	global_load_dwordx2 v[8:9], v[2:3], off offset:3584
	s_addc_u32 s1, s1, s63
	s_add_u32 s6, s6, s62
	s_addc_u32 s7, s7, s63
	s_cmpk_lt_i32 s8, 0x4400
	s_waitcnt vmcnt(39)
	v_lshlrev_b32_e32 v4, 16, v6
	v_and_b32_e32 v5, 0xffff0000, v6
	v_lshlrev_b32_e32 v6, 16, v7
	v_and_b32_e32 v7, 0xffff0000, v7
	s_waitcnt vmcnt(38)
	v_lshlrev_b32_e32 v90, 16, v78
	v_and_b32_e32 v91, 0xffff0000, v78
	v_lshlrev_b32_e32 v78, 16, v79
	v_and_b32_e32 v79, 0xffff0000, v79
	v_pk_add_f32 v[90:91], v[4:5], v[90:91]
	v_pk_add_f32 v[4:5], v[6:7], v[78:79]
	s_waitcnt vmcnt(37)
	v_lshlrev_b32_e32 v6, 16, v80
	v_and_b32_e32 v7, 0xffff0000, v80
	v_lshlrev_b32_e32 v78, 16, v81
	v_and_b32_e32 v79, 0xffff0000, v81
	s_waitcnt vmcnt(36)
	v_lshlrev_b32_e32 v80, 16, v92
	v_and_b32_e32 v81, 0xffff0000, v92
	v_lshlrev_b32_e32 v92, 16, v93
	v_and_b32_e32 v93, 0xffff0000, v93
	v_pk_add_f32 v[6:7], v[6:7], v[80:81]
	v_pk_add_f32 v[78:79], v[78:79], v[92:93]
	s_waitcnt vmcnt(35)
	v_cvt_f32_f16_e32 v80, v95
	v_pk_add_f32 v[4:5], v[4:5], v[78:79]
	v_pk_add_f32 v[78:79], v[90:91], v[6:7]
	ds_read_b128 v[90:93], v88 offset:16384
	v_cvt_f32_f16_e32 v6, v94
	v_cvt_f32_f16_sdwa v7, v94 dst_sel:DWORD dst_unused:UNUSED_PAD src0_sel:WORD_1
	v_cvt_f32_f16_sdwa v81, v95 dst_sel:DWORD dst_unused:UNUSED_PAD src0_sel:WORD_1
	s_waitcnt lgkmcnt(0)
	v_pk_mul_f32 v[78:79], v[78:79], v[90:91]
	v_pk_mul_f32 v[4:5], v[4:5], v[92:93]
	v_pk_fma_f32 v[6:7], v[6:7], s[12:13], v[78:79] op_sel_hi:[1,0,1]
	v_pk_fma_f32 v[4:5], v[80:81], s[12:13], v[4:5] op_sel_hi:[1,0,1]
	s_waitcnt vmcnt(34)
	v_lshlrev_b32_e32 v78, 16, v76
	v_and_b32_e32 v79, 0xffff0000, v76
	v_lshlrev_b32_e32 v76, 16, v77
	v_and_b32_e32 v77, 0xffff0000, v77
	s_waitcnt vmcnt(33)
	v_lshlrev_b32_e32 v80, 16, v74
	v_and_b32_e32 v81, 0xffff0000, v74
	v_lshlrev_b32_e32 v74, 16, v75
	v_and_b32_e32 v75, 0xffff0000, v75
	v_pk_add_f32 v[78:79], v[78:79], v[80:81]
	v_pk_add_f32 v[74:75], v[76:77], v[74:75]
	s_waitcnt vmcnt(32)
	v_lshlrev_b32_e32 v76, 16, v72
	v_and_b32_e32 v77, 0xffff0000, v72
	v_lshlrev_b32_e32 v72, 16, v73
	v_and_b32_e32 v73, 0xffff0000, v73
	s_waitcnt vmcnt(31)
	v_lshlrev_b32_e32 v80, 16, v20
	v_and_b32_e32 v81, 0xffff0000, v20
	v_lshlrev_b32_e32 v20, 16, v21
	v_and_b32_e32 v21, 0xffff0000, v21
	v_pk_add_f32 v[76:77], v[76:77], v[80:81]
	v_pk_add_f32 v[20:21], v[72:73], v[20:21]
	s_nop 0
	v_pk_add_f32 v[72:73], v[74:75], v[20:21]
	v_pk_add_f32 v[74:75], v[78:79], v[76:77]
	s_waitcnt vmcnt(30)
	v_cvt_f32_f16_e32 v76, v18
	v_cvt_f32_f16_sdwa v77, v18 dst_sel:DWORD dst_unused:UNUSED_PAD src0_sel:WORD_1
	v_cvt_f32_f16_e32 v78, v19
	v_cvt_f32_f16_sdwa v79, v19 dst_sel:DWORD dst_unused:UNUSED_PAD src0_sel:WORD_1
	ds_read_b128 v[18:21], v88 offset:17408
	s_waitcnt lgkmcnt(0)
	v_pk_mul_f32 v[74:75], v[74:75], v[18:19]
	v_pk_mul_f32 v[18:19], v[72:73], v[20:21]
	v_pk_fma_f32 v[20:21], v[76:77], s[12:13], v[74:75] op_sel_hi:[1,0,1]
	s_waitcnt vmcnt(29)
	v_lshlrev_b32_e32 v72, 16, v70
	v_and_b32_e32 v73, 0xffff0000, v70
	v_lshlrev_b32_e32 v70, 16, v71
	v_and_b32_e32 v71, 0xffff0000, v71
	s_waitcnt vmcnt(28)
	v_lshlrev_b32_e32 v74, 16, v68
	v_and_b32_e32 v75, 0xffff0000, v68
	v_lshlrev_b32_e32 v68, 16, v69
	v_and_b32_e32 v69, 0xffff0000, v69
	v_pk_add_f32 v[72:73], v[72:73], v[74:75]
	v_pk_add_f32 v[68:69], v[70:71], v[68:69]
	s_waitcnt vmcnt(27)
	v_lshlrev_b32_e32 v70, 16, v66
	v_and_b32_e32 v71, 0xffff0000, v66
	v_lshlrev_b32_e32 v66, 16, v67
	v_and_b32_e32 v67, 0xffff0000, v67
	s_waitcnt vmcnt(26)
	v_lshlrev_b32_e32 v74, 16, v34
	v_and_b32_e32 v75, 0xffff0000, v34
	v_lshlrev_b32_e32 v34, 16, v35
	v_and_b32_e32 v35, 0xffff0000, v35
	v_pk_add_f32 v[70:71], v[70:71], v[74:75]
	v_pk_add_f32 v[34:35], v[66:67], v[34:35]
	v_pk_fma_f32 v[18:19], v[78:79], s[12:13], v[18:19] op_sel_hi:[1,0,1]
	v_pk_add_f32 v[66:67], v[68:69], v[34:35]
	v_pk_add_f32 v[68:69], v[72:73], v[70:71]
	s_waitcnt vmcnt(25)
	v_cvt_f32_f16_e32 v70, v32
	v_cvt_f32_f16_sdwa v71, v32 dst_sel:DWORD dst_unused:UNUSED_PAD src0_sel:WORD_1
	v_cvt_f32_f16_e32 v72, v33
	v_cvt_f32_f16_sdwa v73, v33 dst_sel:DWORD dst_unused:UNUSED_PAD src0_sel:WORD_1
	ds_read_b128 v[32:35], v88 offset:18432
	s_waitcnt lgkmcnt(0)
	v_pk_mul_f32 v[32:33], v[68:69], v[32:33]
	v_pk_mul_f32 v[34:35], v[66:67], v[34:35]
	s_waitcnt vmcnt(24)
	v_lshlrev_b32_e32 v66, 16, v64
	v_and_b32_e32 v67, 0xffff0000, v64
	v_lshlrev_b32_e32 v64, 16, v65
	v_and_b32_e32 v65, 0xffff0000, v65
	s_waitcnt vmcnt(23)
	v_lshlrev_b32_e32 v68, 16, v62
	v_and_b32_e32 v69, 0xffff0000, v62
	v_lshlrev_b32_e32 v62, 16, v63
	v_and_b32_e32 v63, 0xffff0000, v63
	v_pk_add_f32 v[66:67], v[66:67], v[68:69]
	v_pk_add_f32 v[62:63], v[64:65], v[62:63]
	s_waitcnt vmcnt(22)
	v_lshlrev_b32_e32 v64, 16, v60
	v_and_b32_e32 v65, 0xffff0000, v60
	v_lshlrev_b32_e32 v60, 16, v61
	v_and_b32_e32 v61, 0xffff0000, v61
	s_waitcnt vmcnt(21)
	v_lshlrev_b32_e32 v68, 16, v48
	v_and_b32_e32 v69, 0xffff0000, v48
	v_lshlrev_b32_e32 v48, 16, v49
	v_and_b32_e32 v49, 0xffff0000, v49
	v_pk_add_f32 v[64:65], v[64:65], v[68:69]
	v_pk_add_f32 v[48:49], v[60:61], v[48:49]
	v_pk_fma_f32 v[34:35], v[72:73], s[12:13], v[34:35] op_sel_hi:[1,0,1]
	v_pk_add_f32 v[60:61], v[62:63], v[48:49]
	v_pk_add_f32 v[62:63], v[66:67], v[64:65]
	s_waitcnt vmcnt(20)
	v_cvt_f32_f16_e32 v64, v46
	v_cvt_f32_f16_sdwa v65, v46 dst_sel:DWORD dst_unused:UNUSED_PAD src0_sel:WORD_1
	v_cvt_f32_f16_e32 v66, v47
	v_cvt_f32_f16_sdwa v67, v47 dst_sel:DWORD dst_unused:UNUSED_PAD src0_sel:WORD_1
	ds_read_b128 v[46:49], v88 offset:19456
	v_pk_fma_f32 v[32:33], v[70:71], s[12:13], v[32:33] op_sel_hi:[1,0,1]
	s_waitcnt lgkmcnt(0)
	v_pk_mul_f32 v[46:47], v[62:63], v[46:47]
	v_pk_mul_f32 v[48:49], v[60:61], v[48:49]
	s_waitcnt vmcnt(19)
	v_lshlrev_b32_e32 v60, 16, v58
	v_and_b32_e32 v61, 0xffff0000, v58
	v_lshlrev_b32_e32 v58, 16, v59
	v_and_b32_e32 v59, 0xffff0000, v59
	s_waitcnt vmcnt(18)
	v_lshlrev_b32_e32 v62, 16, v56
	v_and_b32_e32 v63, 0xffff0000, v56
	v_lshlrev_b32_e32 v56, 16, v57
	v_and_b32_e32 v57, 0xffff0000, v57
	v_pk_add_f32 v[60:61], v[60:61], v[62:63]
	v_pk_add_f32 v[56:57], v[58:59], v[56:57]
	s_waitcnt vmcnt(17)
	v_lshlrev_b32_e32 v58, 16, v54
	v_and_b32_e32 v59, 0xffff0000, v54
	v_lshlrev_b32_e32 v54, 16, v55
	v_and_b32_e32 v55, 0xffff0000, v55
	s_waitcnt vmcnt(16)
	v_lshlrev_b32_e32 v62, 16, v52
	v_and_b32_e32 v63, 0xffff0000, v52
	v_lshlrev_b32_e32 v52, 16, v53
	v_and_b32_e32 v53, 0xffff0000, v53
	v_pk_add_f32 v[58:59], v[58:59], v[62:63]
	v_pk_add_f32 v[52:53], v[54:55], v[52:53]
	v_pk_fma_f32 v[48:49], v[66:67], s[12:13], v[48:49] op_sel_hi:[1,0,1]
	v_pk_add_f32 v[54:55], v[56:57], v[52:53]
	v_pk_add_f32 v[56:57], v[60:61], v[58:59]
	s_waitcnt vmcnt(15)
	v_cvt_f32_f16_e32 v58, v50
	v_cvt_f32_f16_sdwa v59, v50 dst_sel:DWORD dst_unused:UNUSED_PAD src0_sel:WORD_1
	v_cvt_f32_f16_e32 v60, v51
	v_cvt_f32_f16_sdwa v61, v51 dst_sel:DWORD dst_unused:UNUSED_PAD src0_sel:WORD_1
	ds_read_b128 v[50:53], v88 offset:20480
	v_pk_fma_f32 v[46:47], v[64:65], s[12:13], v[46:47] op_sel_hi:[1,0,1]
	s_waitcnt lgkmcnt(0)
	v_pk_mul_f32 v[50:51], v[56:57], v[50:51]
	v_pk_mul_f32 v[52:53], v[54:55], v[52:53]
	s_waitcnt vmcnt(14)
	v_lshlrev_b32_e32 v54, 16, v44
	v_and_b32_e32 v55, 0xffff0000, v44
	v_lshlrev_b32_e32 v44, 16, v45
	v_and_b32_e32 v45, 0xffff0000, v45
	s_waitcnt vmcnt(13)
	v_lshlrev_b32_e32 v56, 16, v42
	v_and_b32_e32 v57, 0xffff0000, v42
	v_lshlrev_b32_e32 v42, 16, v43
	v_and_b32_e32 v43, 0xffff0000, v43
	v_pk_add_f32 v[54:55], v[54:55], v[56:57]
	v_pk_add_f32 v[42:43], v[44:45], v[42:43]
	s_waitcnt vmcnt(12)
	v_lshlrev_b32_e32 v44, 16, v40
	v_and_b32_e32 v45, 0xffff0000, v40
	v_lshlrev_b32_e32 v40, 16, v41
	v_and_b32_e32 v41, 0xffff0000, v41
	s_waitcnt vmcnt(11)
	v_lshlrev_b32_e32 v56, 16, v38
	v_and_b32_e32 v57, 0xffff0000, v38
	v_lshlrev_b32_e32 v38, 16, v39
	v_and_b32_e32 v39, 0xffff0000, v39
	v_pk_add_f32 v[44:45], v[44:45], v[56:57]
	v_pk_add_f32 v[38:39], v[40:41], v[38:39]
	v_pk_fma_f32 v[52:53], v[60:61], s[12:13], v[52:53] op_sel_hi:[1,0,1]
	v_pk_add_f32 v[40:41], v[42:43], v[38:39]
	v_pk_add_f32 v[42:43], v[54:55], v[44:45]
	s_waitcnt vmcnt(10)
	v_cvt_f32_f16_e32 v44, v36
	v_cvt_f32_f16_sdwa v45, v36 dst_sel:DWORD dst_unused:UNUSED_PAD src0_sel:WORD_1
	v_cvt_f32_f16_e32 v54, v37
	v_cvt_f32_f16_sdwa v55, v37 dst_sel:DWORD dst_unused:UNUSED_PAD src0_sel:WORD_1
	ds_read_b128 v[36:39], v88 offset:21504
	v_pk_fma_f32 v[50:51], v[58:59], s[12:13], v[50:51] op_sel_hi:[1,0,1]
	s_waitcnt lgkmcnt(0)
	v_pk_mul_f32 v[36:37], v[42:43], v[36:37]
	v_pk_mul_f32 v[38:39], v[40:41], v[38:39]
	s_waitcnt vmcnt(9)
	v_lshlrev_b32_e32 v40, 16, v30
	v_and_b32_e32 v41, 0xffff0000, v30
	v_lshlrev_b32_e32 v30, 16, v31
	v_and_b32_e32 v31, 0xffff0000, v31
	s_waitcnt vmcnt(8)
	v_lshlrev_b32_e32 v42, 16, v28
	v_and_b32_e32 v43, 0xffff0000, v28
	v_lshlrev_b32_e32 v28, 16, v29
	v_and_b32_e32 v29, 0xffff0000, v29
	v_pk_add_f32 v[40:41], v[40:41], v[42:43]
	v_pk_add_f32 v[28:29], v[30:31], v[28:29]
	s_waitcnt vmcnt(7)
	v_lshlrev_b32_e32 v30, 16, v26
	v_and_b32_e32 v31, 0xffff0000, v26
	v_lshlrev_b32_e32 v26, 16, v27
	v_and_b32_e32 v27, 0xffff0000, v27
	s_waitcnt vmcnt(6)
	v_lshlrev_b32_e32 v42, 16, v24
	v_and_b32_e32 v43, 0xffff0000, v24
	v_lshlrev_b32_e32 v24, 16, v25
	v_and_b32_e32 v25, 0xffff0000, v25
	v_pk_add_f32 v[30:31], v[30:31], v[42:43]
	v_pk_add_f32 v[24:25], v[26:27], v[24:25]
	v_pk_fma_f32 v[38:39], v[54:55], s[12:13], v[38:39] op_sel_hi:[1,0,1]
	v_pk_add_f32 v[26:27], v[28:29], v[24:25]
	v_pk_add_f32 v[28:29], v[40:41], v[30:31]
	s_waitcnt vmcnt(5)
	v_cvt_f32_f16_e32 v30, v22
	v_cvt_f32_f16_sdwa v31, v22 dst_sel:DWORD dst_unused:UNUSED_PAD src0_sel:WORD_1
	v_cvt_f32_f16_e32 v40, v23
	v_cvt_f32_f16_sdwa v41, v23 dst_sel:DWORD dst_unused:UNUSED_PAD src0_sel:WORD_1
	ds_read_b128 v[22:25], v88 offset:22528
	v_pk_fma_f32 v[36:37], v[44:45], s[12:13], v[36:37] op_sel_hi:[1,0,1]
	s_waitcnt lgkmcnt(0)
	v_pk_mul_f32 v[28:29], v[28:29], v[22:23]
	v_pk_mul_f32 v[22:23], v[26:27], v[24:25]
	v_pk_fma_f32 v[24:25], v[30:31], s[12:13], v[28:29] op_sel_hi:[1,0,1]
	s_waitcnt vmcnt(4)
	v_lshlrev_b32_e32 v26, 16, v16
	v_and_b32_e32 v27, 0xffff0000, v16
	v_lshlrev_b32_e32 v16, 16, v17
	v_and_b32_e32 v17, 0xffff0000, v17
	s_waitcnt vmcnt(3)
	v_lshlrev_b32_e32 v28, 16, v14
	v_and_b32_e32 v29, 0xffff0000, v14
	v_lshlrev_b32_e32 v14, 16, v15
	v_and_b32_e32 v15, 0xffff0000, v15
	v_pk_add_f32 v[26:27], v[26:27], v[28:29]
	v_pk_add_f32 v[14:15], v[16:17], v[14:15]
	s_waitcnt vmcnt(2)
	v_lshlrev_b32_e32 v16, 16, v12
	v_and_b32_e32 v17, 0xffff0000, v12
	v_lshlrev_b32_e32 v12, 16, v13
	v_and_b32_e32 v13, 0xffff0000, v13
	s_waitcnt vmcnt(1)
	v_lshlrev_b32_e32 v28, 16, v10
	v_and_b32_e32 v29, 0xffff0000, v10
	v_lshlrev_b32_e32 v10, 16, v11
	v_and_b32_e32 v11, 0xffff0000, v11
	v_pk_add_f32 v[16:17], v[16:17], v[28:29]
	v_pk_add_f32 v[10:11], v[12:13], v[10:11]
	v_pk_fma_f32 v[22:23], v[40:41], s[12:13], v[22:23] op_sel_hi:[1,0,1]
	v_pk_add_f32 v[12:13], v[14:15], v[10:11]
	v_pk_add_f32 v[14:15], v[26:27], v[16:17]
	s_waitcnt vmcnt(0)
	v_cvt_f32_f16_e32 v16, v8
	v_cvt_f32_f16_sdwa v17, v8 dst_sel:DWORD dst_unused:UNUSED_PAD src0_sel:WORD_1
	v_cvt_f32_f16_e32 v26, v9
	v_cvt_f32_f16_sdwa v27, v9 dst_sel:DWORD dst_unused:UNUSED_PAD src0_sel:WORD_1
	ds_read_b128 v[8:11], v88 offset:23552
	s_waitcnt lgkmcnt(0)
	v_pk_mul_f32 v[8:9], v[8:9], v[14:15]
	v_pk_mul_f32 v[10:11], v[10:11], v[12:13]
	v_pk_fma_f32 v[54:55], v[16:17], s[12:13], v[8:9] op_sel_hi:[1,0,1]
	v_pk_fma_f32 v[44:45], v[26:27], s[12:13], v[10:11] op_sel_hi:[1,0,1]
	v_mov_b32_e32 v8, v6
	v_mov_b32_e32 v9, v20
	v_mov_b32_e32 v10, v7
	v_mov_b32_e32 v11, v21
	v_pk_add_f32 v[8:9], v[8:9], v[10:11]
	v_mov_b32_e32 v10, v4
	v_mov_b32_e32 v11, v18
	v_mov_b32_e32 v12, v5
	v_mov_b32_e32 v13, v19
	v_pk_add_f32 v[10:11], v[10:11], v[12:13]
	v_mov_b32_e32 v12, v32
	v_pk_add_f32 v[8:9], v[8:9], v[10:11]
	v_pk_mov_b32 v[10:11], v[32:33], v[34:35] op_sel:[1,0]
	v_mov_b32_e32 v13, v35
	v_pk_add_f32 v[10:11], v[10:11], v[12:13]
	v_add_f32_e32 v8, 0, v8
	v_pk_add_f32 v[10:11], v[10:11], v[10:11] op_sel:[0,1] op_sel_hi:[1,0]
	v_add_f32_e32 v8, v8, v9
	v_add_f32_e32 v12, v46, v47
	v_add_f32_e32 v14, v48, v49
	v_mov_b32_e32 v9, v50
	v_mov_b32_e32 v11, v51
	v_mov_b32_e32 v13, v52
	v_mov_b32_e32 v15, v53
	v_pk_add_f32 v[8:9], v[8:9], v[10:11]
	v_pk_add_f32 v[10:11], v[12:13], v[14:15]
	v_mov_b32_e32 v12, v36
	v_pk_add_f32 v[8:9], v[8:9], v[10:11]
	v_pk_mov_b32 v[10:11], v[36:37], v[38:39] op_sel:[1,0]
	v_mov_b32_e32 v13, v39
	v_pk_add_f32 v[10:11], v[10:11], v[12:13]
	v_pk_add_f32 v[8:9], v[8:9], v[8:9] op_sel:[0,1] op_sel_hi:[1,0]
	v_pk_add_f32 v[10:11], v[10:11], v[10:11] op_sel:[0,1] op_sel_hi:[1,0]
	v_add_f32_e32 v12, v24, v25
	v_add_f32_e32 v14, v22, v23
	v_mov_b32_e32 v9, v54
	v_mov_b32_e32 v11, v55
	v_mov_b32_e32 v13, v44
	v_mov_b32_e32 v15, v45
	v_pk_add_f32 v[8:9], v[8:9], v[10:11]
	v_pk_add_f32 v[10:11], v[12:13], v[14:15]
	s_nop 0
	v_pk_add_f32 v[8:9], v[8:9], v[10:11]
	s_nop 0
	v_add_f32_e32 v8, v8, v9
	s_waitcnt lgkmcnt(0)
	s_nop 1
	v_add_f32_dpp v8, v8, v8 quad_perm:[1,0,3,2] row_mask:0xf bank_mask:0xf
	s_nop 1
	v_add_f32_dpp v8, v8, v8 quad_perm:[2,3,0,1] row_mask:0xf bank_mask:0xf
	s_nop 1
	v_add_f32_dpp v8, v8, v8 row_half_mirror row_mask:0xf bank_mask:0xf
	s_nop 1
	v_add_f32_dpp v8, v8, v8 row_ror:8 row_mask:0xf bank_mask:0xf
	s_nop 0
	v_readlane_b32 s100, v8, 0
	v_readlane_b32 s101, v8, 16
	s_nop 0
	v_mov_b32_e32 v9, s100
	v_add_f32_e32 v9, s101, v9
	v_readlane_b32 s100, v8, 32
	v_readlane_b32 s101, v8, 48
	s_nop 0
	v_add_f32_e32 v9, s100, v9
	v_add_f32_e32 v16, s101, v9
	v_fmamk_f32 v7, v16, 0xba000000, v7
	v_fmamk_f32 v21, v16, 0xba000000, v21
	v_fmamk_f32 v5, v16, 0xba000000, v5
	v_fmac_f32_e32 v6, 0xba000000, v16
	v_fmamk_f32 v19, v16, 0xba000000, v19
	v_fmac_f32_e32 v20, 0xba000000, v16
	v_mov_b32_e32 v10, v7
	v_mov_b32_e32 v11, v21
	v_fmac_f32_e32 v4, 0xba000000, v16
	v_fmac_f32_e32 v18, 0xba000000, v16
	v_mov_b32_e32 v8, v6
	v_mov_b32_e32 v9, v20
	v_pk_mul_f32 v[10:11], v[10:11], v[10:11]
	v_mov_b32_e32 v12, v5
	v_mov_b32_e32 v13, v19
	v_pk_fma_f32 v[8:9], v[8:9], v[8:9], v[10:11]
	v_mov_b32_e32 v10, v4
	v_mov_b32_e32 v11, v18
	v_pk_mul_f32 v[12:13], v[12:13], v[12:13]
	v_fmamk_f32 v33, v16, 0xba000000, v33
	v_pk_fma_f32 v[10:11], v[10:11], v[10:11], v[12:13]
	v_fmac_f32_e32 v32, 0xba000000, v16
	v_pk_add_f32 v[8:9], v[8:9], v[10:11]
	v_fmamk_f32 v35, v16, 0xba000000, v35
	v_fmac_f32_e32 v34, 0xba000000, v16
	v_pk_add_f32 v[8:9], v[8:9], v[8:9] op_sel_hi:[0,1]
	v_pk_mul_f32 v[10:11], v[34:35], v[34:35]
	v_pk_mul_f32 v[12:13], v[32:33], v[32:33]
	v_fmac_f32_e32 v46, 0xba000000, v16
	v_pk_mov_b32 v[14:15], v[12:13], v[10:11] op_sel:[1,0]
	v_mov_b32_e32 v13, v11
	v_fmamk_f32 v47, v16, 0xba000000, v47
	v_fmac_f32_e32 v48, 0xba000000, v16
	v_mul_f32_e32 v8, v46, v46
	v_pk_add_f32 v[10:11], v[14:15], v[12:13]
	v_fmamk_f32 v49, v16, 0xba000000, v49
	v_pk_fma_f32 v[12:13], v[46:47], v[46:47], v[8:9] op_sel_hi:[1,1,0]
	v_mul_f32_e32 v8, v48, v48
	v_pk_add_f32 v[10:11], v[10:11], v[10:11] op_sel_hi:[0,1]
	v_pk_fma_f32 v[14:15], v[48:49], v[48:49], v[8:9] op_sel_hi:[1,1,0]
	v_fmamk_f32 v53, v16, 0xba000000, v53
	v_fmac_f32_e32 v52, 0xba000000, v16
	v_fmamk_f32 v51, v16, 0xba000000, v51
	v_fmac_f32_e32 v50, 0xba000000, v16
	v_mul_f32_e32 v12, v50, v50
	v_mul_f32_e32 v14, v51, v51
	v_mul_f32_e32 v10, v52, v52
	v_mul_f32_e32 v8, v53, v53
	v_pk_add_f32 v[12:13], v[12:13], v[14:15]
	v_pk_add_f32 v[8:9], v[10:11], v[8:9]
	v_fmamk_f32 v37, v16, 0xba000000, v37
	v_pk_add_f32 v[8:9], v[12:13], v[8:9]
	v_fmac_f32_e32 v36, 0xba000000, v16
	v_fmamk_f32 v39, v16, 0xba000000, v39
	v_fmac_f32_e32 v38, 0xba000000, v16
	v_pk_add_f32 v[8:9], v[8:9], v[8:9] op_sel_hi:[0,1]
	v_pk_mul_f32 v[10:11], v[38:39], v[38:39]
	v_pk_mul_f32 v[12:13], v[36:37], v[36:37]
	v_fmac_f32_e32 v24, 0xba000000, v16
	v_pk_mov_b32 v[14:15], v[12:13], v[10:11] op_sel:[1,0]
	v_mov_b32_e32 v13, v11
	v_fmamk_f32 v25, v16, 0xba000000, v25
	v_fmac_f32_e32 v22, 0xba000000, v16
	v_mul_f32_e32 v8, v24, v24
	v_pk_add_f32 v[10:11], v[14:15], v[12:13]
	v_fmamk_f32 v23, v16, 0xba000000, v23
	v_pk_fma_f32 v[12:13], v[24:25], v[24:25], v[8:9] op_sel_hi:[1,1,0]
	v_mul_f32_e32 v8, v22, v22
	v_pk_add_f32 v[10:11], v[10:11], v[10:11] op_sel_hi:[0,1]
	v_pk_fma_f32 v[14:15], v[22:23], v[22:23], v[8:9] op_sel_hi:[1,1,0]
	v_fmamk_f32 v45, v16, 0xba000000, v45
	v_fmac_f32_e32 v44, 0xba000000, v16
	v_fmamk_f32 v55, v16, 0xba000000, v55
	v_fmac_f32_e32 v54, 0xba000000, v16
	v_mul_f32_e32 v12, v54, v54
	v_mul_f32_e32 v14, v55, v55
	v_mul_f32_e32 v10, v44, v44
	v_mul_f32_e32 v8, v45, v45
	v_pk_add_f32 v[12:13], v[12:13], v[14:15]
	v_pk_add_f32 v[8:9], v[10:11], v[8:9]
	s_nop 0
	v_pk_add_f32 v[8:9], v[12:13], v[8:9]
	s_nop 0
	v_add_f32_e32 v8, v8, v9
	s_waitcnt lgkmcnt(0)
	s_nop 1
	v_add_f32_dpp v8, v8, v8 quad_perm:[1,0,3,2] row_mask:0xf bank_mask:0xf
	s_nop 1
	v_add_f32_dpp v8, v8, v8 quad_perm:[2,3,0,1] row_mask:0xf bank_mask:0xf
	s_nop 1
	v_add_f32_dpp v8, v8, v8 row_half_mirror row_mask:0xf bank_mask:0xf
	s_nop 1
	v_add_f32_dpp v8, v8, v8 row_ror:8 row_mask:0xf bank_mask:0xf
	s_nop 0
	v_readlane_b32 s100, v8, 0
	v_readlane_b32 s101, v8, 16
	s_nop 0
	v_mov_b32_e32 v9, s100
	v_add_f32_e32 v9, s101, v9
	v_readlane_b32 s100, v8, 32
	v_readlane_b32 s101, v8, 48
	s_nop 0
	v_add_f32_e32 v9, s100, v9
	v_add_f32_e32 v8, s101, v9
	v_fmamk_f32 v8, v8, 0x3a000000, v229
	v_cmp_gt_f32_e32 vcc, s10, v8
	v_mul_f32_e32 v9, 0x4f800000, v8
	s_nop 0
	v_cndmask_b32_e32 v8, v8, v9, vcc
	v_sqrt_f32_e32 v9, v8
	s_nop 0
	v_add_u32_e32 v10, -1, v9
	v_fma_f32 v11, -v10, v9, v8
	v_cmp_ge_f32_e64 s[4:5], 0, v11
	v_add_u32_e32 v11, 1, v9
	s_nop 0
	v_cndmask_b32_e64 v10, v9, v10, s[4:5]
	v_fma_f32 v9, -v11, v9, v8
	v_cmp_lt_f32_e64 s[4:5], 0, v9
	s_nop 1
	v_cndmask_b32_e64 v9, v10, v11, s[4:5]
	v_mul_f32_e32 v10, 0x37800000, v9
	v_cndmask_b32_e32 v9, v9, v10, vcc
	v_cmp_class_f32_e32 vcc, v8, v230
	s_nop 1
	v_cndmask_b32_e32 v8, v9, v8, vcc
	v_div_scale_f32 v9, s[4:5], v8, v8, 1.0
	v_rcp_f32_e32 v10, v9
	s_nop 0
	v_fma_f32 v11, -v9, v10, 1.0
	v_fmac_f32_e32 v10, v11, v10
	v_div_scale_f32 v11, vcc, 1.0, v8, 1.0
	v_mul_f32_e32 v12, v11, v10
	v_fma_f32 v13, -v9, v12, v11
	v_fmac_f32_e32 v12, v13, v10
	v_fma_f32 v9, -v9, v12, v11
	v_div_fmas_f32 v9, v9, v10, v12
	v_div_fixup_f32 v56, v9, v8, 1.0
	ds_read_b128 v[8:11], v88
	ds_read_b128 v[12:15], v88 offset:8192
	v_pk_mul_f32 v[4:5], v[4:5], v[56:57] op_sel_hi:[1,0]
	v_pk_mul_f32 v[6:7], v[6:7], v[56:57] op_sel_hi:[1,0]
	s_waitcnt lgkmcnt(0)
	v_pk_fma_f32 v[60:61], v[10:11], v[4:5], v[14:15]
	v_pk_fma_f32 v[58:59], v[8:9], v[6:7], v[12:13]
	v_cvt_pk_f16_f32 v5, v60, v61
	v_cvt_pk_f16_f32 v4, v58, v59
	global_store_dwordx2 v[2:3], v[4:5], off
	ds_read_b128 v[4:7], v88 offset:1024
	ds_read_b128 v[8:11], v88 offset:9216
	v_pk_mul_f32 v[12:13], v[18:19], v[56:57] op_sel_hi:[1,0]
	v_pk_mul_f32 v[14:15], v[20:21], v[56:57] op_sel_hi:[1,0]
	s_waitcnt lgkmcnt(0)
	v_pk_fma_f32 v[40:41], v[12:13], v[6:7], v[10:11]
	v_pk_fma_f32 v[42:43], v[14:15], v[4:5], v[8:9]
	v_cvt_pk_f16_f32 v5, v40, v41
	v_cvt_pk_f16_f32 v4, v42, v43
	global_store_dwordx2 v[2:3], v[4:5], off offset:512
	ds_read_b128 v[4:7], v88 offset:2048
	ds_read_b128 v[8:11], v88 offset:10240
	v_pk_mul_f32 v[12:13], v[34:35], v[56:57] op_sel_hi:[1,0]
	v_pk_mul_f32 v[14:15], v[32:33], v[56:57] op_sel_hi:[1,0]
	s_waitcnt lgkmcnt(0)
	v_pk_fma_f32 v[30:31], v[12:13], v[6:7], v[10:11]
	v_pk_fma_f32 v[28:29], v[14:15], v[4:5], v[8:9]
	v_cvt_pk_f16_f32 v5, v30, v31
	v_cvt_pk_f16_f32 v4, v28, v29
	global_store_dwordx2 v[2:3], v[4:5], off offset:1024
	ds_read_b128 v[4:7], v88 offset:3072
	ds_read_b128 v[8:11], v88 offset:11264
	v_pk_mul_f32 v[12:13], v[48:49], v[56:57] op_sel_hi:[1,0]
	v_pk_mul_f32 v[14:15], v[46:47], v[56:57] op_sel_hi:[1,0]
	s_waitcnt lgkmcnt(0)
	v_pk_fma_f32 v[26:27], v[12:13], v[6:7], v[10:11]
	v_pk_fma_f32 v[20:21], v[14:15], v[4:5], v[8:9]
	v_cvt_pk_f16_f32 v5, v26, v27
	v_cvt_pk_f16_f32 v4, v20, v21
	global_store_dwordx2 v[2:3], v[4:5], off offset:1536
	ds_read_b128 v[4:7], v88 offset:4096
	ds_read_b128 v[8:11], v88 offset:12288
	v_pk_mul_f32 v[12:13], v[52:53], v[56:57] op_sel_hi:[1,0]
	v_pk_mul_f32 v[14:15], v[50:51], v[56:57] op_sel_hi:[1,0]
	s_waitcnt lgkmcnt(0)
	v_pk_fma_f32 v[16:17], v[12:13], v[6:7], v[10:11]
	v_pk_fma_f32 v[18:19], v[14:15], v[4:5], v[8:9]
	v_cvt_pk_f16_f32 v5, v16, v17
	v_cvt_pk_f16_f32 v4, v18, v19
	global_store_dwordx2 v[2:3], v[4:5], off offset:2048
	ds_read_b128 v[4:7], v88 offset:5120
	ds_read_b128 v[8:11], v88 offset:13312
	v_pk_mul_f32 v[14:15], v[38:39], v[56:57] op_sel_hi:[1,0]
	v_pk_mul_f32 v[12:13], v[36:37], v[56:57] op_sel_hi:[1,0]
	s_waitcnt lgkmcnt(0)
	v_pk_fma_f32 v[14:15], v[14:15], v[6:7], v[10:11]
	v_pk_fma_f32 v[12:13], v[12:13], v[4:5], v[8:9]
	v_cvt_pk_f16_f32 v5, v14, v15
	v_cvt_pk_f16_f32 v4, v12, v13
	global_store_dwordx2 v[2:3], v[4:5], off offset:2560
	ds_read_b128 v[4:7], v88 offset:6144
	ds_read_b128 v[32:35], v88 offset:14336
	v_pk_mul_f32 v[10:11], v[24:25], v[56:57] op_sel_hi:[1,0]
	v_pk_mul_f32 v[8:9], v[22:23], v[56:57] op_sel_hi:[1,0]
	s_waitcnt lgkmcnt(0)
	v_pk_fma_f32 v[10:11], v[10:11], v[4:5], v[32:33]
	v_pk_fma_f32 v[8:9], v[8:9], v[6:7], v[34:35]
	v_cvt_pk_f16_f32 v4, v10, v11
	v_cvt_pk_f16_f32 v5, v8, v9
	global_store_dwordx2 v[2:3], v[4:5], off offset:3072
	ds_read_b128 v[22:25], v88 offset:7168
	ds_read_b128 v[32:35], v88 offset:15360
	v_pk_mul_f32 v[6:7], v[54:55], v[56:57] op_sel_hi:[1,0]
	v_pk_mul_f32 v[4:5], v[44:45], v[56:57] op_sel_hi:[1,0]
	s_waitcnt lgkmcnt(0)
	v_pk_fma_f32 v[6:7], v[6:7], v[22:23], v[32:33]
	v_pk_fma_f32 v[4:5], v[4:5], v[24:25], v[34:35]
	v_cvt_pk_f16_f32 v22, v6, v7
	v_cvt_pk_f16_f32 v23, v4, v5
	global_store_dwordx2 v[2:3], v[22:23], off offset:3584
	v_mov_b32_e32 v2, v58
	v_mov_b32_e32 v3, v42
	v_mov_b32_e32 v22, v59
	v_mov_b32_e32 v23, v43
	v_pk_add_f32 v[2:3], v[2:3], v[22:23]
	v_mov_b32_e32 v22, v60
	v_mov_b32_e32 v23, v40
	v_mov_b32_e32 v24, v61
	v_mov_b32_e32 v25, v41
	v_pk_add_f32 v[22:23], v[22:23], v[24:25]
	v_mov_b32_e32 v24, v28
	v_pk_add_f32 v[2:3], v[2:3], v[22:23]
	v_pk_mov_b32 v[22:23], v[28:29], v[30:31] op_sel:[1,0]
	v_mov_b32_e32 v25, v31
	v_pk_add_f32 v[22:23], v[22:23], v[24:25]
	v_add_f32_e32 v2, 0, v2
	v_pk_add_f32 v[22:23], v[22:23], v[22:23] op_sel:[0,1] op_sel_hi:[1,0]
	v_add_f32_e32 v2, v2, v3
	v_add_f32_e32 v24, v20, v21
	v_add_f32_e32 v32, v26, v27
	v_mov_b32_e32 v3, v18
	v_mov_b32_e32 v23, v19
	v_mov_b32_e32 v25, v16
	v_mov_b32_e32 v33, v17
	v_pk_add_f32 v[2:3], v[2:3], v[22:23]
	v_pk_add_f32 v[22:23], v[24:25], v[32:33]
	v_mov_b32_e32 v24, v12
	v_pk_add_f32 v[2:3], v[2:3], v[22:23]
	v_pk_mov_b32 v[22:23], v[12:13], v[14:15] op_sel:[1,0]
	v_mov_b32_e32 v25, v15
	v_pk_add_f32 v[22:23], v[22:23], v[24:25]
	v_pk_add_f32 v[2:3], v[2:3], v[2:3] op_sel:[0,1] op_sel_hi:[1,0]
	v_pk_add_f32 v[22:23], v[22:23], v[22:23] op_sel:[0,1] op_sel_hi:[1,0]
	v_add_f32_e32 v24, v10, v11
	v_add_f32_e32 v32, v8, v9
	v_mov_b32_e32 v3, v6
	v_mov_b32_e32 v23, v7
	v_mov_b32_e32 v25, v4
	v_mov_b32_e32 v33, v5
	v_pk_add_f32 v[2:3], v[2:3], v[22:23]
	v_pk_add_f32 v[22:23], v[24:25], v[32:33]
	s_nop 0
	v_pk_add_f32 v[2:3], v[2:3], v[22:23]
	s_nop 0
	v_add_f32_e32 v2, v2, v3
	s_waitcnt lgkmcnt(0)
	s_nop 1
	v_add_f32_dpp v2, v2, v2 quad_perm:[1,0,3,2] row_mask:0xf bank_mask:0xf
	s_nop 1
	v_add_f32_dpp v2, v2, v2 quad_perm:[2,3,0,1] row_mask:0xf bank_mask:0xf
	s_nop 1
	v_add_f32_dpp v2, v2, v2 row_half_mirror row_mask:0xf bank_mask:0xf
	s_nop 1
	v_add_f32_dpp v2, v2, v2 row_ror:8 row_mask:0xf bank_mask:0xf
	s_nop 0
	v_readlane_b32 s100, v2, 0
	v_readlane_b32 s101, v2, 16
	s_nop 0
	v_mov_b32_e32 v3, s100
	v_add_f32_e32 v3, s101, v3
	v_readlane_b32 s100, v2, 32
	v_readlane_b32 s101, v2, 48
	s_nop 0
	v_add_f32_e32 v3, s100, v3
	v_add_f32_e32 v34, s101, v3
	v_fmamk_f32 v59, v34, 0xba000000, v59
	v_fmamk_f32 v43, v34, 0xba000000, v43
	v_fmamk_f32 v61, v34, 0xba000000, v61
	v_fmac_f32_e32 v58, 0xba000000, v34
	v_fmamk_f32 v41, v34, 0xba000000, v41
	v_fmac_f32_e32 v42, 0xba000000, v34
	v_mov_b32_e32 v22, v59
	v_mov_b32_e32 v23, v43
	v_fmac_f32_e32 v60, 0xba000000, v34
	v_fmac_f32_e32 v40, 0xba000000, v34
	v_mov_b32_e32 v2, v58
	v_mov_b32_e32 v3, v42
	v_pk_mul_f32 v[22:23], v[22:23], v[22:23]
	v_mov_b32_e32 v24, v61
	v_mov_b32_e32 v25, v41
	v_pk_fma_f32 v[2:3], v[2:3], v[2:3], v[22:23]
	v_mov_b32_e32 v22, v60
	v_mov_b32_e32 v23, v40
	v_pk_mul_f32 v[24:25], v[24:25], v[24:25]
	v_fmamk_f32 v29, v34, 0xba000000, v29
	v_pk_fma_f32 v[22:23], v[22:23], v[22:23], v[24:25]
	v_fmac_f32_e32 v28, 0xba000000, v34
	v_pk_add_f32 v[2:3], v[2:3], v[22:23]
	v_fmamk_f32 v31, v34, 0xba000000, v31
	v_fmac_f32_e32 v30, 0xba000000, v34
	v_pk_add_f32 v[2:3], v[2:3], v[2:3] op_sel_hi:[0,1]
	v_pk_mul_f32 v[22:23], v[30:31], v[30:31]
	v_pk_mul_f32 v[24:25], v[28:29], v[28:29]
	v_fmac_f32_e32 v20, 0xba000000, v34
	v_pk_mov_b32 v[32:33], v[24:25], v[22:23] op_sel:[1,0]
	v_mov_b32_e32 v25, v23
	v_fmamk_f32 v21, v34, 0xba000000, v21
	v_fmac_f32_e32 v26, 0xba000000, v34
	v_mul_f32_e32 v2, v20, v20
	v_pk_add_f32 v[22:23], v[32:33], v[24:25]
	v_fmamk_f32 v27, v34, 0xba000000, v27
	v_pk_fma_f32 v[24:25], v[20:21], v[20:21], v[2:3] op_sel_hi:[1,1,0]
	v_mul_f32_e32 v2, v26, v26
	v_pk_add_f32 v[22:23], v[22:23], v[22:23] op_sel_hi:[0,1]
	v_pk_fma_f32 v[32:33], v[26:27], v[26:27], v[2:3] op_sel_hi:[1,1,0]
	v_fmamk_f32 v17, v34, 0xba000000, v17
	v_fmac_f32_e32 v16, 0xba000000, v34
	v_fmamk_f32 v19, v34, 0xba000000, v19
	v_fmac_f32_e32 v18, 0xba000000, v34
	v_mul_f32_e32 v24, v18, v18
	v_mul_f32_e32 v32, v19, v19
	v_mul_f32_e32 v22, v16, v16
	v_mul_f32_e32 v2, v17, v17
	v_pk_add_f32 v[24:25], v[24:25], v[32:33]
	v_pk_add_f32 v[2:3], v[22:23], v[2:3]
	v_fmamk_f32 v13, v34, 0xba000000, v13
	v_pk_add_f32 v[2:3], v[24:25], v[2:3]
	v_fmac_f32_e32 v12, 0xba000000, v34
	v_fmamk_f32 v15, v34, 0xba000000, v15
	v_fmac_f32_e32 v14, 0xba000000, v34
	v_pk_add_f32 v[2:3], v[2:3], v[2:3] op_sel_hi:[0,1]
	v_pk_mul_f32 v[22:23], v[14:15], v[14:15]
	v_pk_mul_f32 v[24:25], v[12:13], v[12:13]
	v_fmac_f32_e32 v10, 0xba000000, v34
	v_pk_mov_b32 v[32:33], v[24:25], v[22:23] op_sel:[1,0]
	v_mov_b32_e32 v25, v23
	v_fmamk_f32 v11, v34, 0xba000000, v11
	v_fmac_f32_e32 v8, 0xba000000, v34
	v_mul_f32_e32 v2, v10, v10
	v_pk_add_f32 v[22:23], v[32:33], v[24:25]
	v_fmamk_f32 v9, v34, 0xba000000, v9
	v_pk_fma_f32 v[24:25], v[10:11], v[10:11], v[2:3] op_sel_hi:[1,1,0]
	v_mul_f32_e32 v2, v8, v8
	v_pk_add_f32 v[22:23], v[22:23], v[22:23] op_sel_hi:[0,1]
	v_pk_fma_f32 v[32:33], v[8:9], v[8:9], v[2:3] op_sel_hi:[1,1,0]
	v_fmamk_f32 v5, v34, 0xba000000, v5
	v_fmac_f32_e32 v4, 0xba000000, v34
	v_fmamk_f32 v7, v34, 0xba000000, v7
	v_fmac_f32_e32 v6, 0xba000000, v34
	v_mul_f32_e32 v24, v6, v6
	v_mul_f32_e32 v32, v7, v7
	v_mul_f32_e32 v22, v4, v4
	v_mul_f32_e32 v2, v5, v5
	v_pk_add_f32 v[24:25], v[24:25], v[32:33]
	v_pk_add_f32 v[2:3], v[22:23], v[2:3]
	s_nop 0
	v_pk_add_f32 v[2:3], v[24:25], v[2:3]
	s_nop 0
	v_add_f32_e32 v2, v2, v3
	s_waitcnt lgkmcnt(0)
	s_nop 1
	v_add_f32_dpp v2, v2, v2 quad_perm:[1,0,3,2] row_mask:0xf bank_mask:0xf
	s_nop 1
	v_add_f32_dpp v2, v2, v2 quad_perm:[2,3,0,1] row_mask:0xf bank_mask:0xf
	s_nop 1
	v_add_f32_dpp v2, v2, v2 row_half_mirror row_mask:0xf bank_mask:0xf
	s_nop 1
	v_add_f32_dpp v2, v2, v2 row_ror:8 row_mask:0xf bank_mask:0xf
	s_nop 0
	v_readlane_b32 s100, v2, 0
	v_readlane_b32 s101, v2, 16
	s_nop 0
	v_mov_b32_e32 v3, s100
	v_add_f32_e32 v3, s101, v3
	v_readlane_b32 s100, v2, 32
	v_readlane_b32 s101, v2, 48
	s_nop 0
	v_add_f32_e32 v3, s100, v3
	v_add_f32_e32 v2, s101, v3
	v_fmamk_f32 v2, v2, 0x3a000000, v229
	v_cmp_gt_f32_e32 vcc, s10, v2
	v_mul_f32_e32 v3, 0x4f800000, v2
	s_nop 0
	v_cndmask_b32_e32 v2, v2, v3, vcc
	v_sqrt_f32_e32 v3, v2
	s_nop 0
	v_add_u32_e32 v22, -1, v3
	v_fma_f32 v23, -v22, v3, v2
	v_cmp_ge_f32_e64 s[4:5], 0, v23
	v_add_u32_e32 v23, 1, v3
	s_nop 0
	v_cndmask_b32_e64 v22, v3, v22, s[4:5]
	v_fma_f32 v3, -v23, v3, v2
	v_cmp_lt_f32_e64 s[4:5], 0, v3
	s_nop 1
	v_cndmask_b32_e64 v3, v22, v23, s[4:5]
	v_mul_f32_e32 v22, 0x37800000, v3
	v_cndmask_b32_e32 v3, v3, v22, vcc
	v_cmp_class_f32_e32 vcc, v2, v230
	s_nop 1
	v_cndmask_b32_e32 v2, v3, v2, vcc
	v_div_scale_f32 v3, s[4:5], v2, v2, 1.0
	v_rcp_f32_e32 v22, v3
	s_nop 0
	v_fma_f32 v23, -v3, v22, 1.0
	v_fmac_f32_e32 v22, v23, v22
	v_div_scale_f32 v23, vcc, 1.0, v2, 1.0
	v_mul_f32_e32 v24, v23, v22
	v_fma_f32 v25, -v3, v24, v23
	v_fmac_f32_e32 v24, v25, v22
	v_fma_f32 v3, -v3, v24, v23
	v_div_fmas_f32 v3, v3, v22, v24
	ds_read_b128 v[22:25], v88 offset:24576
	ds_read_b128 v[32:35], v88 offset:32768
	v_div_fixup_f32 v36, v3, v2, 1.0
	v_pk_mul_f32 v[2:3], v[58:59], v[36:37] op_sel_hi:[1,0]
	v_pk_mul_f32 v[38:39], v[60:61], v[36:37] op_sel_hi:[1,0]
	v_pk_mul_f32 v[28:29], v[28:29], v[36:37] op_sel_hi:[1,0]
	s_waitcnt lgkmcnt(0)
	v_pk_add_f32 v[32:33], v[32:33], 1.0 op_sel_hi:[1,0]
	v_pk_add_f32 v[34:35], v[34:35], 1.0 op_sel_hi:[1,0]
	v_pk_fma_f32 v[2:3], v[32:33], v[2:3], v[22:23]
	v_pk_fma_f32 v[24:25], v[34:35], v[38:39], v[24:25]
	v_bfe_u32 v22, v2, 16, 1
	v_add3_u32 v2, v2, v22, s69
	v_bfe_u32 v22, v3, 16, 1
	v_lshrrev_b32_e32 v2, 16, v2
	v_add3_u32 v3, v3, v22, s69
	v_and_or_b32 v2, v3, s9, v2
	v_bfe_u32 v3, v24, 16, 1
	v_add3_u32 v3, v24, v3, s69
	v_bfe_u32 v22, v25, 16, 1
	v_lshrrev_b32_e32 v3, 16, v3
	v_add3_u32 v22, v25, v22, s69
	v_add_co_u32_e32 v32, vcc, s11, v0
	v_and_or_b32 v3, v22, s9, v3
	s_nop 0
	v_addc_co_u32_e32 v33, vcc, 0, v1, vcc
	global_store_dwordx2 v[32:33], v[2:3], off
	ds_read_b128 v[0:3], v88 offset:25600
	ds_read_b128 v[22:25], v88 offset:33792
	v_pk_mul_f32 v[34:35], v[42:43], v[36:37] op_sel_hi:[1,0]
	v_pk_mul_f32 v[38:39], v[40:41], v[36:37] op_sel_hi:[1,0]
	v_pk_mul_f32 v[30:31], v[30:31], v[36:37] op_sel_hi:[1,0]
	v_pk_mul_f32 v[20:21], v[20:21], v[36:37] op_sel_hi:[1,0]
	s_waitcnt lgkmcnt(0)
	v_pk_add_f32 v[22:23], v[22:23], 1.0 op_sel_hi:[1,0]
	v_pk_add_f32 v[24:25], v[24:25], 1.0 op_sel_hi:[1,0]
	v_pk_fma_f32 v[0:1], v[22:23], v[34:35], v[0:1]
	v_pk_fma_f32 v[2:3], v[24:25], v[38:39], v[2:3]
	v_bfe_u32 v22, v0, 16, 1
	v_add3_u32 v0, v0, v22, s69
	v_bfe_u32 v22, v1, 16, 1
	v_lshrrev_b32_e32 v0, 16, v0
	v_add3_u32 v1, v1, v22, s69
	v_and_or_b32 v0, v1, s9, v0
	v_bfe_u32 v1, v2, 16, 1
	v_add3_u32 v1, v2, v1, s69
	v_bfe_u32 v2, v3, 16, 1
	v_lshrrev_b32_e32 v1, 16, v1
	v_add3_u32 v2, v3, v2, s69
	v_and_or_b32 v1, v2, s9, v1
	global_store_dwordx2 v[32:33], v[0:1], off offset:512
	ds_read_b128 v[0:3], v88 offset:26624
	ds_read_b128 v[22:25], v88 offset:34816
	v_pk_mul_f32 v[26:27], v[26:27], v[36:37] op_sel_hi:[1,0]
	v_pk_mul_f32 v[18:19], v[18:19], v[36:37] op_sel_hi:[1,0]
	v_pk_mul_f32 v[16:17], v[16:17], v[36:37] op_sel_hi:[1,0]
	v_pk_mul_f32 v[12:13], v[12:13], v[36:37] op_sel_hi:[1,0]
	s_waitcnt lgkmcnt(0)
	v_pk_add_f32 v[22:23], v[22:23], 1.0 op_sel_hi:[1,0]
	v_pk_add_f32 v[24:25], v[24:25], 1.0 op_sel_hi:[1,0]
	v_pk_fma_f32 v[0:1], v[22:23], v[28:29], v[0:1]
	v_pk_fma_f32 v[2:3], v[24:25], v[30:31], v[2:3]
	v_bfe_u32 v22, v0, 16, 1
	v_add3_u32 v0, v0, v22, s69
	v_bfe_u32 v22, v1, 16, 1
	v_lshrrev_b32_e32 v0, 16, v0
	v_add3_u32 v1, v1, v22, s69
	v_and_or_b32 v0, v1, s9, v0
	v_bfe_u32 v1, v2, 16, 1
	v_add3_u32 v1, v2, v1, s69
	v_bfe_u32 v2, v3, 16, 1
	v_lshrrev_b32_e32 v1, 16, v1
	v_add3_u32 v2, v3, v2, s69
	v_and_or_b32 v1, v2, s9, v1
	global_store_dwordx2 v[32:33], v[0:1], off offset:1024
	ds_read_b128 v[0:3], v88 offset:27648
	ds_read_b128 v[22:25], v88 offset:35840
	v_pk_mul_f32 v[14:15], v[14:15], v[36:37] op_sel_hi:[1,0]
	v_pk_mul_f32 v[10:11], v[10:11], v[36:37] op_sel_hi:[1,0]
	v_pk_mul_f32 v[8:9], v[8:9], v[36:37] op_sel_hi:[1,0]
	v_pk_mul_f32 v[6:7], v[6:7], v[36:37] op_sel_hi:[1,0]
	s_waitcnt lgkmcnt(0)
	v_pk_add_f32 v[22:23], v[22:23], 1.0 op_sel_hi:[1,0]
	v_pk_add_f32 v[24:25], v[24:25], 1.0 op_sel_hi:[1,0]
	v_pk_fma_f32 v[0:1], v[22:23], v[20:21], v[0:1]
	v_pk_fma_f32 v[2:3], v[24:25], v[26:27], v[2:3]
	v_bfe_u32 v20, v0, 16, 1
	v_add3_u32 v0, v0, v20, s69
	v_bfe_u32 v20, v1, 16, 1
	v_lshrrev_b32_e32 v0, 16, v0
	v_add3_u32 v1, v1, v20, s69
	v_and_or_b32 v0, v1, s9, v0
	v_bfe_u32 v1, v2, 16, 1
	v_add3_u32 v1, v2, v1, s69
	v_bfe_u32 v2, v3, 16, 1
	v_lshrrev_b32_e32 v1, 16, v1
	v_add3_u32 v2, v3, v2, s69
	v_and_or_b32 v1, v2, s9, v1
	global_store_dwordx2 v[32:33], v[0:1], off offset:1536
	ds_read_b128 v[0:3], v88 offset:28672
	ds_read_b128 v[20:23], v88 offset:36864
	v_pk_mul_f32 v[4:5], v[4:5], v[36:37] op_sel_hi:[1,0]
	s_waitcnt lgkmcnt(0)
	v_pk_add_f32 v[20:21], v[20:21], 1.0 op_sel_hi:[1,0]
	v_pk_add_f32 v[22:23], v[22:23], 1.0 op_sel_hi:[1,0]
	v_pk_fma_f32 v[0:1], v[20:21], v[18:19], v[0:1]
	v_pk_fma_f32 v[2:3], v[22:23], v[16:17], v[2:3]
	v_bfe_u32 v16, v0, 16, 1
	v_add3_u32 v0, v0, v16, s69
	v_bfe_u32 v16, v1, 16, 1
	v_lshrrev_b32_e32 v0, 16, v0
	v_add3_u32 v1, v1, v16, s69
	v_and_or_b32 v0, v1, s9, v0
	v_bfe_u32 v1, v2, 16, 1
	v_add3_u32 v1, v2, v1, s69
	v_bfe_u32 v2, v3, 16, 1
	v_lshrrev_b32_e32 v1, 16, v1
	v_add3_u32 v2, v3, v2, s69
	v_and_or_b32 v1, v2, s9, v1
	global_store_dwordx2 v[32:33], v[0:1], off offset:2048
	ds_read_b128 v[0:3], v88 offset:29696
	ds_read_b128 v[16:19], v88 offset:37888
	s_waitcnt lgkmcnt(0)
	v_pk_add_f32 v[16:17], v[16:17], 1.0 op_sel_hi:[1,0]
	s_nop 0
	v_pk_fma_f32 v[0:1], v[16:17], v[12:13], v[0:1]
	v_pk_add_f32 v[18:19], v[18:19], 1.0 op_sel_hi:[1,0]
	v_bfe_u32 v12, v0, 16, 1
	v_add3_u32 v0, v0, v12, s69
	v_bfe_u32 v12, v1, 16, 1
	v_pk_fma_f32 v[2:3], v[18:19], v[14:15], v[2:3]
	v_lshrrev_b32_e32 v0, 16, v0
	v_add3_u32 v1, v1, v12, s69
	v_and_or_b32 v0, v1, s9, v0
	v_bfe_u32 v1, v2, 16, 1
	v_add3_u32 v1, v2, v1, s69
	v_bfe_u32 v2, v3, 16, 1
	v_lshrrev_b32_e32 v1, 16, v1
	v_add3_u32 v2, v3, v2, s69
	v_and_or_b32 v1, v2, s9, v1
	global_store_dwordx2 v[32:33], v[0:1], off offset:2560
	ds_read_b128 v[0:3], v88 offset:30720
	ds_read_b128 v[12:15], v88 offset:38912
	s_waitcnt lgkmcnt(0)
	v_pk_add_f32 v[12:13], v[12:13], 1.0 op_sel_hi:[1,0]
	v_pk_add_f32 v[14:15], v[14:15], 1.0 op_sel_hi:[1,0]
	v_pk_fma_f32 v[0:1], v[12:13], v[10:11], v[0:1]
	v_pk_fma_f32 v[2:3], v[14:15], v[8:9], v[2:3]
	v_bfe_u32 v8, v0, 16, 1
	v_add3_u32 v0, v0, v8, s69
	v_bfe_u32 v8, v1, 16, 1
	v_lshrrev_b32_e32 v0, 16, v0
	v_add3_u32 v1, v1, v8, s69
	v_and_or_b32 v0, v1, s9, v0
	v_bfe_u32 v1, v2, 16, 1
	v_add3_u32 v1, v2, v1, s69
	v_bfe_u32 v2, v3, 16, 1
	v_lshrrev_b32_e32 v1, 16, v1
	v_add3_u32 v2, v3, v2, s69
	v_and_or_b32 v1, v2, s9, v1
	global_store_dwordx2 v[32:33], v[0:1], off offset:3072
	ds_read_b128 v[0:3], v88 offset:31744
	ds_read_b128 v[8:11], v88 offset:39936
	s_waitcnt lgkmcnt(0)
	v_pk_add_f32 v[8:9], v[8:9], 1.0 op_sel_hi:[1,0]
	v_pk_add_f32 v[10:11], v[10:11], 1.0 op_sel_hi:[1,0]
	v_pk_fma_f32 v[0:1], v[6:7], v[8:9], v[0:1]
	v_pk_fma_f32 v[2:3], v[4:5], v[10:11], v[2:3]
	v_bfe_u32 v4, v0, 16, 1
	v_add3_u32 v0, v0, v4, s69
	v_bfe_u32 v4, v1, 16, 1
	v_lshrrev_b32_e32 v0, 16, v0
	v_add3_u32 v1, v1, v4, s69
	v_and_or_b32 v0, v1, s9, v0
	v_bfe_u32 v1, v2, 16, 1
	v_add3_u32 v1, v2, v1, s69
	v_bfe_u32 v2, v3, 16, 1
	v_lshrrev_b32_e32 v1, 16, v1
	v_add3_u32 v2, v3, v2, s69
	v_and_or_b32 v1, v2, s9, v1
	global_store_dwordx2 v[32:33], v[0:1], off offset:3584
	s_cbranch_scc1 .LBB0_1300
